# pool rewrite + K-loops slimmed: setprio flips deleted, LDS-DMA loads in saddr form (78 64-bit VALU adds per 5 loops removed, 18 replaced by scalar adds), duplicate lgkmcnt(0) waits removed
# speedup vs baseline: 1.0155x; 1.0155x over previous
; #define PG8_STAGE(bufoff, gbase, voff) do { _Pragma("unroll") for (int _i = 0; _i < 2; ++_i) \
;         __builtin_amdgcn_global_load_lds((const unsigned*)((const char*)(gbase) + (voff)[_i]), (LAS unsigned*)(lds + (bufoff) + ldsw + _i * 8192), 16, 0, 0); } while (0)
; #define PG8_LDA(dst, b, h) do { _Pragma("unroll") for (int m = 0; m < 4; ++m) _Pragma("unroll") for (int k = 0; k < 2; ++k) dst[m][k] = *(const LAS bf16x8*)(lds + PG8_SA(b, h) + aoff + m * 2048 + k * 1024); } while (0)
; #define PG8_LDB(dst, b, h) do { _Pragma("unroll") for (int n = 0; n < 2; ++n) _Pragma("unroll") for (int k = 0; k < 2; ++k) dst[n][k] = *(const LAS bf16x8*)(lds + PG8_SB(b, h) + boff + n * 2048 + k * 1024); } while (0)
; #define PG8_MMA(ai, bj, At, Bt) do { __builtin_amdgcn_s_setprio(1); _Pragma("unroll") for (int m = 0; m < 4; ++m) _Pragma("unroll") for (int n = 0; n < 2; ++n) _Pragma("unroll") for (int k = 0; k < 2; ++k) \
;         acc[ai][bj][m][n] = __builtin_amdgcn_mfma_f32_16x16x32_bf16(Bt[n][k], At[m][k], acc[ai][bj][m][n], 0, 0, 0); __builtin_amdgcn_s_setprio(0); } while (0)
; #define PG8_WAIT_V(n) asm volatile("s_waitcnt vmcnt(" #n ")" ::: "memory")
; #define PG8_WAIT_L(n) asm volatile("s_waitcnt lgkmcnt(" #n ")" ::: "memory")
; #define PG8_BAR __builtin_amdgcn_s_barrier()
; #define PG8_SCHED __builtin_amdgcn_sched_barrier(0)
; template <class Epi>
; __device__ __forceinline__ void gemm_phase(LAS unsigned char* lds, const Gemm g, const StaticOrder& S, const Epi& E) {
;     ...
;             PG8_LDB(B0, 0, 0); PG8_SCHED; PG8_LDA(At, 0, 0); PG8_STAGE(PG8_SA(1, 1), a1 + hstepA, voffA);
;             PG8_WAIT_L(8); PG8_BAR; PG8_WAIT_L(0); PG8_MMA(0, 0, At, B0); PG8_BAR; PG8_SCHED;
;             PG8_LDB(B1, 0, 1); PG8_STAGE(PG8_SB(0, 0), b2, voffB);
;             PG8_BAR; PG8_WAIT_L(0); PG8_MMA(0, 1, At, B1); PG8_BAR;
;             PG8_LDA(At, 0, 1); PG8_STAGE(PG8_SA(0, 0), a2, voffA);
;             PG8_BAR; PG8_WAIT_L(0); PG8_MMA(1, 0, At, B0); PG8_BAR; PG8_SCHED;
;             PG8_STAGE(PG8_SB(0, 1), b2 + hstepB, voffB);
;             PG8_WAIT_V(6); PG8_BAR; PG8_MMA(1, 1, At, B1); PG8_BAR;
.LBB0_158:
	s_add_u32 s42, s38, 0x100
	s_addc_u32 s43, s39, 0
	s_add_i32 s60, 0, 0x10000
	v_add_u32_e32 v0, s60, v152
	ds_read_b128 v[146:149], v0
	ds_read_b128 v[162:165], v0 offset:1024
	ds_read_b128 v[166:169], v0 offset:2048
	ds_read_b128 v[170:173], v0 offset:3072
	s_cmp_eq_u32 s59, 28
	s_cselect_b32 s25, s23, s43
	s_cselect_b32 s24, s55, s42
	s_cselect_b32 s5, s21, s58
	s_cselect_b32 s4, s56, s57
	s_add_i32 m0, s46, 0xc000
	ds_read_b128 v[174:177], v154
	ds_read_b128 v[188:191], v154 offset:1024
	ds_read_b128 v[192:195], v154 offset:2048
	ds_read_b128 v[196:199], v154 offset:3072
	ds_read_b128 v[200:203], v154 offset:4096
	ds_read_b128 v[204:207], v154 offset:5120
	ds_read_b128 v[208:211], v154 offset:6144
	ds_read_b128 v[212:215], v154 offset:7168
	global_load_lds_dwordx4 v140, s[38:39]
	s_add_i32 m0, s46, 0xe000
	s_nop 0
	global_load_lds_dwordx4 v142, s[38:39]
	s_waitcnt lgkmcnt(8)
	s_barrier
	s_waitcnt lgkmcnt(0)
	v_mfma_f32_16x16x32_bf16 v[126:129], v[146:149], v[174:177], v[126:129]
	v_mfma_f32_16x16x32_bf16 v[122:125], v[166:169], v[174:177], v[122:125]
	v_mfma_f32_16x16x32_bf16 v[110:113], v[146:149], v[192:195], v[110:113]
	v_mfma_f32_16x16x32_bf16 v[106:109], v[166:169], v[192:195], v[106:109]
	v_mfma_f32_16x16x32_bf16 v[94:97], v[146:149], v[200:203], v[94:97]
	v_mfma_f32_16x16x32_bf16 v[90:93], v[166:169], v[200:203], v[90:93]
	v_mfma_f32_16x16x32_bf16 v[78:81], v[146:149], v[208:211], v[78:81]
	v_mfma_f32_16x16x32_bf16 v[74:77], v[166:169], v[208:211], v[74:77]
	v_mfma_f32_16x16x32_bf16 v[126:129], v[162:165], v[188:191], v[126:129]
	v_mfma_f32_16x16x32_bf16 v[122:125], v[170:173], v[188:191], v[122:125]
	v_mfma_f32_16x16x32_bf16 v[110:113], v[162:165], v[196:199], v[110:113]
	v_mfma_f32_16x16x32_bf16 v[106:109], v[170:173], v[196:199], v[106:109]
	v_mfma_f32_16x16x32_bf16 v[94:97], v[162:165], v[204:207], v[94:97]
	v_mfma_f32_16x16x32_bf16 v[90:93], v[170:173], v[204:207], v[90:93]
	v_mfma_f32_16x16x32_bf16 v[78:81], v[162:165], v[212:215], v[78:81]
	v_mfma_f32_16x16x32_bf16 v[74:77], v[170:173], v[212:215], v[74:77]
	s_barrier
	s_add_i32 s61, 0, 0x14000
	s_add_i32 s38, s60, s45
	v_add_u32_e32 v0, s61, v152
	s_add_u32 s100, s4, s6
	s_addc_u32 s101, s5, s7
	s_mov_b32 m0, s38
	ds_read_b128 v[216:219], v0
	ds_read_b128 v[220:223], v0 offset:1024
	ds_read_b128 v[224:227], v0 offset:2048
	ds_read_b128 v[228:231], v0 offset:3072
	global_load_lds_dwordx4 v134, s[4:5]
	s_add_i32 m0, s38, 0x2000
	s_nop 0
	global_load_lds_dwordx4 v130, s[4:5]
	s_barrier
	s_waitcnt lgkmcnt(0)
	v_mfma_f32_16x16x32_bf16 v[118:121], v[216:219], v[174:177], v[118:121]
	v_mfma_f32_16x16x32_bf16 v[114:117], v[224:227], v[174:177], v[114:117]
	v_mfma_f32_16x16x32_bf16 v[102:105], v[216:219], v[192:195], v[102:105]
	v_mfma_f32_16x16x32_bf16 v[98:101], v[224:227], v[192:195], v[98:101]
	v_mfma_f32_16x16x32_bf16 v[86:89], v[216:219], v[200:203], v[86:89]
	v_mfma_f32_16x16x32_bf16 v[82:85], v[224:227], v[200:203], v[82:85]
	v_mfma_f32_16x16x32_bf16 v[70:73], v[216:219], v[208:211], v[70:73]
	v_mfma_f32_16x16x32_bf16 v[66:69], v[224:227], v[208:211], v[66:69]
	v_mfma_f32_16x16x32_bf16 v[118:121], v[220:223], v[188:191], v[118:121]
	v_mfma_f32_16x16x32_bf16 v[114:117], v[228:231], v[188:191], v[114:117]
	v_mfma_f32_16x16x32_bf16 v[102:105], v[220:223], v[196:199], v[102:105]
	v_mfma_f32_16x16x32_bf16 v[98:101], v[228:231], v[196:199], v[98:101]
	v_mfma_f32_16x16x32_bf16 v[86:89], v[220:223], v[204:207], v[86:89]
	v_mfma_f32_16x16x32_bf16 v[82:85], v[228:231], v[204:207], v[82:85]
	v_mfma_f32_16x16x32_bf16 v[70:73], v[220:223], v[212:215], v[70:73]
	v_mfma_f32_16x16x32_bf16 v[66:69], v[228:231], v[212:215], v[66:69]
	s_mov_b32 m0, s46
	s_add_u32 vcc_lo, s24, s6
	s_addc_u32 vcc_hi, s25, s7
	s_barrier
	ds_read_b128 v[174:177], v154 offset:16384
	ds_read_b128 v[188:191], v154 offset:17408
	ds_read_b128 v[192:195], v154 offset:18432
	ds_read_b128 v[196:199], v154 offset:19456
	ds_read_b128 v[200:203], v154 offset:20480
	ds_read_b128 v[204:207], v154 offset:21504
	ds_read_b128 v[208:211], v154 offset:22528
	ds_read_b128 v[212:215], v154 offset:23552
	global_load_lds_dwordx4 v136, s[24:25]
	s_mov_b32 m0, s47
	s_nop 0
	global_load_lds_dwordx4 v132, s[24:25]
	s_barrier
	s_waitcnt lgkmcnt(0)
	v_mfma_f32_16x16x32_bf16 v[62:65], v[146:149], v[174:177], v[62:65]
	v_mfma_f32_16x16x32_bf16 v[58:61], v[166:169], v[174:177], v[58:61]
	v_mfma_f32_16x16x32_bf16 v[46:49], v[146:149], v[192:195], v[46:49]
	v_mfma_f32_16x16x32_bf16 v[42:45], v[166:169], v[192:195], v[42:45]
	v_mfma_f32_16x16x32_bf16 v[30:33], v[146:149], v[200:203], v[30:33]
	v_mfma_f32_16x16x32_bf16 v[26:29], v[166:169], v[200:203], v[26:29]
	v_mfma_f32_16x16x32_bf16 v[14:17], v[146:149], v[208:211], v[14:17]
	v_mfma_f32_16x16x32_bf16 v[10:13], v[166:169], v[208:211], v[10:13]
	v_mfma_f32_16x16x32_bf16 v[62:65], v[162:165], v[188:191], v[62:65]
	v_mfma_f32_16x16x32_bf16 v[58:61], v[170:173], v[188:191], v[58:61]
	v_mfma_f32_16x16x32_bf16 v[46:49], v[162:165], v[196:199], v[46:49]
	v_mfma_f32_16x16x32_bf16 v[42:45], v[170:173], v[196:199], v[42:45]
	v_mfma_f32_16x16x32_bf16 v[30:33], v[162:165], v[204:207], v[30:33]
	v_mfma_f32_16x16x32_bf16 v[26:29], v[170:173], v[204:207], v[26:29]
	v_mfma_f32_16x16x32_bf16 v[14:17], v[162:165], v[212:215], v[14:17]
	v_mfma_f32_16x16x32_bf16 v[10:13], v[170:173], v[212:215], v[10:13]
	s_barrier
	s_add_u32 s38, s4, 0x80000
	s_addc_u32 s39, s5, 0
	s_add_i32 s60, s61, s45
	s_mov_b32 m0, s60
	s_nop 0
	global_load_lds_dwordx4 v134, s[38:39]
	s_add_i32 m0, s60, 0x2000
	s_nop 0
	global_load_lds_dwordx4 v130, s[38:39]
	s_waitcnt vmcnt(6)
	s_barrier
; #define PG8_STAGE(bufoff, gbase, voff) do { _Pragma("unroll") for (int _i = 0; _i < 2; ++_i) \
;         __builtin_amdgcn_global_load_lds((const unsigned*)((const char*)(gbase) + (voff)[_i]), (LAS unsigned*)(lds + (bufoff) + ldsw + _i * 8192), 16, 0, 0); } while (0)
; #define PG8_LDA(dst, b, h) do { _Pragma("unroll") for (int m = 0; m < 4; ++m) _Pragma("unroll") for (int k = 0; k < 2; ++k) dst[m][k] = *(const LAS bf16x8*)(lds + PG8_SA(b, h) + aoff + m * 2048 + k * 1024); } while (0)
; #define PG8_LDB(dst, b, h) do { _Pragma("unroll") for (int n = 0; n < 2; ++n) _Pragma("unroll") for (int k = 0; k < 2; ++k) dst[n][k] = *(const LAS bf16x8*)(lds + PG8_SB(b, h) + boff + n * 2048 + k * 1024); } while (0)
; #define PG8_MMA(ai, bj, At, Bt) do { __builtin_amdgcn_s_setprio(1); _Pragma("unroll") for (int m = 0; m < 4; ++m) _Pragma("unroll") for (int n = 0; n < 2; ++n) _Pragma("unroll") for (int k = 0; k < 2; ++k) \
;         acc[ai][bj][m][n] = __builtin_amdgcn_mfma_f32_16x16x32_bf16(Bt[n][k], At[m][k], acc[ai][bj][m][n], 0, 0, 0); __builtin_amdgcn_s_setprio(0); } while (0)
; #define PG8_WAIT_V(n) asm volatile("s_waitcnt vmcnt(" #n ")" ::: "memory")
; #define PG8_WAIT_L(n) asm volatile("s_waitcnt lgkmcnt(" #n ")" ::: "memory")
; #define PG8_BAR __builtin_amdgcn_s_barrier()
; #define PG8_SCHED __builtin_amdgcn_sched_barrier(0)
; template <class Epi>
; __device__ __forceinline__ void gemm_phase(LAS unsigned char* lds, const Gemm g, const StaticOrder& S, const Epi& E) {
;     ...
;             PG8_WAIT_V(6); PG8_BAR; PG8_MMA(1, 1, At, B1); PG8_BAR;
;             PG8_LDB(B0, 1, 0); PG8_SCHED; PG8_LDA(At, 1, 0); PG8_STAGE(PG8_SA(0, 1), a2 + hstepA, voffA);
;             PG8_WAIT_L(8); PG8_BAR; PG8_WAIT_L(0); PG8_MMA(0, 0, At, B0); PG8_BAR; PG8_SCHED;
;             PG8_LDB(B1, 1, 1); PG8_STAGE(PG8_SB(1, 0), b3, voffB);
;             PG8_BAR; PG8_WAIT_L(0); PG8_MMA(0, 1, At, B1); PG8_BAR;
;             PG8_LDA(At, 1, 1); PG8_STAGE(PG8_SA(1, 0), a3, voffA);
	v_mfma_f32_16x16x32_bf16 v[54:57], v[216:219], v[174:177], v[54:57]
	v_mfma_f32_16x16x32_bf16 v[50:53], v[224:227], v[174:177], v[50:53]
	v_mfma_f32_16x16x32_bf16 v[38:41], v[216:219], v[192:195], v[38:41]
	v_mfma_f32_16x16x32_bf16 v[34:37], v[224:227], v[192:195], v[34:37]
	v_mfma_f32_16x16x32_bf16 v[22:25], v[216:219], v[200:203], v[22:25]
	v_mfma_f32_16x16x32_bf16 v[18:21], v[224:227], v[200:203], v[18:21]
	v_mfma_f32_16x16x32_bf16 v[6:9], v[216:219], v[208:211], v[6:9]
	v_mfma_f32_16x16x32_bf16 v[2:5], v[224:227], v[208:211], v[2:5]
	v_mfma_f32_16x16x32_bf16 v[54:57], v[220:223], v[188:191], v[54:57]
	v_mfma_f32_16x16x32_bf16 v[50:53], v[228:231], v[188:191], v[50:53]
	v_mfma_f32_16x16x32_bf16 v[38:41], v[220:223], v[196:199], v[38:41]
	v_mfma_f32_16x16x32_bf16 v[34:37], v[228:231], v[196:199], v[34:37]
	v_mfma_f32_16x16x32_bf16 v[22:25], v[220:223], v[204:207], v[22:25]
	v_mfma_f32_16x16x32_bf16 v[18:21], v[228:231], v[204:207], v[18:21]
	v_mfma_f32_16x16x32_bf16 v[6:9], v[220:223], v[212:215], v[6:9]
	v_mfma_f32_16x16x32_bf16 v[2:5], v[228:231], v[212:215], v[2:5]
	s_add_i32 s38, 0, 0x18000
	v_add_u32_e32 v0, s38, v152
	s_barrier
	ds_read_b128 v[146:149], v0
	ds_read_b128 v[162:165], v0 offset:1024
	ds_read_b128 v[166:169], v0 offset:2048
	ds_read_b128 v[170:173], v0 offset:3072
	s_add_u32 s24, s24, 0x80000
	s_addc_u32 s25, s25, 0
	s_mov_b32 m0, s48
	ds_read_b128 v[174:177], v154 offset:32768
	ds_read_b128 v[188:191], v154 offset:33792
	ds_read_b128 v[192:195], v154 offset:34816
	ds_read_b128 v[196:199], v154 offset:35840
	ds_read_b128 v[200:203], v154 offset:36864
	ds_read_b128 v[204:207], v154 offset:37888
	ds_read_b128 v[208:211], v154 offset:38912
	ds_read_b128 v[212:215], v154 offset:39936
	global_load_lds_dwordx4 v136, s[24:25]
	s_mov_b32 m0, s49
	s_nop 0
	global_load_lds_dwordx4 v132, s[24:25]
	s_waitcnt lgkmcnt(8)
	s_barrier
	s_waitcnt lgkmcnt(0)
	v_mfma_f32_16x16x32_bf16 v[126:129], v[146:149], v[174:177], v[126:129]
	v_mfma_f32_16x16x32_bf16 v[122:125], v[166:169], v[174:177], v[122:125]
	v_mfma_f32_16x16x32_bf16 v[110:113], v[146:149], v[192:195], v[110:113]
	v_mfma_f32_16x16x32_bf16 v[106:109], v[166:169], v[192:195], v[106:109]
	v_mfma_f32_16x16x32_bf16 v[94:97], v[146:149], v[200:203], v[94:97]
	v_mfma_f32_16x16x32_bf16 v[90:93], v[166:169], v[200:203], v[90:93]
	v_mfma_f32_16x16x32_bf16 v[78:81], v[146:149], v[208:211], v[78:81]
	v_mfma_f32_16x16x32_bf16 v[74:77], v[166:169], v[208:211], v[74:77]
	v_mfma_f32_16x16x32_bf16 v[126:129], v[162:165], v[188:191], v[126:129]
	v_mfma_f32_16x16x32_bf16 v[122:125], v[170:173], v[188:191], v[122:125]
	v_mfma_f32_16x16x32_bf16 v[110:113], v[162:165], v[196:199], v[110:113]
	v_mfma_f32_16x16x32_bf16 v[106:109], v[170:173], v[196:199], v[106:109]
	v_mfma_f32_16x16x32_bf16 v[94:97], v[162:165], v[204:207], v[94:97]
	v_mfma_f32_16x16x32_bf16 v[90:93], v[170:173], v[204:207], v[90:93]
	v_mfma_f32_16x16x32_bf16 v[78:81], v[162:165], v[212:215], v[78:81]
	v_mfma_f32_16x16x32_bf16 v[74:77], v[170:173], v[212:215], v[74:77]
	s_barrier
	s_add_i32 s24, 0, 0x1c000
	s_add_i32 s25, s38, s45
	v_add_u32_e32 v0, s24, v152
	s_mov_b32 m0, s25
	ds_read_b128 v[216:219], v0
	ds_read_b128 v[220:223], v0 offset:1024
	ds_read_b128 v[224:227], v0 offset:2048
	ds_read_b128 v[228:231], v0 offset:3072
	global_load_lds_dwordx4 v134, s[100:101]
	s_add_i32 m0, s25, 0x2000
	s_nop 0
	global_load_lds_dwordx4 v130, s[100:101]
	s_barrier
	s_waitcnt lgkmcnt(0)
	v_mfma_f32_16x16x32_bf16 v[118:121], v[216:219], v[174:177], v[118:121]
	v_mfma_f32_16x16x32_bf16 v[114:117], v[224:227], v[174:177], v[114:117]
	v_mfma_f32_16x16x32_bf16 v[102:105], v[216:219], v[192:195], v[102:105]
	v_mfma_f32_16x16x32_bf16 v[98:101], v[224:227], v[192:195], v[98:101]
	v_mfma_f32_16x16x32_bf16 v[86:89], v[216:219], v[200:203], v[86:89]
	v_mfma_f32_16x16x32_bf16 v[82:85], v[224:227], v[200:203], v[82:85]
	v_mfma_f32_16x16x32_bf16 v[70:73], v[216:219], v[208:211], v[70:73]
	v_mfma_f32_16x16x32_bf16 v[66:69], v[224:227], v[208:211], v[66:69]
	v_mfma_f32_16x16x32_bf16 v[118:121], v[220:223], v[188:191], v[118:121]
	v_mfma_f32_16x16x32_bf16 v[114:117], v[228:231], v[188:191], v[114:117]
	v_mfma_f32_16x16x32_bf16 v[102:105], v[220:223], v[196:199], v[102:105]
	v_mfma_f32_16x16x32_bf16 v[98:101], v[228:231], v[196:199], v[98:101]
	v_mfma_f32_16x16x32_bf16 v[86:89], v[220:223], v[204:207], v[86:89]
	v_mfma_f32_16x16x32_bf16 v[82:85], v[228:231], v[204:207], v[82:85]
	v_mfma_f32_16x16x32_bf16 v[70:73], v[220:223], v[212:215], v[70:73]
	v_mfma_f32_16x16x32_bf16 v[66:69], v[228:231], v[212:215], v[66:69]
	s_mov_b32 m0, s50
	s_barrier
; __device__ __forceinline__ unsigned cvt_pk_bf16(float lo, float hi) { unsigned r; asm volatile("v_cvt_pk_bf16_f32 %0, %1, %2" : "=v"(r) : "v"(lo), "v"(hi)); return r; }
; #define PG8_STAGE(bufoff, gbase, voff) do { _Pragma("unroll") for (int _i = 0; _i < 2; ++_i) \
;         __builtin_amdgcn_global_load_lds((const unsigned*)((const char*)(gbase) + (voff)[_i]), (LAS unsigned*)(lds + (bufoff) + ldsw + _i * 8192), 16, 0, 0); } while (0)
; #define PG8_LDA(dst, b, h) do { _Pragma("unroll") for (int m = 0; m < 4; ++m) _Pragma("unroll") for (int k = 0; k < 2; ++k) dst[m][k] = *(const LAS bf16x8*)(lds + PG8_SA(b, h) + aoff + m * 2048 + k * 1024); } while (0)
; #define PG8_WAIT_V(n) asm volatile("s_waitcnt vmcnt(" #n ")" ::: "memory")
; #define PG8_WAIT_L(n) asm volatile("s_waitcnt lgkmcnt(" #n ")" ::: "memory")
; #define PG8_BAR __builtin_amdgcn_s_barrier()
; template <class Epi>
; __device__ __forceinline__ void gemm_phase(LAS unsigned char* lds, const Gemm g, const StaticOrder& S, const Epi& E) {
;     ...
;             PG8_LDA(At, 1, 1); PG8_STAGE(PG8_SA(1, 0), a3, voffA);
;             PG8_BAR; PG8_WAIT_L(0); PG8_MMA(1, 0, At, B0); PG8_BAR; PG8_SCHED;
;             PG8_STAGE(PG8_SB(1, 1), b3 + hstepB, voffB);
;             PG8_WAIT_V(6); PG8_BAR; PG8_MMA(1, 1, At, B1); PG8_BAR;
;     __device__ __forceinline__ void operator()(const f32x4 (&acc)[2][2][4][2], const Unit& u, int wr, int wc, int fr, int fq, const Pre& pp) const {
;         const int row0 = u.pm * BM + wr * 64 + fr, col0 = u.pn * BM + wc * 32 + 8 * fq;
;         const bool gm = (UG != nullptr) && (u.pn < DE / BM);
;         const float (&rs)[8] = pp.rs;
; #pragma unroll
;         for (int ai = 0; ai < 2; ++ai)
; #pragma unroll
;             for (int m = 0; m < 4; ++m) { const int r = row0 + ai * HALF + m * 16; const float inv = rsqrtf(rs[ai * 4 + m] * (1.0f / DM) + EPS);
; #pragma unroll
;                 for (int bj = 0; bj < 2; ++bj) { const f32x4 v0 = acc[ai][bj][m][0] * inv, v1 = acc[ai][bj][m][1] * inv; const int c = col0 + bj * HALF;
;                     u32x4 w; w.x = cvt_pk_bf16(v0[0], v0[1]); w.y = cvt_pk_bf16(v0[2], v0[3]); w.z = cvt_pk_bf16(v1[0], v1[1]); w.w = cvt_pk_bf16(v1[2], v1[3]);
;                     bf16_t* dst = gm ? UG + (size_t)(c >> 4) * GSTR + r * 16 + (c & 15) : O + (size_t)r * DE2 + c;
;                     *(u32x4*)dst = w; } }
	ds_read_b128 v[174:177], v154 offset:49152
	ds_read_b128 v[188:191], v154 offset:50176
	ds_read_b128 v[192:195], v154 offset:51200
	ds_read_b128 v[196:199], v154 offset:52224
	ds_read_b128 v[200:203], v154 offset:53248
	ds_read_b128 v[204:207], v154 offset:54272
	ds_read_b128 v[208:211], v154 offset:55296
	ds_read_b128 v[212:215], v154 offset:56320
	global_load_lds_dwordx4 v136, vcc
	s_mov_b32 m0, s51
	s_nop 0
	global_load_lds_dwordx4 v132, vcc
	s_barrier
	s_waitcnt lgkmcnt(0)
	v_mfma_f32_16x16x32_bf16 v[62:65], v[146:149], v[174:177], v[62:65]
	v_mfma_f32_16x16x32_bf16 v[58:61], v[166:169], v[174:177], v[58:61]
	v_mfma_f32_16x16x32_bf16 v[46:49], v[146:149], v[192:195], v[46:49]
	v_mfma_f32_16x16x32_bf16 v[42:45], v[166:169], v[192:195], v[42:45]
	v_mfma_f32_16x16x32_bf16 v[30:33], v[146:149], v[200:203], v[30:33]
	v_mfma_f32_16x16x32_bf16 v[26:29], v[166:169], v[200:203], v[26:29]
	v_mfma_f32_16x16x32_bf16 v[14:17], v[146:149], v[208:211], v[14:17]
	v_mfma_f32_16x16x32_bf16 v[10:13], v[166:169], v[208:211], v[10:13]
	v_mfma_f32_16x16x32_bf16 v[62:65], v[162:165], v[188:191], v[62:65]
	v_mfma_f32_16x16x32_bf16 v[58:61], v[170:173], v[188:191], v[58:61]
	v_mfma_f32_16x16x32_bf16 v[46:49], v[162:165], v[196:199], v[46:49]
	v_mfma_f32_16x16x32_bf16 v[42:45], v[170:173], v[196:199], v[42:45]
	v_mfma_f32_16x16x32_bf16 v[30:33], v[162:165], v[204:207], v[30:33]
	v_mfma_f32_16x16x32_bf16 v[26:29], v[170:173], v[204:207], v[26:29]
	v_mfma_f32_16x16x32_bf16 v[14:17], v[162:165], v[212:215], v[14:17]
	v_mfma_f32_16x16x32_bf16 v[10:13], v[170:173], v[212:215], v[10:13]
	s_barrier
	s_add_u32 s4, s4, 0x80080
	s_addc_u32 s5, s5, 0
	s_add_i32 s24, s24, s45
	s_mov_b32 m0, s24
	s_nop 0
	global_load_lds_dwordx4 v134, s[4:5]
	s_add_i32 m0, s24, 0x2000
	s_nop 0
	global_load_lds_dwordx4 v130, s[4:5]
	s_waitcnt vmcnt(6)
	s_barrier
	v_mfma_f32_16x16x32_bf16 v[54:57], v[216:219], v[174:177], v[54:57]
	v_mfma_f32_16x16x32_bf16 v[50:53], v[224:227], v[174:177], v[50:53]
	v_mfma_f32_16x16x32_bf16 v[38:41], v[216:219], v[192:195], v[38:41]
	v_mfma_f32_16x16x32_bf16 v[34:37], v[224:227], v[192:195], v[34:37]
	v_mfma_f32_16x16x32_bf16 v[22:25], v[216:219], v[200:203], v[22:25]
	v_mfma_f32_16x16x32_bf16 v[18:21], v[224:227], v[200:203], v[18:21]
	v_mfma_f32_16x16x32_bf16 v[6:9], v[216:219], v[208:211], v[6:9]
	v_mfma_f32_16x16x32_bf16 v[2:5], v[224:227], v[208:211], v[2:5]
	v_mfma_f32_16x16x32_bf16 v[54:57], v[220:223], v[188:191], v[54:57]
	v_mfma_f32_16x16x32_bf16 v[50:53], v[228:231], v[188:191], v[50:53]
	v_mfma_f32_16x16x32_bf16 v[38:41], v[220:223], v[196:199], v[38:41]
	v_mfma_f32_16x16x32_bf16 v[34:37], v[228:231], v[196:199], v[34:37]
	v_mfma_f32_16x16x32_bf16 v[22:25], v[220:223], v[204:207], v[22:25]
	v_mfma_f32_16x16x32_bf16 v[18:21], v[228:231], v[204:207], v[18:21]
	v_mfma_f32_16x16x32_bf16 v[6:9], v[220:223], v[212:215], v[6:9]
	v_mfma_f32_16x16x32_bf16 v[2:5], v[228:231], v[212:215], v[2:5]
	s_add_i32 s59, s59, 2
	s_add_u32 s57, s57, 0x100
	s_addc_u32 s58, s58, 0
	s_cmp_gt_u32 s59, 29
	s_mov_b64 s[38:39], s[42:43]
	s_barrier
	s_cbranch_scc0 .LBB0_158
	v_fmamk_f32 v0, v145, 0x3a000000, v233
	v_cmp_gt_f32_e32 vcc, s66, v0
	v_mul_f32_e32 v145, 0x4b800000, v0
	v_readlane_b32 s38, v254, 47
	v_cndmask_b32_e32 v0, v0, v145, vcc
	v_rsq_f32_e32 v0, v0
	v_lshl_add_u32 v146, s54, 8, v139
	s_cmp_gt_i32 s53, 15
	v_readlane_b32 s39, v254, 48
	v_mul_f32_e32 v145, 0x45800000, v0
	s_cselect_b64 s[4:5], -1, 0
	s_xor_b64 s[38:39], s[38:39], -1
	v_cndmask_b32_e32 v148, v0, v145, vcc
	v_ashrrev_i32_e32 v147, 31, v146
	s_or_b64 s[4:5], s[38:39], s[4:5]
	v_lshl_or_b32 v144, s53, 8, v153
	v_lshlrev_b64 v[150:151], 14, v[146:147]
	v_pk_mul_f32 v[128:129], v[148:149], v[128:129] op_sel_hi:[0,1]
	s_mov_b64 s[24:25], -1
	v_pk_mul_f32 v[126:127], v[148:149], v[126:127] op_sel_hi:[0,1]
	v_pk_mul_f32 v[162:163], v[148:149], v[124:125] op_sel_hi:[0,1]
	v_pk_mul_f32 v[124:125], v[148:149], v[122:123] op_sel_hi:[0,1]
	v_cvt_pk_bf16_f32 v122, v126, v127
	v_cvt_pk_bf16_f32 v123, v128, v129
	s_and_b64 vcc, exec, s[4:5]
	v_lshl_add_u64 v[128:129], s[16:17], 0, v[150:151]
	v_ashrrev_i32_e32 v145, 31, v144
	v_cvt_pk_bf16_f32 v124, v124, v125
	v_cvt_pk_bf16_f32 v125, v162, v163
	s_cbranch_vccz .LBB0_161
	v_lshl_add_u64 v[150:151], v[144:145], 1, v[128:129]
	s_mov_b64 s[24:25], 0

; #define PG8_STAGE(bufoff, gbase, voff) do { _Pragma("unroll") for (int _i = 0; _i < 2; ++_i) \
;         __builtin_amdgcn_global_load_lds((const unsigned*)((const char*)(gbase) + (voff)[_i]), (LAS unsigned*)(lds + (bufoff) + ldsw + _i * 8192), 16, 0, 0); } while (0)
; #define PG8_LDA(dst, b, h) do { _Pragma("unroll") for (int m = 0; m < 4; ++m) _Pragma("unroll") for (int k = 0; k < 2; ++k) dst[m][k] = *(const LAS bf16x8*)(lds + PG8_SA(b, h) + aoff + m * 2048 + k * 1024); } while (0)
; #define PG8_LDB(dst, b, h) do { _Pragma("unroll") for (int n = 0; n < 2; ++n) _Pragma("unroll") for (int k = 0; k < 2; ++k) dst[n][k] = *(const LAS bf16x8*)(lds + PG8_SB(b, h) + boff + n * 2048 + k * 1024); } while (0)
; #define PG8_MMA(ai, bj, At, Bt) do { __builtin_amdgcn_s_setprio(1); _Pragma("unroll") for (int m = 0; m < 4; ++m) _Pragma("unroll") for (int n = 0; n < 2; ++n) _Pragma("unroll") for (int k = 0; k < 2; ++k) \
;         acc[ai][bj][m][n] = __builtin_amdgcn_mfma_f32_16x16x32_bf16(Bt[n][k], At[m][k], acc[ai][bj][m][n], 0, 0, 0); __builtin_amdgcn_s_setprio(0); } while (0)
; #define PG8_WAIT_V(n) asm volatile("s_waitcnt vmcnt(" #n ")" ::: "memory")
; #define PG8_WAIT_L(n) asm volatile("s_waitcnt lgkmcnt(" #n ")" ::: "memory")
; #define PG8_BAR __builtin_amdgcn_s_barrier()
; #define PG8_SCHED __builtin_amdgcn_sched_barrier(0)
; template <class Epi>
; __device__ __forceinline__ void gemm_phase(LAS unsigned char* lds, const Gemm g, const StaticOrder& S, const Epi& E) {
;     ...
;             PG8_LDB(B0, 0, 0); PG8_SCHED; PG8_LDA(At, 0, 0); PG8_STAGE(PG8_SA(1, 1), a1 + hstepA, voffA);
;             PG8_WAIT_L(8); PG8_BAR; PG8_WAIT_L(0); PG8_MMA(0, 0, At, B0); PG8_BAR; PG8_SCHED;
;             PG8_LDB(B1, 0, 1); PG8_STAGE(PG8_SB(0, 0), b2, voffB);
;             PG8_BAR; PG8_WAIT_L(0); PG8_MMA(0, 1, At, B1); PG8_BAR;
;             PG8_LDA(At, 0, 1); PG8_STAGE(PG8_SA(0, 0), a2, voffA);
;             PG8_BAR; PG8_WAIT_L(0); PG8_MMA(1, 0, At, B0); PG8_BAR; PG8_SCHED;
;             PG8_STAGE(PG8_SB(0, 1), b2 + hstepB, voffB);
;             PG8_WAIT_V(6); PG8_BAR; PG8_MMA(1, 1, At, B1); PG8_BAR;
.LBB0_359:
	s_add_u32 s26, s22, 0x100
	s_addc_u32 s27, s23, 0
	s_add_i32 s65, 0, 0x10000
	v_add_u32_e32 v86, s65, v209
	ds_read_b128 v[70:73], v86
	ds_read_b128 v[74:77], v86 offset:1024
	ds_read_b128 v[82:85], v86 offset:2048
	ds_read_b128 v[86:89], v86 offset:3072
	s_cmp_eq_u32 s64, 60
	s_cselect_b32 s25, s17, s27
	s_cselect_b32 s24, s60, s26
	s_cselect_b32 s37, s15, s63
	s_cselect_b32 s36, s61, s62
	s_add_i32 m0, s53, 0xc000
	ds_read_b128 v[146:149], v211
	ds_read_b128 v[150:153], v211 offset:1024
	ds_read_b128 v[154:157], v211 offset:2048
	ds_read_b128 v[158:161], v211 offset:3072
	ds_read_b128 v[162:165], v211 offset:4096
	ds_read_b128 v[166:169], v211 offset:5120
	ds_read_b128 v[170:173], v211 offset:6144
	ds_read_b128 v[184:187], v211 offset:7168
	global_load_lds_dwordx4 v190, s[22:23]
	s_add_i32 m0, s53, 0xe000
	s_nop 0
	global_load_lds_dwordx4 v192, s[22:23]
	s_waitcnt lgkmcnt(8)
	s_barrier
	s_waitcnt lgkmcnt(0)
	v_mfma_f32_16x16x32_bf16 v[142:145], v[70:73], v[146:149], v[142:145]
	v_mfma_f32_16x16x32_bf16 v[138:141], v[82:85], v[146:149], v[138:141]
	v_mfma_f32_16x16x32_bf16 v[126:129], v[70:73], v[154:157], v[126:129]
	v_mfma_f32_16x16x32_bf16 v[122:125], v[82:85], v[154:157], v[122:125]
	v_mfma_f32_16x16x32_bf16 v[110:113], v[70:73], v[162:165], v[110:113]
	v_mfma_f32_16x16x32_bf16 v[106:109], v[82:85], v[162:165], v[106:109]
	v_mfma_f32_16x16x32_bf16 v[94:97], v[70:73], v[170:173], v[94:97]
	v_mfma_f32_16x16x32_bf16 v[90:93], v[82:85], v[170:173], v[90:93]
	v_mfma_f32_16x16x32_bf16 v[142:145], v[74:77], v[150:153], v[142:145]
	v_mfma_f32_16x16x32_bf16 v[138:141], v[86:89], v[150:153], v[138:141]
	v_mfma_f32_16x16x32_bf16 v[126:129], v[74:77], v[158:161], v[126:129]
	v_mfma_f32_16x16x32_bf16 v[122:125], v[86:89], v[158:161], v[122:125]
	v_mfma_f32_16x16x32_bf16 v[110:113], v[74:77], v[166:169], v[110:113]
	v_mfma_f32_16x16x32_bf16 v[106:109], v[86:89], v[166:169], v[106:109]
	v_mfma_f32_16x16x32_bf16 v[94:97], v[74:77], v[184:187], v[94:97]
	v_mfma_f32_16x16x32_bf16 v[90:93], v[86:89], v[184:187], v[90:93]
	s_barrier
	s_add_i32 s66, 0, 0x14000
	v_add_u32_e32 v206, s66, v209
	s_add_i32 s22, s65, s52
	ds_read_b128 v[194:197], v206
	ds_read_b128 v[198:201], v206 offset:1024
	ds_read_b128 v[202:205], v206 offset:2048
	ds_read_b128 v[212:215], v206 offset:3072
	s_add_u32 s100, s36, s6
	s_addc_u32 s101, s37, s7
	s_mov_b32 m0, s22
	s_nop 0
	global_load_lds_dwordx4 v0, s[36:37]
	s_add_i32 m0, s22, 0x2000
	s_nop 0
	global_load_lds_dwordx4 v174, s[36:37]
	s_barrier
	s_waitcnt lgkmcnt(0)
	v_mfma_f32_16x16x32_bf16 v[134:137], v[194:197], v[146:149], v[134:137]
	v_mfma_f32_16x16x32_bf16 v[130:133], v[202:205], v[146:149], v[130:133]
	v_mfma_f32_16x16x32_bf16 v[118:121], v[194:197], v[154:157], v[118:121]
	v_mfma_f32_16x16x32_bf16 v[114:117], v[202:205], v[154:157], v[114:117]
	v_mfma_f32_16x16x32_bf16 v[102:105], v[194:197], v[162:165], v[102:105]
	v_mfma_f32_16x16x32_bf16 v[98:101], v[202:205], v[162:165], v[98:101]
	v_mfma_f32_16x16x32_bf16 v[78:81], v[194:197], v[170:173], v[78:81]
	v_mfma_f32_16x16x32_bf16 v[66:69], v[202:205], v[170:173], v[66:69]
	v_mfma_f32_16x16x32_bf16 v[134:137], v[198:201], v[150:153], v[134:137]
	v_mfma_f32_16x16x32_bf16 v[130:133], v[212:215], v[150:153], v[130:133]
	v_mfma_f32_16x16x32_bf16 v[118:121], v[198:201], v[158:161], v[118:121]
	v_mfma_f32_16x16x32_bf16 v[114:117], v[212:215], v[158:161], v[114:117]
	v_mfma_f32_16x16x32_bf16 v[102:105], v[198:201], v[166:169], v[102:105]
	v_mfma_f32_16x16x32_bf16 v[98:101], v[212:215], v[166:169], v[98:101]
	v_mfma_f32_16x16x32_bf16 v[78:81], v[198:201], v[184:187], v[78:81]
	v_mfma_f32_16x16x32_bf16 v[66:69], v[212:215], v[184:187], v[66:69]
	s_mov_b32 m0, s53
	s_add_u32 vcc_lo, s24, s6
	s_addc_u32 vcc_hi, s25, s7
	s_barrier
	ds_read_b128 v[146:149], v211 offset:16384
	ds_read_b128 v[150:153], v211 offset:17408
	ds_read_b128 v[154:157], v211 offset:18432
	ds_read_b128 v[158:161], v211 offset:19456
	ds_read_b128 v[162:165], v211 offset:20480
	ds_read_b128 v[166:169], v211 offset:21504
	ds_read_b128 v[170:173], v211 offset:22528
	ds_read_b128 v[184:187], v211 offset:23552
	global_load_lds_dwordx4 v188, s[24:25]
	s_mov_b32 m0, s54
	s_nop 0
	global_load_lds_dwordx4 v176, s[24:25]
	s_barrier
	s_waitcnt lgkmcnt(0)
	v_mfma_f32_16x16x32_bf16 v[62:65], v[70:73], v[146:149], v[62:65]
	v_mfma_f32_16x16x32_bf16 v[58:61], v[82:85], v[146:149], v[58:61]
	v_mfma_f32_16x16x32_bf16 v[46:49], v[70:73], v[154:157], v[46:49]
	v_mfma_f32_16x16x32_bf16 v[42:45], v[82:85], v[154:157], v[42:45]
	v_mfma_f32_16x16x32_bf16 v[30:33], v[70:73], v[162:165], v[30:33]
	v_mfma_f32_16x16x32_bf16 v[26:29], v[82:85], v[162:165], v[26:29]
	v_mfma_f32_16x16x32_bf16 v[14:17], v[70:73], v[170:173], v[14:17]
	v_mfma_f32_16x16x32_bf16 v[10:13], v[82:85], v[170:173], v[10:13]
	v_mfma_f32_16x16x32_bf16 v[62:65], v[74:77], v[150:153], v[62:65]
	v_mfma_f32_16x16x32_bf16 v[58:61], v[86:89], v[150:153], v[58:61]
	v_mfma_f32_16x16x32_bf16 v[46:49], v[74:77], v[158:161], v[46:49]
	v_mfma_f32_16x16x32_bf16 v[42:45], v[86:89], v[158:161], v[42:45]
	v_mfma_f32_16x16x32_bf16 v[30:33], v[74:77], v[166:169], v[30:33]
	v_mfma_f32_16x16x32_bf16 v[26:29], v[86:89], v[166:169], v[26:29]
	v_mfma_f32_16x16x32_bf16 v[14:17], v[74:77], v[184:187], v[14:17]
	v_mfma_f32_16x16x32_bf16 v[10:13], v[86:89], v[184:187], v[10:13]
	s_barrier
	s_add_u32 s22, s36, 0x100000
	s_addc_u32 s23, s37, 0
	s_add_i32 s65, s66, s52
	s_mov_b32 m0, s65
	s_nop 0
	global_load_lds_dwordx4 v0, s[22:23]
	s_add_i32 m0, s65, 0x2000
	s_nop 0
	global_load_lds_dwordx4 v174, s[22:23]
	s_waitcnt vmcnt(6)
	s_barrier
; #define PG8_STAGE(bufoff, gbase, voff) do { _Pragma("unroll") for (int _i = 0; _i < 2; ++_i) \
;         __builtin_amdgcn_global_load_lds((const unsigned*)((const char*)(gbase) + (voff)[_i]), (LAS unsigned*)(lds + (bufoff) + ldsw + _i * 8192), 16, 0, 0); } while (0)
; #define PG8_LDA(dst, b, h) do { _Pragma("unroll") for (int m = 0; m < 4; ++m) _Pragma("unroll") for (int k = 0; k < 2; ++k) dst[m][k] = *(const LAS bf16x8*)(lds + PG8_SA(b, h) + aoff + m * 2048 + k * 1024); } while (0)
; #define PG8_LDB(dst, b, h) do { _Pragma("unroll") for (int n = 0; n < 2; ++n) _Pragma("unroll") for (int k = 0; k < 2; ++k) dst[n][k] = *(const LAS bf16x8*)(lds + PG8_SB(b, h) + boff + n * 2048 + k * 1024); } while (0)
; #define PG8_MMA(ai, bj, At, Bt) do { __builtin_amdgcn_s_setprio(1); _Pragma("unroll") for (int m = 0; m < 4; ++m) _Pragma("unroll") for (int n = 0; n < 2; ++n) _Pragma("unroll") for (int k = 0; k < 2; ++k) \
;         acc[ai][bj][m][n] = __builtin_amdgcn_mfma_f32_16x16x32_bf16(Bt[n][k], At[m][k], acc[ai][bj][m][n], 0, 0, 0); __builtin_amdgcn_s_setprio(0); } while (0)
; #define PG8_WAIT_V(n) asm volatile("s_waitcnt vmcnt(" #n ")" ::: "memory")
; #define PG8_WAIT_L(n) asm volatile("s_waitcnt lgkmcnt(" #n ")" ::: "memory")
; #define PG8_BAR __builtin_amdgcn_s_barrier()
; #define PG8_SCHED __builtin_amdgcn_sched_barrier(0)
; template <class Epi>
; __device__ __forceinline__ void gemm_phase(LAS unsigned char* lds, const Gemm g, const StaticOrder& S, const Epi& E) {
;     ...
;             PG8_WAIT_V(6); PG8_BAR; PG8_MMA(1, 1, At, B1); PG8_BAR;
;             PG8_LDB(B0, 1, 0); PG8_SCHED; PG8_LDA(At, 1, 0); PG8_STAGE(PG8_SA(0, 1), a2 + hstepA, voffA);
;             PG8_WAIT_L(8); PG8_BAR; PG8_WAIT_L(0); PG8_MMA(0, 0, At, B0); PG8_BAR; PG8_SCHED;
;             PG8_LDB(B1, 1, 1); PG8_STAGE(PG8_SB(1, 0), b3, voffB);
;             PG8_BAR; PG8_WAIT_L(0); PG8_MMA(0, 1, At, B1); PG8_BAR;
;             PG8_LDA(At, 1, 1); PG8_STAGE(PG8_SA(1, 0), a3, voffA);
	v_mfma_f32_16x16x32_bf16 v[54:57], v[194:197], v[146:149], v[54:57]
	v_mfma_f32_16x16x32_bf16 v[50:53], v[202:205], v[146:149], v[50:53]
	v_mfma_f32_16x16x32_bf16 v[38:41], v[194:197], v[154:157], v[38:41]
	v_mfma_f32_16x16x32_bf16 v[34:37], v[202:205], v[154:157], v[34:37]
	v_mfma_f32_16x16x32_bf16 v[22:25], v[194:197], v[162:165], v[22:25]
	v_mfma_f32_16x16x32_bf16 v[18:21], v[202:205], v[162:165], v[18:21]
	v_mfma_f32_16x16x32_bf16 v[6:9], v[194:197], v[170:173], v[6:9]
	v_mfma_f32_16x16x32_bf16 v[2:5], v[202:205], v[170:173], v[2:5]
	v_mfma_f32_16x16x32_bf16 v[54:57], v[198:201], v[150:153], v[54:57]
	v_mfma_f32_16x16x32_bf16 v[50:53], v[212:215], v[150:153], v[50:53]
	v_mfma_f32_16x16x32_bf16 v[38:41], v[198:201], v[158:161], v[38:41]
	v_mfma_f32_16x16x32_bf16 v[34:37], v[212:215], v[158:161], v[34:37]
	v_mfma_f32_16x16x32_bf16 v[22:25], v[198:201], v[166:169], v[22:25]
	v_mfma_f32_16x16x32_bf16 v[18:21], v[212:215], v[166:169], v[18:21]
	v_mfma_f32_16x16x32_bf16 v[6:9], v[198:201], v[184:187], v[6:9]
	v_mfma_f32_16x16x32_bf16 v[2:5], v[212:215], v[184:187], v[2:5]
	s_add_i32 s65, 0, 0x18000
	v_add_u32_e32 v86, s65, v209
	s_barrier
	ds_read_b128 v[70:73], v86
	ds_read_b128 v[74:77], v86 offset:1024
	ds_read_b128 v[82:85], v86 offset:2048
	ds_read_b128 v[86:89], v86 offset:3072
	s_add_u32 s22, s24, 0x100000
	s_addc_u32 s23, s25, 0
	s_mov_b32 m0, s55
	ds_read_b128 v[146:149], v211 offset:32768
	ds_read_b128 v[150:153], v211 offset:33792
	ds_read_b128 v[154:157], v211 offset:34816
	ds_read_b128 v[158:161], v211 offset:35840
	ds_read_b128 v[162:165], v211 offset:36864
	ds_read_b128 v[166:169], v211 offset:37888
	ds_read_b128 v[170:173], v211 offset:38912
	ds_read_b128 v[184:187], v211 offset:39936
	global_load_lds_dwordx4 v188, s[22:23]
	s_mov_b32 m0, s56
	s_nop 0
	global_load_lds_dwordx4 v176, s[22:23]
	s_waitcnt lgkmcnt(8)
	s_barrier
	s_waitcnt lgkmcnt(0)
	v_mfma_f32_16x16x32_bf16 v[142:145], v[70:73], v[146:149], v[142:145]
	v_mfma_f32_16x16x32_bf16 v[138:141], v[82:85], v[146:149], v[138:141]
	v_mfma_f32_16x16x32_bf16 v[126:129], v[70:73], v[154:157], v[126:129]
	v_mfma_f32_16x16x32_bf16 v[122:125], v[82:85], v[154:157], v[122:125]
	v_mfma_f32_16x16x32_bf16 v[110:113], v[70:73], v[162:165], v[110:113]
	v_mfma_f32_16x16x32_bf16 v[106:109], v[82:85], v[162:165], v[106:109]
	v_mfma_f32_16x16x32_bf16 v[94:97], v[70:73], v[170:173], v[94:97]
	v_mfma_f32_16x16x32_bf16 v[90:93], v[82:85], v[170:173], v[90:93]
	v_mfma_f32_16x16x32_bf16 v[142:145], v[74:77], v[150:153], v[142:145]
	v_mfma_f32_16x16x32_bf16 v[138:141], v[86:89], v[150:153], v[138:141]
	v_mfma_f32_16x16x32_bf16 v[126:129], v[74:77], v[158:161], v[126:129]
	v_mfma_f32_16x16x32_bf16 v[122:125], v[86:89], v[158:161], v[122:125]
	v_mfma_f32_16x16x32_bf16 v[110:113], v[74:77], v[166:169], v[110:113]
	v_mfma_f32_16x16x32_bf16 v[106:109], v[86:89], v[166:169], v[106:109]
	v_mfma_f32_16x16x32_bf16 v[94:97], v[74:77], v[184:187], v[94:97]
	v_mfma_f32_16x16x32_bf16 v[90:93], v[86:89], v[184:187], v[90:93]
	s_barrier
	s_add_i32 s24, 0, 0x1c000
	s_add_i32 s22, s65, s52
	v_add_u32_e32 v212, s24, v209
	s_mov_b32 m0, s22
	ds_read_b128 v[194:197], v212
	ds_read_b128 v[198:201], v212 offset:1024
	ds_read_b128 v[202:205], v212 offset:2048
	ds_read_b128 v[212:215], v212 offset:3072
	global_load_lds_dwordx4 v0, s[100:101]
	s_add_i32 m0, s22, 0x2000
	s_nop 0
	global_load_lds_dwordx4 v174, s[100:101]
	s_barrier
	s_waitcnt lgkmcnt(0)
	v_mfma_f32_16x16x32_bf16 v[134:137], v[194:197], v[146:149], v[134:137]
	v_mfma_f32_16x16x32_bf16 v[130:133], v[202:205], v[146:149], v[130:133]
	v_mfma_f32_16x16x32_bf16 v[118:121], v[194:197], v[154:157], v[118:121]
	v_mfma_f32_16x16x32_bf16 v[114:117], v[202:205], v[154:157], v[114:117]
	v_mfma_f32_16x16x32_bf16 v[102:105], v[194:197], v[162:165], v[102:105]
	v_mfma_f32_16x16x32_bf16 v[98:101], v[202:205], v[162:165], v[98:101]
	v_mfma_f32_16x16x32_bf16 v[78:81], v[194:197], v[170:173], v[78:81]
	v_mfma_f32_16x16x32_bf16 v[66:69], v[202:205], v[170:173], v[66:69]
	v_mfma_f32_16x16x32_bf16 v[134:137], v[198:201], v[150:153], v[134:137]
	v_mfma_f32_16x16x32_bf16 v[130:133], v[212:215], v[150:153], v[130:133]
	v_mfma_f32_16x16x32_bf16 v[118:121], v[198:201], v[158:161], v[118:121]
	v_mfma_f32_16x16x32_bf16 v[114:117], v[212:215], v[158:161], v[114:117]
	v_mfma_f32_16x16x32_bf16 v[102:105], v[198:201], v[166:169], v[102:105]
	v_mfma_f32_16x16x32_bf16 v[98:101], v[212:215], v[166:169], v[98:101]
	v_mfma_f32_16x16x32_bf16 v[78:81], v[198:201], v[184:187], v[78:81]
	v_mfma_f32_16x16x32_bf16 v[66:69], v[212:215], v[184:187], v[66:69]
	s_mov_b32 m0, s58
	s_barrier
	ds_read_b128 v[146:149], v211 offset:49152
	ds_read_b128 v[150:153], v211 offset:50176
	ds_read_b128 v[154:157], v211 offset:51200
	ds_read_b128 v[158:161], v211 offset:52224
	ds_read_b128 v[162:165], v211 offset:53248
	ds_read_b128 v[166:169], v211 offset:54272
	ds_read_b128 v[170:173], v211 offset:55296
	ds_read_b128 v[184:187], v211 offset:56320
	global_load_lds_dwordx4 v188, vcc
	s_mov_b32 m0, s59
	s_nop 0
	global_load_lds_dwordx4 v176, vcc
	s_barrier
; __device__ __forceinline__ unsigned cvt_pk_bf16(float lo, float hi) { unsigned r; asm volatile("v_cvt_pk_bf16_f32 %0, %1, %2" : "=v"(r) : "v"(lo), "v"(hi)); return r; }
; #define PG8_BAR __builtin_amdgcn_s_barrier()
; template <class Epi>
; __device__ __forceinline__ void gemm_phase(LAS unsigned char* lds, const Gemm g, const StaticOrder& S, const Epi& E) {
;     ...
;             PG8_LDA(At, 1, 1); PG8_STAGE(PG8_SA(1, 0), a3, voffA);
;             PG8_BAR; PG8_WAIT_L(0); PG8_MMA(1, 0, At, B0); PG8_BAR; PG8_SCHED;
;             PG8_STAGE(PG8_SB(1, 1), b3 + hstepB, voffB);
;             PG8_WAIT_V(6); PG8_BAR; PG8_MMA(1, 1, At, B1); PG8_BAR;
;     __device__ __forceinline__ void operator()(const f32x4 (&acc)[2][2][4][2], const Unit& u, int wr, int wc, int fr, int fq, const Pre&) const {
;         const int row0 = u.pm * BM + wr * 64 + fr, col0 = u.pn * BM + wc * 32 + 4 * fq;
;         f32x4 gv[2][2];
; #pragma unroll
;         for (int bj = 0; bj < 2; ++bj)
; #pragma unroll
;             for (int n = 0; n < 2; ++n) gv[bj][n] = *(const f32x4*)(gnext + col0 + bj * HALF + n * 16);
;         f32x4 xb[2][2][2];
; #pragma unroll
;         for (int bj = 0; bj < 2; ++bj)
; #pragma unroll
;             for (int n = 0; n < 2; ++n) xb[0][bj][n] = *(const f32x4*)(Xin + (size_t)row0 * DM + col0 + bj * HALF + n * 16);
; #pragma unroll
;         for (int grp = 0; grp < 8; ++grp) { const int ai = grp >> 2, m = grp & 3, cur = grp & 1; const int r = row0 + ai * HALF + m * 16; float ss = 0.f;
;             if (grp < 7) { const int rn = row0 + ((grp + 1) >> 2) * HALF + ((grp + 1) & 3) * 16;
; #pragma unroll
;                 for (int bj = 0; bj < 2; ++bj)
; #pragma unroll
;                     for (int n = 0; n < 2; ++n) xb[cur ^ 1][bj][n] = *(const f32x4*)(Xin + (size_t)rn * DM + col0 + bj * HALF + n * 16); }
; #pragma unroll
;             for (int bj = 0; bj < 2; ++bj)
; #pragma unroll
;                 for (int n = 0; n < 2; ++n) { const int c = col0 + bj * HALF + n * 16;
;                     const f32x4 xv = xb[cur][bj][n] + acc[ai][bj][m][n]; *(f32x4*)(X + (size_t)r * DM + c) = xv;
;                     ss += (xv[0] * xv[0] + xv[1] * xv[1]) + (xv[2] * xv[2] + xv[3] * xv[3]);
;                     if (H) { const f32x4 hv = xv * gv[bj][n]; u32x2 w; w.x = cvt_pk_bf16(hv[0], hv[1]); w.y = cvt_pk_bf16(hv[2], hv[3]);
;                         *(u32x2*)(H + (size_t)r * DM + c) = w; } }
	s_waitcnt lgkmcnt(0)
	v_mfma_f32_16x16x32_bf16 v[62:65], v[70:73], v[146:149], v[62:65]
	v_mfma_f32_16x16x32_bf16 v[58:61], v[82:85], v[146:149], v[58:61]
	v_mfma_f32_16x16x32_bf16 v[46:49], v[70:73], v[154:157], v[46:49]
	v_mfma_f32_16x16x32_bf16 v[42:45], v[82:85], v[154:157], v[42:45]
	v_mfma_f32_16x16x32_bf16 v[30:33], v[70:73], v[162:165], v[30:33]
	v_mfma_f32_16x16x32_bf16 v[26:29], v[82:85], v[162:165], v[26:29]
	v_mfma_f32_16x16x32_bf16 v[14:17], v[70:73], v[170:173], v[14:17]
	v_mfma_f32_16x16x32_bf16 v[10:13], v[82:85], v[170:173], v[10:13]
	v_mfma_f32_16x16x32_bf16 v[62:65], v[74:77], v[150:153], v[62:65]
	v_mfma_f32_16x16x32_bf16 v[58:61], v[86:89], v[150:153], v[58:61]
	v_mfma_f32_16x16x32_bf16 v[46:49], v[74:77], v[158:161], v[46:49]
	v_mfma_f32_16x16x32_bf16 v[42:45], v[86:89], v[158:161], v[42:45]
	v_mfma_f32_16x16x32_bf16 v[30:33], v[74:77], v[166:169], v[30:33]
	v_mfma_f32_16x16x32_bf16 v[26:29], v[86:89], v[166:169], v[26:29]
	v_mfma_f32_16x16x32_bf16 v[14:17], v[74:77], v[184:187], v[14:17]
	v_mfma_f32_16x16x32_bf16 v[10:13], v[86:89], v[184:187], v[10:13]
	s_barrier
	s_add_u32 s22, s36, 0x100080
	s_addc_u32 s23, s37, 0
	s_add_i32 s24, s24, s52
	s_mov_b32 m0, s24
	s_nop 0
	global_load_lds_dwordx4 v0, s[22:23]
	s_add_i32 m0, s24, 0x2000
	s_nop 0
	global_load_lds_dwordx4 v174, s[22:23]
	s_waitcnt vmcnt(6)
	s_barrier
	v_mfma_f32_16x16x32_bf16 v[54:57], v[194:197], v[146:149], v[54:57]
	v_mfma_f32_16x16x32_bf16 v[50:53], v[202:205], v[146:149], v[50:53]
	v_mfma_f32_16x16x32_bf16 v[38:41], v[194:197], v[154:157], v[38:41]
	v_mfma_f32_16x16x32_bf16 v[34:37], v[202:205], v[154:157], v[34:37]
	v_mfma_f32_16x16x32_bf16 v[22:25], v[194:197], v[162:165], v[22:25]
	v_mfma_f32_16x16x32_bf16 v[18:21], v[202:205], v[162:165], v[18:21]
	v_mfma_f32_16x16x32_bf16 v[6:9], v[194:197], v[170:173], v[6:9]
	v_mfma_f32_16x16x32_bf16 v[2:5], v[202:205], v[170:173], v[2:5]
	v_mfma_f32_16x16x32_bf16 v[54:57], v[198:201], v[150:153], v[54:57]
	v_mfma_f32_16x16x32_bf16 v[50:53], v[212:215], v[150:153], v[50:53]
	v_mfma_f32_16x16x32_bf16 v[38:41], v[198:201], v[158:161], v[38:41]
	v_mfma_f32_16x16x32_bf16 v[34:37], v[212:215], v[158:161], v[34:37]
	v_mfma_f32_16x16x32_bf16 v[22:25], v[198:201], v[166:169], v[22:25]
	v_mfma_f32_16x16x32_bf16 v[18:21], v[212:215], v[166:169], v[18:21]
	v_mfma_f32_16x16x32_bf16 v[6:9], v[198:201], v[184:187], v[6:9]
	v_mfma_f32_16x16x32_bf16 v[2:5], v[212:215], v[184:187], v[2:5]
	s_add_i32 s64, s64, 2
	s_add_u32 s62, s62, 0x100
	s_addc_u32 s63, s63, 0
	s_cmp_gt_u32 s64, 61
	s_mov_b64 s[22:23], s[26:27]
	s_barrier
	s_cbranch_scc0 .LBB0_359
	v_lshl_add_u32 v198, s44, 8, v208
	v_lshl_or_b32 v194, s45, 8, v210
	v_ashrrev_i32_e32 v199, 31, v198
	v_ashrrev_i32_e32 v195, 31, v194
	v_lshlrev_b64 v[204:205], 13, v[198:199]
	v_or_b32_e32 v202, 16, v198
	v_lshlrev_b64 v[196:197], 2, v[194:195]
	v_lshl_add_u64 v[146:147], s[0:1], 0, v[204:205]
	v_ashrrev_i32_e32 v203, 31, v202
	v_lshl_add_u64 v[70:71], s[4:5], 0, v[196:197]
	v_lshl_add_u64 v[146:147], v[146:147], 0, v[196:197]
	v_lshlrev_b64 v[200:201], 13, v[202:203]
	global_load_dwordx4 v[86:89], v[70:71], off
	global_load_dwordx4 v[82:85], v[70:71], off offset:64
	global_load_dwordx4 v[74:77], v[70:71], off offset:512
	s_nop 0
	global_load_dwordx4 v[70:73], v[70:71], off offset:576
	s_nop 0
	global_load_dwordx4 v[184:187], v[146:147], off
	global_load_dwordx4 v[170:173], v[146:147], off offset:64
	global_load_dwordx4 v[166:169], v[146:147], off offset:512
	global_load_dwordx4 v[162:165], v[146:147], off offset:576
	v_lshl_add_u64 v[146:147], s[0:1], 0, v[200:201]
	v_lshl_add_u64 v[146:147], v[146:147], 0, v[196:197]
	global_load_dwordx4 v[158:161], v[146:147], off
	global_load_dwordx4 v[154:157], v[146:147], off offset:64
	global_load_dwordx4 v[150:153], v[146:147], off offset:512
	s_nop 0
	global_load_dwordx4 v[146:149], v[146:147], off offset:576
	v_cndmask_b32_e64 v206, 0, 1, s[10:11]
	v_lshlrev_b64 v[212:213], 11, v[198:199]
	v_lshl_add_u64 v[204:205], s[48:49], 0, v[204:205]
	v_cmp_ne_u32_e64 s[44:45], 1, v206
	s_andn2_b64 vcc, exec, s[10:11]
	v_lshl_add_u64 v[206:207], v[204:205], 0, v[196:197]
	v_lshl_add_u64 v[204:205], v[212:213], 1, s[50:51]
	s_waitcnt vmcnt(0)
	v_pk_add_f32 v[144:145], v[144:145], v[186:187]
	v_pk_add_f32 v[142:143], v[142:143], v[184:185]
	global_store_dwordx4 v[206:207], v[142:145], off
	s_cbranch_vccnz .LBB0_362
	v_pk_mul_f32 v[184:185], v[88:89], v[144:145]
	v_pk_mul_f32 v[186:187], v[86:87], v[142:143]
	s_nop 0
	v_cvt_pk_bf16_f32 v186, v186, v187
	v_cvt_pk_bf16_f32 v187, v184, v185
	v_lshl_add_u64 v[184:185], v[194:195], 1, v[204:205]
	global_store_dwordx2 v[184:185], v[186:187], off

; #define PG8_STAGE(bufoff, gbase, voff) do { _Pragma("unroll") for (int _i = 0; _i < 2; ++_i) \
;         __builtin_amdgcn_global_load_lds((const unsigned*)((const char*)(gbase) + (voff)[_i]), (LAS unsigned*)(lds + (bufoff) + ldsw + _i * 8192), 16, 0, 0); } while (0)
; #define PG8_LDA(dst, b, h) do { _Pragma("unroll") for (int m = 0; m < 4; ++m) _Pragma("unroll") for (int k = 0; k < 2; ++k) dst[m][k] = *(const LAS bf16x8*)(lds + PG8_SA(b, h) + aoff + m * 2048 + k * 1024); } while (0)
; #define PG8_LDB(dst, b, h) do { _Pragma("unroll") for (int n = 0; n < 2; ++n) _Pragma("unroll") for (int k = 0; k < 2; ++k) dst[n][k] = *(const LAS bf16x8*)(lds + PG8_SB(b, h) + boff + n * 2048 + k * 1024); } while (0)
; #define PG8_MMA(ai, bj, At, Bt) do { __builtin_amdgcn_s_setprio(1); _Pragma("unroll") for (int m = 0; m < 4; ++m) _Pragma("unroll") for (int n = 0; n < 2; ++n) _Pragma("unroll") for (int k = 0; k < 2; ++k) \
;         acc[ai][bj][m][n] = __builtin_amdgcn_mfma_f32_16x16x32_bf16(Bt[n][k], At[m][k], acc[ai][bj][m][n], 0, 0, 0); __builtin_amdgcn_s_setprio(0); } while (0)
; #define PG8_WAIT_L(n) asm volatile("s_waitcnt lgkmcnt(" #n ")" ::: "memory")
; #define PG8_BAR __builtin_amdgcn_s_barrier()
; #define PG8_SCHED __builtin_amdgcn_sched_barrier(0)
; template <class Epi>
; __device__ __forceinline__ void gemm_phase(LAS unsigned char* lds, const Gemm g, const StaticOrder& S, const Epi& E) {
;     ...
;             PG8_LDB(B0, 0, 0); PG8_SCHED; PG8_LDA(At, 0, 0); PG8_STAGE(PG8_SA(1, 1), a1 + hstepA, voffA);
;             PG8_WAIT_L(8); PG8_BAR; PG8_WAIT_L(0); PG8_MMA(0, 0, At, B0); PG8_BAR; PG8_SCHED;
;             PG8_LDB(B1, 0, 1); PG8_STAGE(PG8_SB(0, 0), b2, voffB);
;             PG8_BAR; PG8_WAIT_L(0); PG8_MMA(0, 1, At, B1); PG8_BAR;
;             PG8_LDA(At, 0, 1); PG8_STAGE(PG8_SA(0, 0), a2, voffA);
;             PG8_BAR; PG8_WAIT_L(0); PG8_MMA(1, 0, At, B0); PG8_BAR; PG8_SCHED;
.LBB0_472:
	s_add_u32 s22, s4, s20
	s_addc_u32 s23, s5, s21
	s_add_u32 s22, s22, 0x100
	s_addc_u32 s23, s23, 0
	s_add_u32 s62, s17, s20
	s_addc_u32 s63, s58, s21
	s_add_i32 s64, 0, 0x10000
	v_add_u32_e32 v160, s64, v146
	ds_read_b128 v[148:151], v160
	ds_read_b128 v[152:155], v160 offset:1024
	ds_read_b128 v[156:159], v160 offset:2048
	ds_read_b128 v[160:163], v160 offset:3072
	s_cmpk_eq_i32 s20, 0x1f00
	s_cselect_b32 s25, s11, s23
	s_cselect_b32 s24, s59, s22
	s_cselect_b32 s23, s9, s63
	s_cselect_b32 s22, s60, s62
	v_lshl_add_u64 v[176:177], v[140:141], 0, s[20:21]
	s_add_i32 m0, s48, 0xc000
	ds_read_b128 v[164:167], v147
	ds_read_b128 v[168:171], v147 offset:1024
	ds_read_b128 v[172:175], v147 offset:2048
	ds_read_b128 v[184:187], v147 offset:3072
	ds_read_b128 v[188:191], v147 offset:4096
	ds_read_b128 v[192:195], v147 offset:5120
	ds_read_b128 v[196:199], v147 offset:6144
	ds_read_b128 v[200:203], v147 offset:7168
	global_load_lds_dwordx4 v[176:177], off
	v_lshl_add_u64 v[176:177], v[142:143], 0, s[20:21]
	s_add_i32 m0, s48, 0xe000
	s_nop 0
	global_load_lds_dwordx4 v[176:177], off
	s_waitcnt lgkmcnt(8)
	s_barrier
	s_waitcnt lgkmcnt(0)
	v_mfma_f32_16x16x32_bf16 v[126:129], v[148:151], v[164:167], v[126:129]
	v_mfma_f32_16x16x32_bf16 v[122:125], v[156:159], v[164:167], v[122:125]
	v_mfma_f32_16x16x32_bf16 v[110:113], v[148:151], v[172:175], v[110:113]
	v_mfma_f32_16x16x32_bf16 v[106:109], v[156:159], v[172:175], v[106:109]
	v_mfma_f32_16x16x32_bf16 v[94:97], v[148:151], v[188:191], v[94:97]
	v_mfma_f32_16x16x32_bf16 v[90:93], v[156:159], v[188:191], v[90:93]
	v_mfma_f32_16x16x32_bf16 v[78:81], v[148:151], v[196:199], v[78:81]
	v_mfma_f32_16x16x32_bf16 v[74:77], v[156:159], v[196:199], v[74:77]
	v_mfma_f32_16x16x32_bf16 v[126:129], v[152:155], v[168:171], v[126:129]
	v_mfma_f32_16x16x32_bf16 v[122:125], v[160:163], v[168:171], v[122:125]
	v_mfma_f32_16x16x32_bf16 v[110:113], v[152:155], v[184:187], v[110:113]
	v_mfma_f32_16x16x32_bf16 v[106:109], v[160:163], v[184:187], v[106:109]
	v_mfma_f32_16x16x32_bf16 v[94:97], v[152:155], v[192:195], v[94:97]
	v_mfma_f32_16x16x32_bf16 v[90:93], v[160:163], v[192:195], v[90:93]
	v_mfma_f32_16x16x32_bf16 v[78:81], v[152:155], v[200:203], v[78:81]
	v_mfma_f32_16x16x32_bf16 v[74:77], v[160:163], v[200:203], v[74:77]
	s_barrier
	s_add_i32 s65, 0, 0x14000
	v_add_u32_e32 v176, s65, v146
	s_add_i32 s62, s64, s39
	ds_read_b128 v[204:207], v176
	ds_read_b128 v[208:211], v176 offset:1024
	ds_read_b128 v[212:215], v176 offset:2048
	ds_read_b128 v[216:219], v176 offset:3072
	s_add_u32 s100, s22, s6
	s_addc_u32 s101, s23, s7
	s_mov_b32 m0, s62
	s_nop 0
	global_load_lds_dwordx4 v0, s[22:23]
	s_add_i32 m0, s62, 0x2000
	s_nop 0
	global_load_lds_dwordx4 v130, s[22:23]
	s_barrier
	s_waitcnt lgkmcnt(0)
	v_mfma_f32_16x16x32_bf16 v[118:121], v[204:207], v[164:167], v[118:121]
	v_mfma_f32_16x16x32_bf16 v[114:117], v[212:215], v[164:167], v[114:117]
	v_mfma_f32_16x16x32_bf16 v[102:105], v[204:207], v[172:175], v[102:105]
	v_mfma_f32_16x16x32_bf16 v[98:101], v[212:215], v[172:175], v[98:101]
	v_mfma_f32_16x16x32_bf16 v[86:89], v[204:207], v[188:191], v[86:89]
	v_mfma_f32_16x16x32_bf16 v[82:85], v[212:215], v[188:191], v[82:85]
	v_mfma_f32_16x16x32_bf16 v[70:73], v[204:207], v[196:199], v[70:73]
	v_mfma_f32_16x16x32_bf16 v[66:69], v[212:215], v[196:199], v[66:69]
	v_mfma_f32_16x16x32_bf16 v[118:121], v[208:211], v[168:171], v[118:121]
	v_mfma_f32_16x16x32_bf16 v[114:117], v[216:219], v[168:171], v[114:117]
	v_mfma_f32_16x16x32_bf16 v[102:105], v[208:211], v[184:187], v[102:105]
	v_mfma_f32_16x16x32_bf16 v[98:101], v[216:219], v[184:187], v[98:101]
	v_mfma_f32_16x16x32_bf16 v[86:89], v[208:211], v[192:195], v[86:89]
	v_mfma_f32_16x16x32_bf16 v[82:85], v[216:219], v[192:195], v[82:85]
	v_mfma_f32_16x16x32_bf16 v[70:73], v[208:211], v[200:203], v[70:73]
	v_mfma_f32_16x16x32_bf16 v[66:69], v[216:219], v[200:203], v[66:69]
	s_mov_b32 m0, s48
	s_add_u32 vcc_lo, s24, s6
	s_addc_u32 vcc_hi, s25, s7
	s_barrier
	ds_read_b128 v[164:167], v147 offset:16384
	ds_read_b128 v[168:171], v147 offset:17408
	ds_read_b128 v[172:175], v147 offset:18432
	ds_read_b128 v[184:187], v147 offset:19456
	ds_read_b128 v[188:191], v147 offset:20480
	ds_read_b128 v[192:195], v147 offset:21504
	ds_read_b128 v[196:199], v147 offset:22528
	ds_read_b128 v[200:203], v147 offset:23552
	global_load_lds_dwordx4 v134, s[24:25]
	s_mov_b32 m0, s49
	s_nop 0
	global_load_lds_dwordx4 v132, s[24:25]
	s_barrier
	s_waitcnt lgkmcnt(0)
	v_mfma_f32_16x16x32_bf16 v[62:65], v[148:151], v[164:167], v[62:65]
	v_mfma_f32_16x16x32_bf16 v[58:61], v[156:159], v[164:167], v[58:61]
	v_mfma_f32_16x16x32_bf16 v[46:49], v[148:151], v[172:175], v[46:49]
	v_mfma_f32_16x16x32_bf16 v[42:45], v[156:159], v[172:175], v[42:45]
	v_mfma_f32_16x16x32_bf16 v[30:33], v[148:151], v[188:191], v[30:33]
	v_mfma_f32_16x16x32_bf16 v[26:29], v[156:159], v[188:191], v[26:29]
	v_mfma_f32_16x16x32_bf16 v[18:21], v[148:151], v[196:199], v[18:21]
	v_mfma_f32_16x16x32_bf16 v[10:13], v[156:159], v[196:199], v[10:13]
	v_mfma_f32_16x16x32_bf16 v[62:65], v[152:155], v[168:171], v[62:65]
	v_mfma_f32_16x16x32_bf16 v[58:61], v[160:163], v[168:171], v[58:61]
	v_mfma_f32_16x16x32_bf16 v[46:49], v[152:155], v[184:187], v[46:49]
	v_mfma_f32_16x16x32_bf16 v[42:45], v[160:163], v[184:187], v[42:45]
	v_mfma_f32_16x16x32_bf16 v[30:33], v[152:155], v[192:195], v[30:33]
	v_mfma_f32_16x16x32_bf16 v[26:29], v[160:163], v[192:195], v[26:29]
	v_mfma_f32_16x16x32_bf16 v[18:21], v[152:155], v[200:203], v[18:21]
	v_mfma_f32_16x16x32_bf16 v[10:13], v[160:163], v[200:203], v[10:13]
	s_barrier
; #define PG8_STAGE(bufoff, gbase, voff) do { _Pragma("unroll") for (int _i = 0; _i < 2; ++_i) \
;         __builtin_amdgcn_global_load_lds((const unsigned*)((const char*)(gbase) + (voff)[_i]), (LAS unsigned*)(lds + (bufoff) + ldsw + _i * 8192), 16, 0, 0); } while (0)
; #define PG8_LDA(dst, b, h) do { _Pragma("unroll") for (int m = 0; m < 4; ++m) _Pragma("unroll") for (int k = 0; k < 2; ++k) dst[m][k] = *(const LAS bf16x8*)(lds + PG8_SA(b, h) + aoff + m * 2048 + k * 1024); } while (0)
; #define PG8_LDB(dst, b, h) do { _Pragma("unroll") for (int n = 0; n < 2; ++n) _Pragma("unroll") for (int k = 0; k < 2; ++k) dst[n][k] = *(const LAS bf16x8*)(lds + PG8_SB(b, h) + boff + n * 2048 + k * 1024); } while (0)
; #define PG8_MMA(ai, bj, At, Bt) do { __builtin_amdgcn_s_setprio(1); _Pragma("unroll") for (int m = 0; m < 4; ++m) _Pragma("unroll") for (int n = 0; n < 2; ++n) _Pragma("unroll") for (int k = 0; k < 2; ++k) \
;         acc[ai][bj][m][n] = __builtin_amdgcn_mfma_f32_16x16x32_bf16(Bt[n][k], At[m][k], acc[ai][bj][m][n], 0, 0, 0); __builtin_amdgcn_s_setprio(0); } while (0)
; #define PG8_WAIT_V(n) asm volatile("s_waitcnt vmcnt(" #n ")" ::: "memory")
; #define PG8_WAIT_L(n) asm volatile("s_waitcnt lgkmcnt(" #n ")" ::: "memory")
; #define PG8_BAR __builtin_amdgcn_s_barrier()
; #define PG8_SCHED __builtin_amdgcn_sched_barrier(0)
; template <class Epi>
; __device__ __forceinline__ void gemm_phase(LAS unsigned char* lds, const Gemm g, const StaticOrder& S, const Epi& E) {
;     ...
;             PG8_STAGE(PG8_SB(0, 1), b2 + hstepB, voffB);
;             PG8_WAIT_V(6); PG8_BAR; PG8_MMA(1, 1, At, B1); PG8_BAR;
;             PG8_LDB(B0, 1, 0); PG8_SCHED; PG8_LDA(At, 1, 0); PG8_STAGE(PG8_SA(0, 1), a2 + hstepA, voffA);
;             PG8_WAIT_L(8); PG8_BAR; PG8_WAIT_L(0); PG8_MMA(0, 0, At, B0); PG8_BAR; PG8_SCHED;
;             PG8_LDB(B1, 1, 1); PG8_STAGE(PG8_SB(1, 0), b3, voffB);
;             PG8_BAR; PG8_WAIT_L(0); PG8_MMA(0, 1, At, B1); PG8_BAR;
;             PG8_LDA(At, 1, 1); PG8_STAGE(PG8_SA(1, 0), a3, voffA);
;             PG8_BAR; PG8_WAIT_L(0); PG8_MMA(1, 0, At, B0); PG8_BAR; PG8_SCHED;
	s_add_u32 s62, s22, 0x100000
	s_addc_u32 s63, s23, 0
	s_add_i32 s64, s65, s39
	s_mov_b32 m0, s64
	s_nop 0
	global_load_lds_dwordx4 v0, s[62:63]
	s_add_i32 m0, s64, 0x2000
	s_nop 0
	global_load_lds_dwordx4 v130, s[62:63]
	s_waitcnt vmcnt(6)
	s_barrier
	v_mfma_f32_16x16x32_bf16 v[54:57], v[204:207], v[164:167], v[54:57]
	v_mfma_f32_16x16x32_bf16 v[50:53], v[212:215], v[164:167], v[50:53]
	v_mfma_f32_16x16x32_bf16 v[38:41], v[204:207], v[172:175], v[38:41]
	v_mfma_f32_16x16x32_bf16 v[34:37], v[212:215], v[172:175], v[34:37]
	v_mfma_f32_16x16x32_bf16 v[22:25], v[204:207], v[188:191], v[22:25]
	v_mfma_f32_16x16x32_bf16 v[14:17], v[212:215], v[188:191], v[14:17]
	v_mfma_f32_16x16x32_bf16 v[6:9], v[204:207], v[196:199], v[6:9]
	v_mfma_f32_16x16x32_bf16 v[2:5], v[212:215], v[196:199], v[2:5]
	v_mfma_f32_16x16x32_bf16 v[54:57], v[208:211], v[168:171], v[54:57]
	v_mfma_f32_16x16x32_bf16 v[50:53], v[216:219], v[168:171], v[50:53]
	v_mfma_f32_16x16x32_bf16 v[38:41], v[208:211], v[184:187], v[38:41]
	v_mfma_f32_16x16x32_bf16 v[34:37], v[216:219], v[184:187], v[34:37]
	v_mfma_f32_16x16x32_bf16 v[22:25], v[208:211], v[192:195], v[22:25]
	v_mfma_f32_16x16x32_bf16 v[14:17], v[216:219], v[192:195], v[14:17]
	v_mfma_f32_16x16x32_bf16 v[6:9], v[208:211], v[200:203], v[6:9]
	v_mfma_f32_16x16x32_bf16 v[2:5], v[216:219], v[200:203], v[2:5]
	s_add_i32 s62, 0, 0x18000
	v_add_u32_e32 v160, s62, v146
	s_barrier
	ds_read_b128 v[148:151], v160
	ds_read_b128 v[152:155], v160 offset:1024
	ds_read_b128 v[156:159], v160 offset:2048
	ds_read_b128 v[160:163], v160 offset:3072
	s_add_u32 s24, s24, 0x100000
	s_addc_u32 s25, s25, 0
	s_mov_b32 m0, s50
	ds_read_b128 v[164:167], v147 offset:32768
	ds_read_b128 v[168:171], v147 offset:33792
	ds_read_b128 v[172:175], v147 offset:34816
	ds_read_b128 v[184:187], v147 offset:35840
	ds_read_b128 v[188:191], v147 offset:36864
	ds_read_b128 v[192:195], v147 offset:37888
	ds_read_b128 v[196:199], v147 offset:38912
	ds_read_b128 v[200:203], v147 offset:39936
	global_load_lds_dwordx4 v134, s[24:25]
	s_mov_b32 m0, s51
	s_nop 0
	global_load_lds_dwordx4 v132, s[24:25]
	s_waitcnt lgkmcnt(8)
	s_barrier
	s_waitcnt lgkmcnt(0)
	v_mfma_f32_16x16x32_bf16 v[126:129], v[148:151], v[164:167], v[126:129]
	v_mfma_f32_16x16x32_bf16 v[122:125], v[156:159], v[164:167], v[122:125]
	v_mfma_f32_16x16x32_bf16 v[110:113], v[148:151], v[172:175], v[110:113]
	v_mfma_f32_16x16x32_bf16 v[106:109], v[156:159], v[172:175], v[106:109]
	v_mfma_f32_16x16x32_bf16 v[94:97], v[148:151], v[188:191], v[94:97]
	v_mfma_f32_16x16x32_bf16 v[90:93], v[156:159], v[188:191], v[90:93]
	v_mfma_f32_16x16x32_bf16 v[78:81], v[148:151], v[196:199], v[78:81]
	v_mfma_f32_16x16x32_bf16 v[74:77], v[156:159], v[196:199], v[74:77]
	v_mfma_f32_16x16x32_bf16 v[126:129], v[152:155], v[168:171], v[126:129]
	v_mfma_f32_16x16x32_bf16 v[122:125], v[160:163], v[168:171], v[122:125]
	v_mfma_f32_16x16x32_bf16 v[110:113], v[152:155], v[184:187], v[110:113]
	v_mfma_f32_16x16x32_bf16 v[106:109], v[160:163], v[184:187], v[106:109]
	v_mfma_f32_16x16x32_bf16 v[94:97], v[152:155], v[192:195], v[94:97]
	v_mfma_f32_16x16x32_bf16 v[90:93], v[160:163], v[192:195], v[90:93]
	v_mfma_f32_16x16x32_bf16 v[78:81], v[152:155], v[200:203], v[78:81]
	v_mfma_f32_16x16x32_bf16 v[74:77], v[160:163], v[200:203], v[74:77]
	s_barrier
	s_add_i32 s24, 0, 0x1c000
	s_add_i32 s25, s62, s39
	v_add_u32_e32 v216, s24, v146
	s_mov_b32 m0, s25
	ds_read_b128 v[204:207], v216
	ds_read_b128 v[208:211], v216 offset:1024
	ds_read_b128 v[212:215], v216 offset:2048
	ds_read_b128 v[216:219], v216 offset:3072
	global_load_lds_dwordx4 v0, s[100:101]
	s_add_i32 m0, s25, 0x2000
	s_nop 0
	global_load_lds_dwordx4 v130, s[100:101]
	s_barrier
	s_waitcnt lgkmcnt(0)
	v_mfma_f32_16x16x32_bf16 v[118:121], v[204:207], v[164:167], v[118:121]
	v_mfma_f32_16x16x32_bf16 v[114:117], v[212:215], v[164:167], v[114:117]
	v_mfma_f32_16x16x32_bf16 v[102:105], v[204:207], v[172:175], v[102:105]
	v_mfma_f32_16x16x32_bf16 v[98:101], v[212:215], v[172:175], v[98:101]
	v_mfma_f32_16x16x32_bf16 v[86:89], v[204:207], v[188:191], v[86:89]
	v_mfma_f32_16x16x32_bf16 v[82:85], v[212:215], v[188:191], v[82:85]
	v_mfma_f32_16x16x32_bf16 v[70:73], v[204:207], v[196:199], v[70:73]
	v_mfma_f32_16x16x32_bf16 v[66:69], v[212:215], v[196:199], v[66:69]
	v_mfma_f32_16x16x32_bf16 v[118:121], v[208:211], v[168:171], v[118:121]
	v_mfma_f32_16x16x32_bf16 v[114:117], v[216:219], v[168:171], v[114:117]
	v_mfma_f32_16x16x32_bf16 v[102:105], v[208:211], v[184:187], v[102:105]
	v_mfma_f32_16x16x32_bf16 v[98:101], v[216:219], v[184:187], v[98:101]
	v_mfma_f32_16x16x32_bf16 v[86:89], v[208:211], v[192:195], v[86:89]
	v_mfma_f32_16x16x32_bf16 v[82:85], v[216:219], v[192:195], v[82:85]
	v_mfma_f32_16x16x32_bf16 v[70:73], v[208:211], v[200:203], v[70:73]
	v_mfma_f32_16x16x32_bf16 v[66:69], v[216:219], v[200:203], v[66:69]
	s_mov_b32 m0, s54
	s_barrier
	ds_read_b128 v[164:167], v147 offset:49152
	ds_read_b128 v[168:171], v147 offset:50176
	ds_read_b128 v[172:175], v147 offset:51200
	ds_read_b128 v[184:187], v147 offset:52224
	ds_read_b128 v[188:191], v147 offset:53248
	ds_read_b128 v[192:195], v147 offset:54272
	ds_read_b128 v[196:199], v147 offset:55296
	ds_read_b128 v[200:203], v147 offset:56320
	global_load_lds_dwordx4 v134, vcc
	s_mov_b32 m0, s55
	s_nop 0
	global_load_lds_dwordx4 v132, vcc
	s_barrier
; #define PG8_STAGE(bufoff, gbase, voff) do { _Pragma("unroll") for (int _i = 0; _i < 2; ++_i) \
;         __builtin_amdgcn_global_load_lds((const unsigned*)((const char*)(gbase) + (voff)[_i]), (LAS unsigned*)(lds + (bufoff) + ldsw + _i * 8192), 16, 0, 0); } while (0)
; #define PG8_MMA(ai, bj, At, Bt) do { __builtin_amdgcn_s_setprio(1); _Pragma("unroll") for (int m = 0; m < 4; ++m) _Pragma("unroll") for (int n = 0; n < 2; ++n) _Pragma("unroll") for (int k = 0; k < 2; ++k) \
;         acc[ai][bj][m][n] = __builtin_amdgcn_mfma_f32_16x16x32_bf16(Bt[n][k], At[m][k], acc[ai][bj][m][n], 0, 0, 0); __builtin_amdgcn_s_setprio(0); } while (0)
; #define PG8_WAIT_V(n) asm volatile("s_waitcnt vmcnt(" #n ")" ::: "memory")
; #define PG8_BAR __builtin_amdgcn_s_barrier()
; template <class Epi>
; __device__ __forceinline__ void gemm_phase(LAS unsigned char* lds, const Gemm g, const StaticOrder& S, const Epi& E) {
;     ...
;             PG8_STAGE(PG8_SB(1, 1), b3 + hstepB, voffB);
;             PG8_WAIT_V(6); PG8_BAR; PG8_MMA(1, 1, At, B1); PG8_BAR;
;         }
;         if constexpr (!Epi::AFTER_DRAIN) E(acc, cur, wr, wc, fr, fq, pre);
;         if (!has_next) break;
; #pragma unroll
;         for (int a = 0; a < 2; ++a)
; #pragma unroll
;             for (int b = 0; b < 2; ++b)
; #pragma unroll
;                 for (int m = 0; m < 4; ++m)
; #pragma unroll
;                     for (int n = 0; n < 2; ++n) acc[a][b][m][n] = (f32x4){0.f, 0.f, 0.f, 0.f};
;         cur = nxt; cA = nA; cB = nB; ++ui;
;         pre = E.pre(cur, wr, fr);
	s_waitcnt lgkmcnt(0)
	v_mfma_f32_16x16x32_bf16 v[62:65], v[148:151], v[164:167], v[62:65]
	v_mfma_f32_16x16x32_bf16 v[58:61], v[156:159], v[164:167], v[58:61]
	v_mfma_f32_16x16x32_bf16 v[46:49], v[148:151], v[172:175], v[46:49]
	v_mfma_f32_16x16x32_bf16 v[42:45], v[156:159], v[172:175], v[42:45]
	v_mfma_f32_16x16x32_bf16 v[30:33], v[148:151], v[188:191], v[30:33]
	v_mfma_f32_16x16x32_bf16 v[26:29], v[156:159], v[188:191], v[26:29]
	v_mfma_f32_16x16x32_bf16 v[18:21], v[148:151], v[196:199], v[18:21]
	v_mfma_f32_16x16x32_bf16 v[10:13], v[156:159], v[196:199], v[10:13]
	v_mfma_f32_16x16x32_bf16 v[62:65], v[152:155], v[168:171], v[62:65]
	v_mfma_f32_16x16x32_bf16 v[58:61], v[160:163], v[168:171], v[58:61]
	v_mfma_f32_16x16x32_bf16 v[46:49], v[152:155], v[184:187], v[46:49]
	v_mfma_f32_16x16x32_bf16 v[42:45], v[160:163], v[184:187], v[42:45]
	v_mfma_f32_16x16x32_bf16 v[30:33], v[152:155], v[192:195], v[30:33]
	v_mfma_f32_16x16x32_bf16 v[26:29], v[160:163], v[192:195], v[26:29]
	v_mfma_f32_16x16x32_bf16 v[18:21], v[152:155], v[200:203], v[18:21]
	v_mfma_f32_16x16x32_bf16 v[10:13], v[160:163], v[200:203], v[10:13]
	s_barrier
	s_add_u32 s22, s22, 0x100080
	s_addc_u32 s23, s23, 0
	s_add_i32 s24, s24, s39
	s_mov_b32 m0, s24
	s_nop 0
	global_load_lds_dwordx4 v0, s[22:23]
	s_add_i32 m0, s24, 0x2000
	s_nop 0
	global_load_lds_dwordx4 v130, s[22:23]
	s_waitcnt vmcnt(6)
	s_barrier
	v_mfma_f32_16x16x32_bf16 v[54:57], v[204:207], v[164:167], v[54:57]
	v_mfma_f32_16x16x32_bf16 v[50:53], v[212:215], v[164:167], v[50:53]
	v_mfma_f32_16x16x32_bf16 v[38:41], v[204:207], v[172:175], v[38:41]
	v_mfma_f32_16x16x32_bf16 v[34:37], v[212:215], v[172:175], v[34:37]
	v_mfma_f32_16x16x32_bf16 v[22:25], v[204:207], v[188:191], v[22:25]
	v_mfma_f32_16x16x32_bf16 v[14:17], v[212:215], v[188:191], v[14:17]
	v_mfma_f32_16x16x32_bf16 v[6:9], v[204:207], v[196:199], v[6:9]
	v_mfma_f32_16x16x32_bf16 v[2:5], v[212:215], v[196:199], v[2:5]
	v_mfma_f32_16x16x32_bf16 v[54:57], v[208:211], v[168:171], v[54:57]
	v_mfma_f32_16x16x32_bf16 v[50:53], v[216:219], v[168:171], v[50:53]
	v_mfma_f32_16x16x32_bf16 v[38:41], v[208:211], v[184:187], v[38:41]
	v_mfma_f32_16x16x32_bf16 v[34:37], v[216:219], v[184:187], v[34:37]
	v_mfma_f32_16x16x32_bf16 v[22:25], v[208:211], v[192:195], v[22:25]
	v_mfma_f32_16x16x32_bf16 v[14:17], v[216:219], v[192:195], v[14:17]
	v_mfma_f32_16x16x32_bf16 v[6:9], v[208:211], v[200:203], v[6:9]
	v_mfma_f32_16x16x32_bf16 v[2:5], v[216:219], v[200:203], v[2:5]
	s_add_i32 s61, s61, 2
	s_add_u32 s20, s20, 0x100
	s_addc_u32 s21, s21, 0
	s_cmp_gt_u32 s61, 61
	s_barrier
	s_cbranch_scc0 .LBB0_472
	s_add_u32 s20, s17, 0xffffff00
	s_addc_u32 s21, s58, -1
	s_andn2_b64 vcc, exec, s[42:43]
	s_cbranch_vccnz .LBB0_463
	v_mov_b32_e32 v2, 0
	s_mov_b32 s57, s8
	s_mov_b32 s26, s10
	s_mov_b64 s[4:5], s[18:19]
	s_mov_b32 s56, s16
	v_mov_b32_e32 v3, v2
	v_mov_b32_e32 v4, v2
	v_mov_b32_e32 v5, v2
	v_mov_b32_e32 v6, v2
	v_mov_b32_e32 v7, v2
	v_mov_b32_e32 v8, v2
	v_mov_b32_e32 v9, v2
	v_mov_b32_e32 v14, v2
	v_mov_b32_e32 v15, v2
	v_mov_b32_e32 v16, v2
	v_mov_b32_e32 v17, v2
	v_mov_b32_e32 v22, v2
	v_mov_b32_e32 v23, v2
	v_mov_b32_e32 v24, v2
	v_mov_b32_e32 v25, v2
	v_mov_b32_e32 v34, v2
	v_mov_b32_e32 v35, v2
	v_mov_b32_e32 v36, v2
	v_mov_b32_e32 v37, v2
	v_mov_b32_e32 v38, v2
	v_mov_b32_e32 v39, v2
	v_mov_b32_e32 v40, v2
	v_mov_b32_e32 v41, v2
	v_mov_b32_e32 v50, v2
	v_mov_b32_e32 v51, v2
	v_mov_b32_e32 v52, v2
	v_mov_b32_e32 v53, v2
	v_mov_b32_e32 v54, v2
	v_mov_b32_e32 v55, v2
	v_mov_b32_e32 v56, v2
	v_mov_b32_e32 v57, v2
	v_mov_b32_e32 v10, v2
	v_mov_b32_e32 v11, v2
	v_mov_b32_e32 v12, v2
	v_mov_b32_e32 v13, v2
	v_mov_b32_e32 v18, v2
	v_mov_b32_e32 v19, v2
	v_mov_b32_e32 v20, v2
	v_mov_b32_e32 v21, v2
	v_mov_b32_e32 v26, v2
	v_mov_b32_e32 v27, v2
	v_mov_b32_e32 v28, v2
	v_mov_b32_e32 v29, v2
	v_mov_b32_e32 v30, v2
	v_mov_b32_e32 v31, v2
	v_mov_b32_e32 v32, v2
	v_mov_b32_e32 v33, v2
	v_mov_b32_e32 v42, v2
	v_mov_b32_e32 v43, v2
	v_mov_b32_e32 v44, v2
	v_mov_b32_e32 v45, v2
	v_mov_b32_e32 v46, v2
	v_mov_b32_e32 v47, v2
	v_mov_b32_e32 v48, v2
	v_mov_b32_e32 v49, v2
	v_mov_b32_e32 v58, v2
	v_mov_b32_e32 v59, v2
	v_mov_b32_e32 v60, v2
	v_mov_b32_e32 v61, v2
	v_mov_b32_e32 v62, v2
	v_mov_b32_e32 v63, v2
	v_mov_b32_e32 v64, v2
	v_mov_b32_e32 v65, v2
	v_mov_b32_e32 v66, v2
	v_mov_b32_e32 v67, v2
	v_mov_b32_e32 v68, v2
	v_mov_b32_e32 v69, v2
	v_mov_b32_e32 v70, v2
	v_mov_b32_e32 v71, v2
	v_mov_b32_e32 v72, v2
	v_mov_b32_e32 v73, v2
	v_mov_b32_e32 v82, v2
	v_mov_b32_e32 v83, v2
	v_mov_b32_e32 v84, v2
	v_mov_b32_e32 v85, v2
	v_mov_b32_e32 v86, v2
	v_mov_b32_e32 v87, v2
	v_mov_b32_e32 v88, v2
	v_mov_b32_e32 v89, v2
	v_mov_b32_e32 v98, v2
	v_mov_b32_e32 v99, v2
	v_mov_b32_e32 v100, v2
	v_mov_b32_e32 v101, v2
	v_mov_b32_e32 v102, v2
	v_mov_b32_e32 v103, v2
	v_mov_b32_e32 v104, v2
	v_mov_b32_e32 v105, v2
	v_mov_b32_e32 v114, v2
	v_mov_b32_e32 v115, v2
	v_mov_b32_e32 v116, v2
	v_mov_b32_e32 v117, v2
	v_mov_b32_e32 v118, v2
	v_mov_b32_e32 v119, v2
	v_mov_b32_e32 v120, v2
	v_mov_b32_e32 v121, v2
	v_mov_b32_e32 v74, v2
	v_mov_b32_e32 v75, v2
	v_mov_b32_e32 v76, v2
	v_mov_b32_e32 v77, v2
	v_mov_b32_e32 v78, v2
	v_mov_b32_e32 v79, v2
	v_mov_b32_e32 v80, v2
	v_mov_b32_e32 v81, v2
	v_mov_b32_e32 v90, v2
	v_mov_b32_e32 v91, v2
	v_mov_b32_e32 v92, v2
	v_mov_b32_e32 v93, v2
	v_mov_b32_e32 v94, v2
	v_mov_b32_e32 v95, v2
	v_mov_b32_e32 v96, v2
	v_mov_b32_e32 v97, v2
	v_mov_b32_e32 v106, v2
	v_mov_b32_e32 v107, v2
	v_mov_b32_e32 v108, v2
	v_mov_b32_e32 v109, v2
	v_mov_b32_e32 v110, v2
	v_mov_b32_e32 v111, v2
	v_mov_b32_e32 v112, v2
	v_mov_b32_e32 v113, v2
	v_mov_b32_e32 v122, v2
	v_mov_b32_e32 v123, v2
	v_mov_b32_e32 v124, v2
	v_mov_b32_e32 v125, v2
	v_mov_b32_e32 v126, v2
	v_mov_b32_e32 v127, v2
	v_mov_b32_e32 v128, v2
	v_mov_b32_e32 v129, v2
	s_andn2_b64 vcc, exec, s[40:41]
	s_cbranch_vccnz .LBB0_464

; #define PG8_STAGE(bufoff, gbase, voff) do { _Pragma("unroll") for (int _i = 0; _i < 2; ++_i) \
;         __builtin_amdgcn_global_load_lds((const unsigned*)((const char*)(gbase) + (voff)[_i]), (LAS unsigned*)(lds + (bufoff) + ldsw + _i * 8192), 16, 0, 0); } while (0)
; #define PG8_LDA(dst, b, h) do { _Pragma("unroll") for (int m = 0; m < 4; ++m) _Pragma("unroll") for (int k = 0; k < 2; ++k) dst[m][k] = *(const LAS bf16x8*)(lds + PG8_SA(b, h) + aoff + m * 2048 + k * 1024); } while (0)
; #define PG8_LDB(dst, b, h) do { _Pragma("unroll") for (int n = 0; n < 2; ++n) _Pragma("unroll") for (int k = 0; k < 2; ++k) dst[n][k] = *(const LAS bf16x8*)(lds + PG8_SB(b, h) + boff + n * 2048 + k * 1024); } while (0)
; #define PG8_MMA(ai, bj, At, Bt) do { __builtin_amdgcn_s_setprio(1); _Pragma("unroll") for (int m = 0; m < 4; ++m) _Pragma("unroll") for (int n = 0; n < 2; ++n) _Pragma("unroll") for (int k = 0; k < 2; ++k) \
;         acc[ai][bj][m][n] = __builtin_amdgcn_mfma_f32_16x16x32_bf16(Bt[n][k], At[m][k], acc[ai][bj][m][n], 0, 0, 0); __builtin_amdgcn_s_setprio(0); } while (0)
; #define PG8_WAIT_V(n) asm volatile("s_waitcnt vmcnt(" #n ")" ::: "memory")
; #define PG8_WAIT_L(n) asm volatile("s_waitcnt lgkmcnt(" #n ")" ::: "memory")
; #define PG8_BAR __builtin_amdgcn_s_barrier()
; #define PG8_SCHED __builtin_amdgcn_sched_barrier(0)
; template <class Epi>
; __device__ __forceinline__ void gemm_phase(LAS unsigned char* lds, const Gemm g, const StaticOrder& S, const Epi& E) {
;     ...
;             PG8_LDB(B0, 0, 0); PG8_SCHED; PG8_LDA(At, 0, 0); PG8_STAGE(PG8_SA(1, 1), a1 + hstepA, voffA);
;             PG8_WAIT_L(8); PG8_BAR; PG8_WAIT_L(0); PG8_MMA(0, 0, At, B0); PG8_BAR; PG8_SCHED;
;             PG8_LDB(B1, 0, 1); PG8_STAGE(PG8_SB(0, 0), b2, voffB);
;             PG8_BAR; PG8_WAIT_L(0); PG8_MMA(0, 1, At, B1); PG8_BAR;
;             PG8_LDA(At, 0, 1); PG8_STAGE(PG8_SA(0, 0), a2, voffA);
;             PG8_BAR; PG8_WAIT_L(0); PG8_MMA(1, 0, At, B0); PG8_BAR; PG8_SCHED;
;             PG8_STAGE(PG8_SB(0, 1), b2 + hstepB, voffB);
;             PG8_WAIT_V(6); PG8_BAR; PG8_MMA(1, 1, At, B1); PG8_BAR;
.LBB0_603:
	s_add_u32 s8, s0, 0x100
	s_addc_u32 s9, s1, 0
	s_add_i32 s60, 0, 0x10000
	v_add_u32_e32 v102, s60, v229
	ds_read_b128 v[34:37], v102
	ds_read_b128 v[38:41], v102 offset:1024
	ds_read_b128 v[98:101], v102 offset:2048
	ds_read_b128 v[102:105], v102 offset:3072
	s_cmp_eq_u32 s59, 12
	s_cselect_b32 s11, s35, s9
	s_cselect_b32 s10, s36, s8
	s_cselect_b32 s5, s37, s58
	s_cselect_b32 s4, s51, s53
	s_add_i32 m0, s20, 0xc000
	ds_read_b128 v[106:109], v231
	ds_read_b128 v[118:121], v231 offset:1024
	ds_read_b128 v[130:133], v231 offset:2048
	ds_read_b128 v[142:145], v231 offset:3072
	ds_read_b128 v[154:157], v231 offset:4096
	ds_read_b128 v[158:161], v231 offset:5120
	ds_read_b128 v[170:173], v231 offset:6144
	ds_read_b128 v[174:177], v231 offset:7168
	global_load_lds_dwordx4 v194, s[0:1]
	s_add_i32 m0, s20, 0xe000
	s_nop 0
	global_load_lds_dwordx4 v196, s[0:1]
	s_waitcnt lgkmcnt(8)
	s_barrier
	s_waitcnt lgkmcnt(0)
	v_mfma_f32_16x16x32_bf16 v[166:169], v[34:37], v[106:109], v[166:169]
	v_mfma_f32_16x16x32_bf16 v[162:165], v[98:101], v[106:109], v[162:165]
	v_mfma_f32_16x16x32_bf16 v[150:153], v[34:37], v[130:133], v[150:153]
	v_mfma_f32_16x16x32_bf16 v[146:149], v[98:101], v[130:133], v[146:149]
	v_mfma_f32_16x16x32_bf16 v[138:141], v[34:37], v[154:157], v[138:141]
	v_mfma_f32_16x16x32_bf16 v[134:137], v[98:101], v[154:157], v[134:137]
	v_mfma_f32_16x16x32_bf16 v[126:129], v[34:37], v[170:173], v[126:129]
	v_mfma_f32_16x16x32_bf16 v[122:125], v[98:101], v[170:173], v[122:125]
	v_mfma_f32_16x16x32_bf16 v[166:169], v[38:41], v[118:121], v[166:169]
	v_mfma_f32_16x16x32_bf16 v[162:165], v[102:105], v[118:121], v[162:165]
	v_mfma_f32_16x16x32_bf16 v[150:153], v[38:41], v[142:145], v[150:153]
	v_mfma_f32_16x16x32_bf16 v[146:149], v[102:105], v[142:145], v[146:149]
	v_mfma_f32_16x16x32_bf16 v[138:141], v[38:41], v[158:161], v[138:141]
	v_mfma_f32_16x16x32_bf16 v[134:137], v[102:105], v[158:161], v[134:137]
	v_mfma_f32_16x16x32_bf16 v[126:129], v[38:41], v[174:177], v[126:129]
	v_mfma_f32_16x16x32_bf16 v[122:125], v[102:105], v[174:177], v[122:125]
	s_barrier
	s_add_i32 s61, 0, 0x14000
	v_add_u32_e32 v184, s61, v229
	s_add_i32 s0, s60, s19
	ds_read_b128 v[198:201], v184
	ds_read_b128 v[202:205], v184 offset:1024
	ds_read_b128 v[206:209], v184 offset:2048
	ds_read_b128 v[210:213], v184 offset:3072
	s_add_u32 s100, s4, s6
	s_addc_u32 s101, s5, s7
	s_mov_b32 m0, s0
	s_nop 0
	global_load_lds_dwordx4 v0, s[4:5]
	s_add_i32 m0, s0, 0x2000
	s_nop 0
	global_load_lds_dwordx4 v188, s[4:5]
	s_barrier
	s_waitcnt lgkmcnt(0)
	v_mfma_f32_16x16x32_bf16 v[70:73], v[198:201], v[106:109], v[70:73]
	v_mfma_f32_16x16x32_bf16 v[66:69], v[206:209], v[106:109], v[66:69]
	v_mfma_f32_16x16x32_bf16 v[62:65], v[198:201], v[130:133], v[62:65]
	v_mfma_f32_16x16x32_bf16 v[58:61], v[206:209], v[130:133], v[58:61]
	v_mfma_f32_16x16x32_bf16 v[54:57], v[198:201], v[154:157], v[54:57]
	v_mfma_f32_16x16x32_bf16 v[50:53], v[206:209], v[154:157], v[50:53]
	v_mfma_f32_16x16x32_bf16 v[46:49], v[198:201], v[170:173], v[46:49]
	v_mfma_f32_16x16x32_bf16 v[42:45], v[206:209], v[170:173], v[42:45]
	v_mfma_f32_16x16x32_bf16 v[70:73], v[202:205], v[118:121], v[70:73]
	v_mfma_f32_16x16x32_bf16 v[66:69], v[210:213], v[118:121], v[66:69]
	v_mfma_f32_16x16x32_bf16 v[62:65], v[202:205], v[142:145], v[62:65]
	v_mfma_f32_16x16x32_bf16 v[58:61], v[210:213], v[142:145], v[58:61]
	v_mfma_f32_16x16x32_bf16 v[54:57], v[202:205], v[158:161], v[54:57]
	v_mfma_f32_16x16x32_bf16 v[50:53], v[210:213], v[158:161], v[50:53]
	v_mfma_f32_16x16x32_bf16 v[46:49], v[202:205], v[174:177], v[46:49]
	v_mfma_f32_16x16x32_bf16 v[42:45], v[210:213], v[174:177], v[42:45]
	s_mov_b32 m0, s20
	s_add_u32 vcc_lo, s10, s6
	s_addc_u32 vcc_hi, s11, s7
	s_barrier
	ds_read_b128 v[106:109], v231 offset:16384
	ds_read_b128 v[118:121], v231 offset:17408
	ds_read_b128 v[130:133], v231 offset:18432
	ds_read_b128 v[142:145], v231 offset:19456
	ds_read_b128 v[154:157], v231 offset:20480
	ds_read_b128 v[158:161], v231 offset:21504
	ds_read_b128 v[170:173], v231 offset:22528
	ds_read_b128 v[174:177], v231 offset:23552
	global_load_lds_dwordx4 v192, s[10:11]
	s_mov_b32 m0, s21
	s_nop 0
	global_load_lds_dwordx4 v190, s[10:11]
	s_barrier
	s_waitcnt lgkmcnt(0)
	v_mfma_f32_16x16x32_bf16 v[114:117], v[34:37], v[106:109], v[114:117]
	v_mfma_f32_16x16x32_bf16 v[110:113], v[98:101], v[106:109], v[110:113]
	v_mfma_f32_16x16x32_bf16 v[94:97], v[34:37], v[130:133], v[94:97]
	v_mfma_f32_16x16x32_bf16 v[90:93], v[98:101], v[130:133], v[90:93]
	v_mfma_f32_16x16x32_bf16 v[86:89], v[34:37], v[154:157], v[86:89]
	v_mfma_f32_16x16x32_bf16 v[82:85], v[98:101], v[154:157], v[82:85]
	v_mfma_f32_16x16x32_bf16 v[34:37], v[34:37], v[170:173], v[78:81]
	v_mfma_f32_16x16x32_bf16 v[114:117], v[38:41], v[118:121], v[114:117]
	v_mfma_f32_16x16x32_bf16 v[110:113], v[102:105], v[118:121], v[110:113]
	v_mfma_f32_16x16x32_bf16 v[94:97], v[38:41], v[142:145], v[94:97]
	v_mfma_f32_16x16x32_bf16 v[90:93], v[102:105], v[142:145], v[90:93]
	v_mfma_f32_16x16x32_bf16 v[86:89], v[38:41], v[158:161], v[86:89]
	v_mfma_f32_16x16x32_bf16 v[82:85], v[102:105], v[158:161], v[82:85]
	v_mfma_f32_16x16x32_bf16 v[34:37], v[38:41], v[174:177], v[34:37]
	v_mfma_f32_16x16x32_bf16 v[38:41], v[98:101], v[170:173], v[74:77]
	v_mfma_f32_16x16x32_bf16 v[38:41], v[102:105], v[174:177], v[38:41]
	s_barrier
	s_add_u32 s0, s4, 0x40000
	s_addc_u32 s1, s5, 0
	s_add_i32 s60, s61, s19
	s_mov_b32 m0, s60
	s_nop 0
	global_load_lds_dwordx4 v0, s[0:1]
	s_add_i32 m0, s60, 0x2000
	s_nop 0
	global_load_lds_dwordx4 v188, s[0:1]
	s_waitcnt vmcnt(6)
	s_barrier
; #define PG8_STAGE(bufoff, gbase, voff) do { _Pragma("unroll") for (int _i = 0; _i < 2; ++_i) \
;         __builtin_amdgcn_global_load_lds((const unsigned*)((const char*)(gbase) + (voff)[_i]), (LAS unsigned*)(lds + (bufoff) + ldsw + _i * 8192), 16, 0, 0); } while (0)
; #define PG8_LDA(dst, b, h) do { _Pragma("unroll") for (int m = 0; m < 4; ++m) _Pragma("unroll") for (int k = 0; k < 2; ++k) dst[m][k] = *(const LAS bf16x8*)(lds + PG8_SA(b, h) + aoff + m * 2048 + k * 1024); } while (0)
; #define PG8_LDB(dst, b, h) do { _Pragma("unroll") for (int n = 0; n < 2; ++n) _Pragma("unroll") for (int k = 0; k < 2; ++k) dst[n][k] = *(const LAS bf16x8*)(lds + PG8_SB(b, h) + boff + n * 2048 + k * 1024); } while (0)
; #define PG8_MMA(ai, bj, At, Bt) do { __builtin_amdgcn_s_setprio(1); _Pragma("unroll") for (int m = 0; m < 4; ++m) _Pragma("unroll") for (int n = 0; n < 2; ++n) _Pragma("unroll") for (int k = 0; k < 2; ++k) \
;         acc[ai][bj][m][n] = __builtin_amdgcn_mfma_f32_16x16x32_bf16(Bt[n][k], At[m][k], acc[ai][bj][m][n], 0, 0, 0); __builtin_amdgcn_s_setprio(0); } while (0)
; #define PG8_WAIT_V(n) asm volatile("s_waitcnt vmcnt(" #n ")" ::: "memory")
; #define PG8_WAIT_L(n) asm volatile("s_waitcnt lgkmcnt(" #n ")" ::: "memory")
; #define PG8_BAR __builtin_amdgcn_s_barrier()
; #define PG8_SCHED __builtin_amdgcn_sched_barrier(0)
; template <class Epi>
; __device__ __forceinline__ void gemm_phase(LAS unsigned char* lds, const Gemm g, const StaticOrder& S, const Epi& E) {
;     ...
;             PG8_WAIT_V(6); PG8_BAR; PG8_MMA(1, 1, At, B1); PG8_BAR;
;             PG8_LDB(B0, 1, 0); PG8_SCHED; PG8_LDA(At, 1, 0); PG8_STAGE(PG8_SA(0, 1), a2 + hstepA, voffA);
;             PG8_WAIT_L(8); PG8_BAR; PG8_WAIT_L(0); PG8_MMA(0, 0, At, B0); PG8_BAR; PG8_SCHED;
;             PG8_LDB(B1, 1, 1); PG8_STAGE(PG8_SB(1, 0), b3, voffB);
;             PG8_BAR; PG8_WAIT_L(0); PG8_MMA(0, 1, At, B1); PG8_BAR;
;             PG8_LDA(At, 1, 1); PG8_STAGE(PG8_SA(1, 0), a3, voffA);
;             PG8_BAR; PG8_WAIT_L(0); PG8_MMA(1, 0, At, B0); PG8_BAR; PG8_SCHED;
	v_mfma_f32_16x16x32_bf16 v[30:33], v[198:201], v[106:109], v[30:33]
	v_mfma_f32_16x16x32_bf16 v[26:29], v[206:209], v[106:109], v[26:29]
	v_mfma_f32_16x16x32_bf16 v[22:25], v[198:201], v[130:133], v[22:25]
	v_mfma_f32_16x16x32_bf16 v[18:21], v[206:209], v[130:133], v[18:21]
	v_mfma_f32_16x16x32_bf16 v[14:17], v[198:201], v[154:157], v[14:17]
	v_mfma_f32_16x16x32_bf16 v[10:13], v[206:209], v[154:157], v[10:13]
	v_mfma_f32_16x16x32_bf16 v[6:9], v[198:201], v[170:173], v[6:9]
	v_mfma_f32_16x16x32_bf16 v[2:5], v[206:209], v[170:173], v[2:5]
	v_mfma_f32_16x16x32_bf16 v[30:33], v[202:205], v[118:121], v[30:33]
	v_mfma_f32_16x16x32_bf16 v[26:29], v[210:213], v[118:121], v[26:29]
	v_mfma_f32_16x16x32_bf16 v[22:25], v[202:205], v[142:145], v[22:25]
	v_mfma_f32_16x16x32_bf16 v[18:21], v[210:213], v[142:145], v[18:21]
	v_mfma_f32_16x16x32_bf16 v[14:17], v[202:205], v[158:161], v[14:17]
	v_mfma_f32_16x16x32_bf16 v[10:13], v[210:213], v[158:161], v[10:13]
	v_mfma_f32_16x16x32_bf16 v[6:9], v[202:205], v[174:177], v[6:9]
	v_mfma_f32_16x16x32_bf16 v[2:5], v[210:213], v[174:177], v[2:5]
	s_add_i32 s60, 0, 0x18000
	v_add_u32_e32 v102, s60, v229
	s_barrier
	ds_read_b128 v[74:77], v102
	ds_read_b128 v[78:81], v102 offset:1024
	ds_read_b128 v[98:101], v102 offset:2048
	ds_read_b128 v[102:105], v102 offset:3072
	s_add_u32 s0, s10, 0x100000
	s_addc_u32 s1, s11, 0
	s_mov_b32 m0, s22
	ds_read_b128 v[106:109], v231 offset:32768
	ds_read_b128 v[118:121], v231 offset:33792
	ds_read_b128 v[130:133], v231 offset:34816
	ds_read_b128 v[142:145], v231 offset:35840
	ds_read_b128 v[154:157], v231 offset:36864
	ds_read_b128 v[158:161], v231 offset:37888
	ds_read_b128 v[170:173], v231 offset:38912
	ds_read_b128 v[174:177], v231 offset:39936
	global_load_lds_dwordx4 v192, s[0:1]
	s_mov_b32 m0, s23
	s_nop 0
	global_load_lds_dwordx4 v190, s[0:1]
	s_waitcnt lgkmcnt(8)
	s_barrier
	s_waitcnt lgkmcnt(0)
	v_mfma_f32_16x16x32_bf16 v[166:169], v[74:77], v[106:109], v[166:169]
	v_mfma_f32_16x16x32_bf16 v[162:165], v[98:101], v[106:109], v[162:165]
	v_mfma_f32_16x16x32_bf16 v[150:153], v[74:77], v[130:133], v[150:153]
	v_mfma_f32_16x16x32_bf16 v[146:149], v[98:101], v[130:133], v[146:149]
	v_mfma_f32_16x16x32_bf16 v[138:141], v[74:77], v[154:157], v[138:141]
	v_mfma_f32_16x16x32_bf16 v[134:137], v[98:101], v[154:157], v[134:137]
	v_mfma_f32_16x16x32_bf16 v[126:129], v[74:77], v[170:173], v[126:129]
	v_mfma_f32_16x16x32_bf16 v[122:125], v[98:101], v[170:173], v[122:125]
	v_mfma_f32_16x16x32_bf16 v[166:169], v[78:81], v[118:121], v[166:169]
	v_mfma_f32_16x16x32_bf16 v[162:165], v[102:105], v[118:121], v[162:165]
	v_mfma_f32_16x16x32_bf16 v[150:153], v[78:81], v[142:145], v[150:153]
	v_mfma_f32_16x16x32_bf16 v[146:149], v[102:105], v[142:145], v[146:149]
	v_mfma_f32_16x16x32_bf16 v[138:141], v[78:81], v[158:161], v[138:141]
	v_mfma_f32_16x16x32_bf16 v[134:137], v[102:105], v[158:161], v[134:137]
	v_mfma_f32_16x16x32_bf16 v[126:129], v[78:81], v[174:177], v[126:129]
	v_mfma_f32_16x16x32_bf16 v[122:125], v[102:105], v[174:177], v[122:125]
	s_barrier
	s_add_i32 s10, 0, 0x1c000
	s_add_i32 s0, s60, s19
	v_add_u32_e32 v210, s10, v229
	s_mov_b32 m0, s0
	ds_read_b128 v[198:201], v210
	ds_read_b128 v[202:205], v210 offset:1024
	ds_read_b128 v[206:209], v210 offset:2048
	ds_read_b128 v[210:213], v210 offset:3072
	global_load_lds_dwordx4 v0, s[100:101]
	s_add_i32 m0, s0, 0x2000
	s_nop 0
	global_load_lds_dwordx4 v188, s[100:101]
	s_barrier
	s_waitcnt lgkmcnt(0)
	v_mfma_f32_16x16x32_bf16 v[70:73], v[198:201], v[106:109], v[70:73]
	v_mfma_f32_16x16x32_bf16 v[66:69], v[206:209], v[106:109], v[66:69]
	v_mfma_f32_16x16x32_bf16 v[62:65], v[198:201], v[130:133], v[62:65]
	v_mfma_f32_16x16x32_bf16 v[58:61], v[206:209], v[130:133], v[58:61]
	v_mfma_f32_16x16x32_bf16 v[54:57], v[198:201], v[154:157], v[54:57]
	v_mfma_f32_16x16x32_bf16 v[50:53], v[206:209], v[154:157], v[50:53]
	v_mfma_f32_16x16x32_bf16 v[46:49], v[198:201], v[170:173], v[46:49]
	v_mfma_f32_16x16x32_bf16 v[42:45], v[206:209], v[170:173], v[42:45]
	v_mfma_f32_16x16x32_bf16 v[70:73], v[202:205], v[118:121], v[70:73]
	v_mfma_f32_16x16x32_bf16 v[66:69], v[210:213], v[118:121], v[66:69]
	v_mfma_f32_16x16x32_bf16 v[62:65], v[202:205], v[142:145], v[62:65]
	v_mfma_f32_16x16x32_bf16 v[58:61], v[210:213], v[142:145], v[58:61]
	v_mfma_f32_16x16x32_bf16 v[54:57], v[202:205], v[158:161], v[54:57]
	v_mfma_f32_16x16x32_bf16 v[50:53], v[210:213], v[158:161], v[50:53]
	v_mfma_f32_16x16x32_bf16 v[46:49], v[202:205], v[174:177], v[46:49]
	v_mfma_f32_16x16x32_bf16 v[42:45], v[210:213], v[174:177], v[42:45]
	s_mov_b32 m0, s24
	s_barrier
	ds_read_b128 v[106:109], v231 offset:49152
	ds_read_b128 v[118:121], v231 offset:50176
	ds_read_b128 v[130:133], v231 offset:51200
	ds_read_b128 v[142:145], v231 offset:52224
	ds_read_b128 v[154:157], v231 offset:53248
	ds_read_b128 v[158:161], v231 offset:54272
	ds_read_b128 v[170:173], v231 offset:55296
	ds_read_b128 v[174:177], v231 offset:56320
	global_load_lds_dwordx4 v192, vcc
	s_mov_b32 m0, s25
	s_nop 0
	global_load_lds_dwordx4 v190, vcc
	s_barrier
	s_waitcnt lgkmcnt(0)
	v_mfma_f32_16x16x32_bf16 v[114:117], v[74:77], v[106:109], v[114:117]
	v_mfma_f32_16x16x32_bf16 v[94:97], v[74:77], v[130:133], v[94:97]
	v_mfma_f32_16x16x32_bf16 v[86:89], v[74:77], v[154:157], v[86:89]
	v_mfma_f32_16x16x32_bf16 v[34:37], v[74:77], v[170:173], v[34:37]
	v_mfma_f32_16x16x32_bf16 v[114:117], v[78:81], v[118:121], v[114:117]
	v_mfma_f32_16x16x32_bf16 v[110:113], v[98:101], v[106:109], v[110:113]
	v_mfma_f32_16x16x32_bf16 v[94:97], v[78:81], v[142:145], v[94:97]
	v_mfma_f32_16x16x32_bf16 v[90:93], v[98:101], v[130:133], v[90:93]
	v_mfma_f32_16x16x32_bf16 v[86:89], v[78:81], v[158:161], v[86:89]
	v_mfma_f32_16x16x32_bf16 v[82:85], v[98:101], v[154:157], v[82:85]
	v_mfma_f32_16x16x32_bf16 v[78:81], v[78:81], v[174:177], v[34:37]
	v_mfma_f32_16x16x32_bf16 v[34:37], v[98:101], v[170:173], v[38:41]
	v_mfma_f32_16x16x32_bf16 v[110:113], v[102:105], v[118:121], v[110:113]
	v_mfma_f32_16x16x32_bf16 v[90:93], v[102:105], v[142:145], v[90:93]
	v_mfma_f32_16x16x32_bf16 v[82:85], v[102:105], v[158:161], v[82:85]
	v_mfma_f32_16x16x32_bf16 v[74:77], v[102:105], v[174:177], v[34:37]
	s_barrier
; __device__ __forceinline__ unsigned cvt_pk_bf16(float lo, float hi) { unsigned r; asm volatile("v_cvt_pk_bf16_f32 %0, %1, %2" : "=v"(r) : "v"(lo), "v"(hi)); return r; }
; __device__ __forceinline__ float bf_lo(unsigned w) { return __uint_as_float(w << 16); }
; __device__ __forceinline__ float bf_hi(unsigned w) { return __uint_as_float(w & 0xffff0000u); }
; __device__ __forceinline__ float silu_f(float z) { return z * fast_rcp(1.0f + __builtin_amdgcn_exp2f(z * -1.44269504f)); }
; #define PG8_STAGE(bufoff, gbase, voff) do { _Pragma("unroll") for (int _i = 0; _i < 2; ++_i) \
;         __builtin_amdgcn_global_load_lds((const unsigned*)((const char*)(gbase) + (voff)[_i]), (LAS unsigned*)(lds + (bufoff) + ldsw + _i * 8192), 16, 0, 0); } while (0)
; #define PG8_WAIT_V(n) asm volatile("s_waitcnt vmcnt(" #n ")" ::: "memory")
; #define PG8_BAR __builtin_amdgcn_s_barrier()
; template <class Epi>
; __device__ __forceinline__ void gemm_phase(LAS unsigned char* lds, const Gemm g, const StaticOrder& S, const Epi& E) {
;     ...
;             PG8_STAGE(PG8_SB(1, 1), b3 + hstepB, voffB);
;             PG8_WAIT_V(6); PG8_BAR; PG8_MMA(1, 1, At, B1); PG8_BAR;
;     __device__ __forceinline__ void operator()(const f32x4 (&acc)[2][2][4][2], const Unit& u, int wr, int wc, int fr, int fq, const Pre&) const {
;         const int row0 = u.pm * BM + wr * 64 + fr, col0 = u.pn * BM + wc * 32 + 8 * fq;
;         f32x4 sc[2][2];
; #pragma unroll
;         for (int bj = 0; bj < 2; ++bj) { sc[bj][0] = *(const f32x4*)(scale + col0 + bj * HALF); sc[bj][1] = *(const f32x4*)(scale + col0 + bj * HALF + 4); }
; #pragma unroll
;         for (int bj = 0; bj < 2; ++bj) { const int c = col0 + bj * HALF;
;             u32x4 zv[8];
; #pragma unroll
;             for (int g8 = 0; g8 < 8; ++g8) zv[g8] = *(const u32x4*)(Z + (size_t)(row0 + (g8 >> 2) * HALF + (g8 & 3) * 16) * DE2 + c);
; #pragma unroll
;             for (int ai = 0; ai < 2; ++ai)
; #pragma unroll
;                 for (int m = 0; m < 4; ++m) { const int r = row0 + ai * HALF + m * 16;
;                     const u32x4 zw = zv[ai * 4 + m];
;                     const f32x4 a0 = acc[ai][bj][m][0] * sc[bj][0], a1 = acc[ai][bj][m][1] * sc[bj][1];
;                     u32x4 w;
;                     w.x = cvt_pk_bf16(a0[0] * silu_f(bf_lo(zw.x)), a0[1] * silu_f(bf_hi(zw.x)));
	s_add_u32 s0, s4, 0x40080
	s_addc_u32 s1, s5, 0
	s_add_i32 s4, s10, s19
	s_mov_b32 m0, s4
	s_nop 0
	global_load_lds_dwordx4 v0, s[0:1]
	s_add_i32 m0, s4, 0x2000
	s_nop 0
	global_load_lds_dwordx4 v188, s[0:1]
	s_waitcnt vmcnt(6)
	s_barrier
	v_mfma_f32_16x16x32_bf16 v[30:33], v[198:201], v[106:109], v[30:33]
	v_mfma_f32_16x16x32_bf16 v[26:29], v[206:209], v[106:109], v[26:29]
	v_mfma_f32_16x16x32_bf16 v[22:25], v[198:201], v[130:133], v[22:25]
	v_mfma_f32_16x16x32_bf16 v[18:21], v[206:209], v[130:133], v[18:21]
	v_mfma_f32_16x16x32_bf16 v[14:17], v[198:201], v[154:157], v[14:17]
	v_mfma_f32_16x16x32_bf16 v[10:13], v[206:209], v[154:157], v[10:13]
	v_mfma_f32_16x16x32_bf16 v[6:9], v[198:201], v[170:173], v[6:9]
	v_mfma_f32_16x16x32_bf16 v[2:5], v[206:209], v[170:173], v[2:5]
	v_mfma_f32_16x16x32_bf16 v[30:33], v[202:205], v[118:121], v[30:33]
	v_mfma_f32_16x16x32_bf16 v[26:29], v[210:213], v[118:121], v[26:29]
	v_mfma_f32_16x16x32_bf16 v[22:25], v[202:205], v[142:145], v[22:25]
	v_mfma_f32_16x16x32_bf16 v[18:21], v[210:213], v[142:145], v[18:21]
	v_mfma_f32_16x16x32_bf16 v[14:17], v[202:205], v[158:161], v[14:17]
	v_mfma_f32_16x16x32_bf16 v[10:13], v[210:213], v[158:161], v[10:13]
	v_mfma_f32_16x16x32_bf16 v[6:9], v[202:205], v[174:177], v[6:9]
	v_mfma_f32_16x16x32_bf16 v[2:5], v[210:213], v[174:177], v[2:5]
	s_add_i32 s59, s59, 2
	s_add_u32 s53, s53, 0x100
	s_addc_u32 s58, s58, 0
	s_cmp_gt_u32 s59, 13
	s_mov_b64 s[0:1], s[8:9]
	s_barrier
	s_cbranch_scc0 .LBB0_603
	v_lshl_or_b32 v200, s34, 8, v230
	v_ashrrev_i32_e32 v201, 31, v200
	v_lshl_add_u32 v226, s27, 8, v228
	v_lshlrev_b64 v[216:217], 1, v[200:201]
	v_ashrrev_i32_e32 v227, 31, v226
	v_lshl_add_u64 v[106:107], s[46:47], 0, v[216:217]
	v_lshlrev_b64 v[204:205], 14, v[226:227]
	v_lshl_add_u64 v[38:39], v[200:201], 2, s[48:49]
	v_lshl_add_u64 v[108:109], v[106:107], 0, v[204:205]
	global_load_dwordx4 v[98:101], v[38:39], off offset:16
	global_load_dwordx4 v[102:105], v[38:39], off
	global_load_dwordx4 v[34:37], v[38:39], off offset:528
	s_nop 0
	global_load_dwordx4 v[38:41], v[38:39], off offset:512
	v_or_b32_e32 v224, 16, v226
	global_load_dwordx4 v[174:177], v[108:109], off
	v_ashrrev_i32_e32 v225, 31, v224
	v_or_b32_e32 v222, 32, v226
	v_lshlrev_b64 v[198:199], 14, v[224:225]
	v_ashrrev_i32_e32 v223, 31, v222
	v_or_b32_e32 v220, 48, v226
	v_lshl_add_u64 v[108:109], v[106:107], 0, v[198:199]
	v_lshlrev_b64 v[202:203], 14, v[222:223]
	v_ashrrev_i32_e32 v221, 31, v220
	v_add_u32_e32 v218, 0x80, v226
	global_load_dwordx4 v[170:173], v[108:109], off
	v_lshl_add_u64 v[108:109], v[106:107], 0, v[202:203]
	v_lshlrev_b64 v[206:207], 14, v[220:221]
	v_ashrrev_i32_e32 v219, 31, v218
	global_load_dwordx4 v[158:161], v[108:109], off
	v_lshl_add_u64 v[108:109], v[106:107], 0, v[206:207]
	v_lshlrev_b64 v[208:209], 14, v[218:219]
	global_load_dwordx4 v[154:157], v[108:109], off
	v_lshl_add_u64 v[108:109], v[106:107], 0, v[208:209]
	global_load_dwordx4 v[142:145], v[108:109], off
	v_add_u32_e32 v108, 0x90, v226
	v_ashrrev_i32_e32 v109, 31, v108
	v_lshlrev_b64 v[210:211], 14, v[108:109]
	v_lshl_add_u64 v[108:109], v[106:107], 0, v[210:211]
	global_load_dwordx4 v[130:133], v[108:109], off
	v_add_u32_e32 v108, 0xa0, v226
	v_ashrrev_i32_e32 v109, 31, v108
	v_lshlrev_b64 v[212:213], 14, v[108:109]
	v_lshl_add_u64 v[108:109], v[106:107], 0, v[212:213]
	global_load_dwordx4 v[118:121], v[108:109], off
	v_add_u32_e32 v108, 0xb0, v226
	v_ashrrev_i32_e32 v109, 31, v108
	v_lshlrev_b64 v[214:215], 14, v[108:109]
	v_lshl_add_u64 v[106:107], v[106:107], 0, v[214:215]
	global_load_dwordx4 v[106:109], v[106:107], off
	s_mov_b64 s[0:1], 0x120000
	s_mov_b32 s27, s52
	s_mov_b32 s34, s50
	s_mov_b64 s[8:9], s[56:57]
	s_waitcnt vmcnt(0)
	v_pk_mul_f32 v[146:147], v[146:147], v[98:99]
	v_pk_mul_f32 v[184:185], v[166:167], v[102:103]
	v_pk_mul_f32 v[166:167], v[164:165], v[100:101]
	v_pk_mul_f32 v[164:165], v[162:163], v[98:99]
	v_pk_mul_f32 v[168:169], v[168:169], v[104:105]
	v_lshlrev_b32_e32 v162, 16, v174
	v_mul_f32_e32 v163, 0xbfb8aa3b, v162
	v_exp_f32_e32 v163, v163
	v_pk_mul_f32 v[150:151], v[150:151], v[102:103]
	v_pk_mul_f32 v[152:153], v[152:153], v[104:105]
	v_pk_mul_f32 v[148:149], v[148:149], v[100:101]
	v_add_f32_e32 v163, 1.0, v163
	v_rcp_f32_e32 v163, v163
	v_pk_mul_f32 v[138:139], v[138:139], v[102:103]
	v_pk_mul_f32 v[140:141], v[140:141], v[104:105]
	v_pk_mul_f32 v[134:135], v[134:135], v[98:99]
	v_mul_f32_e32 v162, v163, v162
	v_and_b32_e32 v163, 0xffff0000, v174
	v_mul_f32_e32 v174, 0xbfb8aa3b, v163
	v_exp_f32_e32 v174, v174
	v_mul_f32_e32 v162, v184, v162
	v_pk_mul_f32 v[136:137], v[136:137], v[100:101]
	v_pk_mul_f32 v[126:127], v[126:127], v[102:103]
	v_add_f32_e32 v174, 1.0, v174
	v_rcp_f32_e32 v174, v174
	v_pk_mul_f32 v[128:129], v[128:129], v[104:105]
	v_pk_mul_f32 v[122:123], v[122:123], v[98:99]
	v_pk_mul_f32 v[124:125], v[124:125], v[100:101]
	v_mul_f32_e32 v163, v174, v163
	v_mul_f32_e32 v163, v185, v163
	v_cvt_pk_bf16_f32 v162, v162, v163
	v_lshlrev_b32_e32 v163, 16, v175
	v_mul_f32_e32 v174, 0xbfb8aa3b, v163
	v_exp_f32_e32 v174, v174
	v_pk_mul_f32 v[114:115], v[114:115], v[102:103]
	v_pk_mul_f32 v[116:117], v[116:117], v[104:105]
	v_pk_mul_f32 v[110:111], v[110:111], v[98:99]
	v_add_f32_e32 v174, 1.0, v174
	v_rcp_f32_e32 v174, v174
	v_pk_mul_f32 v[112:113], v[112:113], v[100:101]
	v_pk_mul_f32 v[94:95], v[94:95], v[102:103]
	v_pk_mul_f32 v[96:97], v[96:97], v[104:105]
	v_mul_f32_e32 v163, v174, v163
	v_mul_f32_e32 v163, v168, v163
	v_and_b32_e32 v168, 0xffff0000, v175
	v_mul_f32_e32 v174, 0xbfb8aa3b, v168
	v_exp_f32_e32 v174, v174
	v_pk_mul_f32 v[90:91], v[90:91], v[98:99]
; __device__ __forceinline__ unsigned cvt_pk_bf16(float lo, float hi) { unsigned r; asm volatile("v_cvt_pk_bf16_f32 %0, %1, %2" : "=v"(r) : "v"(lo), "v"(hi)); return r; }
; __device__ __forceinline__ float bf_lo(unsigned w) { return __uint_as_float(w << 16); }
; __device__ __forceinline__ float bf_hi(unsigned w) { return __uint_as_float(w & 0xffff0000u); }
; __device__ __forceinline__ float fast_rcp(float x) { return __builtin_amdgcn_rcpf(x); }
; __device__ __forceinline__ float silu_f(float z) { return z * fast_rcp(1.0f + __builtin_amdgcn_exp2f(z * -1.44269504f)); }
;     __device__ __forceinline__ void operator()(const f32x4 (&acc)[2][2][4][2], const Unit& u, int wr, int wc, int fr, int fq, const Pre&) const {
;     ...
;             for (int ai = 0; ai < 2; ++ai)
; #pragma unroll
;                 for (int m = 0; m < 4; ++m) { const int r = row0 + ai * HALF + m * 16;
;                     const u32x4 zw = zv[ai * 4 + m];
;                     const f32x4 a0 = acc[ai][bj][m][0] * sc[bj][0], a1 = acc[ai][bj][m][1] * sc[bj][1];
;                     u32x4 w;
;                     w.x = cvt_pk_bf16(a0[0] * silu_f(bf_lo(zw.x)), a0[1] * silu_f(bf_hi(zw.x)));
;                     w.y = cvt_pk_bf16(a0[2] * silu_f(bf_lo(zw.y)), a0[3] * silu_f(bf_hi(zw.y)));
;                     w.z = cvt_pk_bf16(a1[0] * silu_f(bf_lo(zw.z)), a1[1] * silu_f(bf_hi(zw.z)));
;                     w.w = cvt_pk_bf16(a1[2] * silu_f(bf_lo(zw.w)), a1[3] * silu_f(bf_hi(zw.w)));
;                     *(u32x4*)(O + (size_t)r * DE + c) = w; } }
	v_pk_mul_f32 v[92:93], v[92:93], v[100:101]
	v_pk_mul_f32 v[86:87], v[86:87], v[102:103]
	v_add_f32_e32 v174, 1.0, v174
	v_rcp_f32_e32 v174, v174
	v_pk_mul_f32 v[88:89], v[88:89], v[104:105]
	v_pk_mul_f32 v[82:83], v[82:83], v[98:99]
	v_pk_mul_f32 v[84:85], v[84:85], v[100:101]
	v_mul_f32_e32 v168, v174, v168
	v_mul_f32_e32 v168, v169, v168
	v_cvt_pk_bf16_f32 v163, v163, v168
	v_lshlrev_b32_e32 v168, 16, v176
	v_mul_f32_e32 v169, 0xbfb8aa3b, v168
	v_exp_f32_e32 v169, v169
	v_pk_mul_f32 v[78:79], v[78:79], v[102:103]
	v_pk_mul_f32 v[80:81], v[80:81], v[104:105]
	v_pk_mul_f32 v[74:75], v[74:75], v[98:99]
	v_add_f32_e32 v169, 1.0, v169
	v_rcp_f32_e32 v169, v169
	v_pk_mul_f32 v[76:77], v[76:77], v[100:101]
	v_pk_mul_f32 v[70:71], v[70:71], v[38:39]
	v_pk_mul_f32 v[72:73], v[72:73], v[40:41]
	v_mul_f32_e32 v168, v169, v168
	v_mul_f32_e32 v164, v164, v168
	v_and_b32_e32 v168, 0xffff0000, v176
	v_mul_f32_e32 v169, 0xbfb8aa3b, v168
	v_exp_f32_e32 v169, v169
	v_pk_mul_f32 v[66:67], v[66:67], v[34:35]
	v_pk_mul_f32 v[68:69], v[68:69], v[36:37]
	v_pk_mul_f32 v[62:63], v[62:63], v[38:39]
	v_add_f32_e32 v169, 1.0, v169
	v_rcp_f32_e32 v169, v169
	v_pk_mul_f32 v[64:65], v[64:65], v[40:41]
	v_pk_mul_f32 v[58:59], v[58:59], v[34:35]
	v_pk_mul_f32 v[60:61], v[60:61], v[36:37]
	v_mul_f32_e32 v168, v169, v168
	v_mul_f32_e32 v165, v165, v168
	v_cvt_pk_bf16_f32 v164, v164, v165
	v_lshlrev_b32_e32 v165, 16, v177
	v_mul_f32_e32 v168, 0xbfb8aa3b, v165
	v_exp_f32_e32 v168, v168
	v_pk_mul_f32 v[54:55], v[54:55], v[38:39]
	v_pk_mul_f32 v[56:57], v[56:57], v[40:41]
	v_pk_mul_f32 v[50:51], v[50:51], v[34:35]
	v_add_f32_e32 v168, 1.0, v168
	v_rcp_f32_e32 v168, v168
	v_pk_mul_f32 v[52:53], v[52:53], v[36:37]
	v_pk_mul_f32 v[46:47], v[46:47], v[38:39]
	v_pk_mul_f32 v[48:49], v[48:49], v[40:41]
	v_mul_f32_e32 v165, v168, v165
	v_mul_f32_e32 v165, v166, v165
	v_and_b32_e32 v166, 0xffff0000, v177
	v_mul_f32_e32 v168, 0xbfb8aa3b, v166
	v_exp_f32_e32 v168, v168
	v_pk_mul_f32 v[42:43], v[42:43], v[34:35]
	v_pk_mul_f32 v[44:45], v[44:45], v[36:37]
	v_pk_mul_f32 v[30:31], v[30:31], v[38:39]
	v_add_f32_e32 v168, 1.0, v168
	v_rcp_f32_e32 v168, v168
	v_pk_mul_f32 v[32:33], v[32:33], v[40:41]
	v_pk_mul_f32 v[26:27], v[26:27], v[34:35]
	v_pk_mul_f32 v[28:29], v[28:29], v[36:37]
	v_mul_f32_e32 v166, v168, v166
	v_mul_f32_e32 v166, v167, v166
	v_cvt_pk_bf16_f32 v165, v165, v166
	v_lshlrev_b64 v[166:167], 13, v[226:227]
	v_lshl_add_u64 v[166:167], s[44:45], 0, v[166:167]
	v_lshl_add_u64 v[166:167], v[166:167], 0, v[216:217]
	global_store_dwordx4 v[166:167], v[162:165], off
	v_pk_mul_f32 v[22:23], v[22:23], v[38:39]
	v_pk_mul_f32 v[24:25], v[24:25], v[40:41]
	v_lshlrev_b32_e32 v162, 16, v170
	v_mul_f32_e32 v163, 0xbfb8aa3b, v162
	v_exp_f32_e32 v163, v163
	v_pk_mul_f32 v[18:19], v[18:19], v[34:35]
	v_pk_mul_f32 v[20:21], v[20:21], v[36:37]
	v_pk_mul_f32 v[14:15], v[14:15], v[38:39]
	v_add_f32_e32 v163, 1.0, v163
	v_rcp_f32_e32 v163, v163
	v_pk_mul_f32 v[16:17], v[16:17], v[40:41]
	v_pk_mul_f32 v[10:11], v[10:11], v[34:35]
	v_pk_mul_f32 v[12:13], v[12:13], v[36:37]
	v_mul_f32_e32 v162, v163, v162
	v_mul_f32_e32 v150, v150, v162
	v_and_b32_e32 v162, 0xffff0000, v170
	v_mul_f32_e32 v163, 0xbfb8aa3b, v162
	v_exp_f32_e32 v163, v163
	v_pk_mul_f32 v[6:7], v[6:7], v[38:39]
	v_pk_mul_f32 v[8:9], v[8:9], v[40:41]
	v_pk_mul_f32 v[2:3], v[2:3], v[34:35]
	v_add_f32_e32 v163, 1.0, v163
	v_rcp_f32_e32 v163, v163
	v_pk_mul_f32 v[4:5], v[4:5], v[36:37]
	v_mul_f32_e32 v162, v163, v162
	v_mul_f32_e32 v151, v151, v162
	v_cvt_pk_bf16_f32 v150, v150, v151
	v_lshlrev_b32_e32 v151, 16, v171
	v_mul_f32_e32 v162, 0xbfb8aa3b, v151
	v_exp_f32_e32 v162, v162
	s_nop 0
	v_add_f32_e32 v162, 1.0, v162
	v_rcp_f32_e32 v162, v162
	s_nop 0
	v_mul_f32_e32 v151, v162, v151
	v_mul_f32_e32 v151, v152, v151
	v_and_b32_e32 v152, 0xffff0000, v171
	v_mul_f32_e32 v162, 0xbfb8aa3b, v152
	v_exp_f32_e32 v162, v162
	s_nop 0
	v_add_f32_e32 v162, 1.0, v162
	v_rcp_f32_e32 v162, v162
	s_nop 0
	v_mul_f32_e32 v152, v162, v152
	v_mul_f32_e32 v152, v153, v152
	v_cvt_pk_bf16_f32 v151, v151, v152
	v_lshlrev_b32_e32 v152, 16, v172
	v_mul_f32_e32 v153, 0xbfb8aa3b, v152
	v_exp_f32_e32 v153, v153
	s_nop 0
	v_add_f32_e32 v153, 1.0, v153
	v_rcp_f32_e32 v153, v153
	s_nop 0
	v_mul_f32_e32 v152, v153, v152
	v_mul_f32_e32 v146, v146, v152
	v_and_b32_e32 v152, 0xffff0000, v172
	v_mul_f32_e32 v153, 0xbfb8aa3b, v152
	v_exp_f32_e32 v153, v153
	s_nop 0
	v_add_f32_e32 v153, 1.0, v153
	v_rcp_f32_e32 v153, v153
	s_nop 0
	v_mul_f32_e32 v152, v153, v152
	v_mul_f32_e32 v147, v147, v152
	v_cvt_pk_bf16_f32 v152, v146, v147
	v_lshlrev_b32_e32 v146, 16, v173
	v_mul_f32_e32 v147, 0xbfb8aa3b, v146
	v_exp_f32_e32 v147, v147
	s_nop 0
	v_add_f32_e32 v147, 1.0, v147
	v_rcp_f32_e32 v147, v147
	s_nop 0
	v_mul_f32_e32 v146, v147, v146
	v_and_b32_e32 v147, 0xffff0000, v173
	v_mul_f32_e32 v146, v148, v146
	v_mul_f32_e32 v148, 0xbfb8aa3b, v147
	v_exp_f32_e32 v148, v148
	s_nop 0
	v_add_f32_e32 v148, 1.0, v148
	v_rcp_f32_e32 v148, v148
	s_nop 0
	v_mul_f32_e32 v147, v148, v147
	v_lshlrev_b32_e32 v148, 16, v158
	v_mul_f32_e32 v147, v149, v147
	v_mul_f32_e32 v149, 0xbfb8aa3b, v148
	v_exp_f32_e32 v149, v149
	v_cvt_pk_bf16_f32 v153, v146, v147
	v_lshlrev_b64 v[146:147], 13, v[224:225]
	v_lshl_add_u64 v[146:147], s[44:45], 0, v[146:147]
	v_add_f32_e32 v149, 1.0, v149
	v_rcp_f32_e32 v149, v149
	v_lshl_add_u64 v[146:147], v[146:147], 0, v[216:217]
	global_store_dwordx4 v[146:147], v[150:153], off
	v_mul_f32_e32 v148, v149, v148
	v_mul_f32_e32 v138, v138, v148
	v_and_b32_e32 v148, 0xffff0000, v158
	v_mul_f32_e32 v149, 0xbfb8aa3b, v148
	v_exp_f32_e32 v149, v149
	s_nop 0
	v_add_f32_e32 v149, 1.0, v149
; __device__ __forceinline__ unsigned cvt_pk_bf16(float lo, float hi) { unsigned r; asm volatile("v_cvt_pk_bf16_f32 %0, %1, %2" : "=v"(r) : "v"(lo), "v"(hi)); return r; }
; __device__ __forceinline__ float bf_lo(unsigned w) { return __uint_as_float(w << 16); }
; __device__ __forceinline__ float bf_hi(unsigned w) { return __uint_as_float(w & 0xffff0000u); }
; __device__ __forceinline__ float fast_rcp(float x) { return __builtin_amdgcn_rcpf(x); }
; __device__ __forceinline__ float silu_f(float z) { return z * fast_rcp(1.0f + __builtin_amdgcn_exp2f(z * -1.44269504f)); }
;     __device__ __forceinline__ void operator()(const f32x4 (&acc)[2][2][4][2], const Unit& u, int wr, int wc, int fr, int fq, const Pre&) const {
;     ...
;             for (int ai = 0; ai < 2; ++ai)
; #pragma unroll
;                 for (int m = 0; m < 4; ++m) { const int r = row0 + ai * HALF + m * 16;
;                     const u32x4 zw = zv[ai * 4 + m];
;                     const f32x4 a0 = acc[ai][bj][m][0] * sc[bj][0], a1 = acc[ai][bj][m][1] * sc[bj][1];
;                     u32x4 w;
;                     w.x = cvt_pk_bf16(a0[0] * silu_f(bf_lo(zw.x)), a0[1] * silu_f(bf_hi(zw.x)));
;                     w.y = cvt_pk_bf16(a0[2] * silu_f(bf_lo(zw.y)), a0[3] * silu_f(bf_hi(zw.y)));
;                     w.z = cvt_pk_bf16(a1[0] * silu_f(bf_lo(zw.z)), a1[1] * silu_f(bf_hi(zw.z)));
;                     w.w = cvt_pk_bf16(a1[2] * silu_f(bf_lo(zw.w)), a1[3] * silu_f(bf_hi(zw.w)));
;                     *(u32x4*)(O + (size_t)r * DE + c) = w; } }
	v_rcp_f32_e32 v149, v149
	s_nop 0
	v_mul_f32_e32 v148, v149, v148
	v_mul_f32_e32 v139, v139, v148
	v_cvt_pk_bf16_f32 v138, v138, v139
	v_lshlrev_b32_e32 v139, 16, v159
	v_mul_f32_e32 v148, 0xbfb8aa3b, v139
	v_exp_f32_e32 v148, v148
	s_nop 0
	v_add_f32_e32 v148, 1.0, v148
	v_rcp_f32_e32 v148, v148
	s_nop 0
	v_mul_f32_e32 v139, v148, v139
	v_mul_f32_e32 v139, v140, v139
	v_and_b32_e32 v140, 0xffff0000, v159
	v_mul_f32_e32 v148, 0xbfb8aa3b, v140
	v_exp_f32_e32 v148, v148
	s_nop 0
	v_add_f32_e32 v148, 1.0, v148
	v_rcp_f32_e32 v148, v148
	s_nop 0
	v_mul_f32_e32 v140, v148, v140
	v_mul_f32_e32 v140, v141, v140
	v_cvt_pk_bf16_f32 v139, v139, v140
	v_lshlrev_b32_e32 v140, 16, v160
	v_mul_f32_e32 v141, 0xbfb8aa3b, v140
	v_exp_f32_e32 v141, v141
	s_nop 0
	v_add_f32_e32 v141, 1.0, v141
	v_rcp_f32_e32 v141, v141
	s_nop 0
	v_mul_f32_e32 v140, v141, v140
	v_mul_f32_e32 v134, v134, v140
	v_and_b32_e32 v140, 0xffff0000, v160
	v_mul_f32_e32 v141, 0xbfb8aa3b, v140
	v_exp_f32_e32 v141, v141
	s_nop 0
	v_add_f32_e32 v141, 1.0, v141
	v_rcp_f32_e32 v141, v141
	s_nop 0
	v_mul_f32_e32 v140, v141, v140
	v_mul_f32_e32 v135, v135, v140
	v_cvt_pk_bf16_f32 v140, v134, v135
	v_lshlrev_b32_e32 v134, 16, v161
	v_mul_f32_e32 v135, 0xbfb8aa3b, v134
	v_exp_f32_e32 v135, v135
	s_nop 0
	v_add_f32_e32 v135, 1.0, v135
	v_rcp_f32_e32 v135, v135
	s_nop 0
	v_mul_f32_e32 v134, v135, v134
	v_and_b32_e32 v135, 0xffff0000, v161
	v_mul_f32_e32 v134, v136, v134
	v_mul_f32_e32 v136, 0xbfb8aa3b, v135
	v_exp_f32_e32 v136, v136
	s_nop 0
	v_add_f32_e32 v136, 1.0, v136
	v_rcp_f32_e32 v136, v136
	s_nop 0
	v_mul_f32_e32 v135, v136, v135
	v_lshlrev_b32_e32 v136, 16, v154
	v_mul_f32_e32 v135, v137, v135
	v_mul_f32_e32 v137, 0xbfb8aa3b, v136
	v_exp_f32_e32 v137, v137
	v_cvt_pk_bf16_f32 v141, v134, v135
	v_lshlrev_b64 v[134:135], 13, v[222:223]
	v_lshl_add_u64 v[134:135], s[44:45], 0, v[134:135]
	v_add_f32_e32 v137, 1.0, v137
	v_rcp_f32_e32 v137, v137
	v_lshl_add_u64 v[134:135], v[134:135], 0, v[216:217]
	global_store_dwordx4 v[134:135], v[138:141], off
	v_mul_f32_e32 v136, v137, v136
	v_mul_f32_e32 v126, v126, v136
	v_and_b32_e32 v136, 0xffff0000, v154
	v_mul_f32_e32 v137, 0xbfb8aa3b, v136
	v_exp_f32_e32 v137, v137
	s_nop 0
	v_add_f32_e32 v137, 1.0, v137
	v_rcp_f32_e32 v137, v137
	s_nop 0
	v_mul_f32_e32 v136, v137, v136
	v_mul_f32_e32 v127, v127, v136
	v_cvt_pk_bf16_f32 v126, v126, v127
	v_lshlrev_b32_e32 v127, 16, v155
	v_mul_f32_e32 v136, 0xbfb8aa3b, v127
	v_exp_f32_e32 v136, v136
	s_nop 0
	v_add_f32_e32 v136, 1.0, v136
	v_rcp_f32_e32 v136, v136
	s_nop 0
	v_mul_f32_e32 v127, v136, v127
	v_mul_f32_e32 v127, v128, v127
	v_and_b32_e32 v128, 0xffff0000, v155
	v_mul_f32_e32 v136, 0xbfb8aa3b, v128
	v_exp_f32_e32 v136, v136
	s_nop 0
	v_add_f32_e32 v136, 1.0, v136
	v_rcp_f32_e32 v136, v136
	s_nop 0
	v_mul_f32_e32 v128, v136, v128
	v_mul_f32_e32 v128, v129, v128
	v_cvt_pk_bf16_f32 v127, v127, v128
	v_lshlrev_b32_e32 v128, 16, v156
	v_mul_f32_e32 v129, 0xbfb8aa3b, v128
	v_exp_f32_e32 v129, v129
	s_nop 0
	v_add_f32_e32 v129, 1.0, v129
	v_rcp_f32_e32 v129, v129
	s_nop 0
	v_mul_f32_e32 v128, v129, v128
	v_mul_f32_e32 v122, v122, v128
	v_and_b32_e32 v128, 0xffff0000, v156
	v_mul_f32_e32 v129, 0xbfb8aa3b, v128
	v_exp_f32_e32 v129, v129
	s_nop 0
	v_add_f32_e32 v129, 1.0, v129
	v_rcp_f32_e32 v129, v129
	s_nop 0
	v_mul_f32_e32 v128, v129, v128
	v_mul_f32_e32 v123, v123, v128
	v_cvt_pk_bf16_f32 v128, v122, v123
	v_lshlrev_b32_e32 v122, 16, v157
	v_mul_f32_e32 v123, 0xbfb8aa3b, v122
	v_exp_f32_e32 v123, v123
	s_nop 0
	v_add_f32_e32 v123, 1.0, v123
	v_rcp_f32_e32 v123, v123
	s_nop 0
	v_mul_f32_e32 v122, v123, v122
	v_and_b32_e32 v123, 0xffff0000, v157
	v_mul_f32_e32 v122, v124, v122
	v_mul_f32_e32 v124, 0xbfb8aa3b, v123
	v_exp_f32_e32 v124, v124
	s_nop 0
	v_add_f32_e32 v124, 1.0, v124
	v_rcp_f32_e32 v124, v124
	s_nop 0
	v_mul_f32_e32 v123, v124, v123
	v_lshlrev_b32_e32 v124, 16, v142
	v_mul_f32_e32 v123, v125, v123
	v_mul_f32_e32 v125, 0xbfb8aa3b, v124
	v_exp_f32_e32 v125, v125
	v_cvt_pk_bf16_f32 v129, v122, v123
	v_lshlrev_b64 v[122:123], 13, v[220:221]
	v_lshl_add_u64 v[122:123], s[44:45], 0, v[122:123]
	v_add_f32_e32 v125, 1.0, v125
	v_rcp_f32_e32 v125, v125
	v_lshl_add_u64 v[122:123], v[122:123], 0, v[216:217]
	global_store_dwordx4 v[122:123], v[126:129], off
	v_mul_f32_e32 v124, v125, v124
	v_mul_f32_e32 v114, v114, v124
	v_and_b32_e32 v124, 0xffff0000, v142
	v_mul_f32_e32 v125, 0xbfb8aa3b, v124
	v_exp_f32_e32 v125, v125
	s_nop 0
	v_add_f32_e32 v125, 1.0, v125
	v_rcp_f32_e32 v125, v125
	s_nop 0
	v_mul_f32_e32 v124, v125, v124
	v_mul_f32_e32 v115, v115, v124
	v_cvt_pk_bf16_f32 v114, v114, v115
	v_lshlrev_b32_e32 v115, 16, v143
	v_mul_f32_e32 v124, 0xbfb8aa3b, v115
	v_exp_f32_e32 v124, v124
	s_nop 0
	v_add_f32_e32 v124, 1.0, v124
	v_rcp_f32_e32 v124, v124
	s_nop 0
	v_mul_f32_e32 v115, v124, v115
	v_mul_f32_e32 v115, v116, v115
	v_and_b32_e32 v116, 0xffff0000, v143
	v_mul_f32_e32 v124, 0xbfb8aa3b, v116
	v_exp_f32_e32 v124, v124
	s_nop 0
	v_add_f32_e32 v124, 1.0, v124
	v_rcp_f32_e32 v124, v124
	s_nop 0
	v_mul_f32_e32 v116, v124, v116
	v_mul_f32_e32 v116, v117, v116
	v_cvt_pk_bf16_f32 v115, v115, v116
	v_lshlrev_b32_e32 v116, 16, v144
	v_mul_f32_e32 v117, 0xbfb8aa3b, v116
	v_exp_f32_e32 v117, v117
	s_nop 0
	v_add_f32_e32 v117, 1.0, v117
	v_rcp_f32_e32 v117, v117
	s_nop 0
	v_mul_f32_e32 v116, v117, v116
	v_mul_f32_e32 v110, v110, v116
	v_and_b32_e32 v116, 0xffff0000, v144
	v_mul_f32_e32 v117, 0xbfb8aa3b, v116
	v_exp_f32_e32 v117, v117
	s_nop 0
	v_add_f32_e32 v117, 1.0, v117
	v_rcp_f32_e32 v117, v117
	s_nop 0
	v_mul_f32_e32 v116, v117, v116
	v_mul_f32_e32 v111, v111, v116
	v_cvt_pk_bf16_f32 v116, v110, v111
; __device__ __forceinline__ unsigned cvt_pk_bf16(float lo, float hi) { unsigned r; asm volatile("v_cvt_pk_bf16_f32 %0, %1, %2" : "=v"(r) : "v"(lo), "v"(hi)); return r; }
; __device__ __forceinline__ float bf_lo(unsigned w) { return __uint_as_float(w << 16); }
; __device__ __forceinline__ float bf_hi(unsigned w) { return __uint_as_float(w & 0xffff0000u); }
; __device__ __forceinline__ float fast_rcp(float x) { return __builtin_amdgcn_rcpf(x); }
; __device__ __forceinline__ float silu_f(float z) { return z * fast_rcp(1.0f + __builtin_amdgcn_exp2f(z * -1.44269504f)); }
;     __device__ __forceinline__ void operator()(const f32x4 (&acc)[2][2][4][2], const Unit& u, int wr, int wc, int fr, int fq, const Pre&) const {
;     ...
;             for (int ai = 0; ai < 2; ++ai)
; #pragma unroll
;                 for (int m = 0; m < 4; ++m) { const int r = row0 + ai * HALF + m * 16;
;                     const u32x4 zw = zv[ai * 4 + m];
;                     const f32x4 a0 = acc[ai][bj][m][0] * sc[bj][0], a1 = acc[ai][bj][m][1] * sc[bj][1];
;                     u32x4 w;
;                     w.x = cvt_pk_bf16(a0[0] * silu_f(bf_lo(zw.x)), a0[1] * silu_f(bf_hi(zw.x)));
;                     w.y = cvt_pk_bf16(a0[2] * silu_f(bf_lo(zw.y)), a0[3] * silu_f(bf_hi(zw.y)));
;                     w.z = cvt_pk_bf16(a1[0] * silu_f(bf_lo(zw.z)), a1[1] * silu_f(bf_hi(zw.z)));
;                     w.w = cvt_pk_bf16(a1[2] * silu_f(bf_lo(zw.w)), a1[3] * silu_f(bf_hi(zw.w)));
;                     *(u32x4*)(O + (size_t)r * DE + c) = w; } }
	v_lshlrev_b32_e32 v110, 16, v145
	v_mul_f32_e32 v111, 0xbfb8aa3b, v110
	v_exp_f32_e32 v111, v111
	s_nop 0
	v_add_f32_e32 v111, 1.0, v111
	v_rcp_f32_e32 v111, v111
	s_nop 0
	v_mul_f32_e32 v110, v111, v110
	v_and_b32_e32 v111, 0xffff0000, v145
	v_mul_f32_e32 v110, v112, v110
	v_mul_f32_e32 v112, 0xbfb8aa3b, v111
	v_exp_f32_e32 v112, v112
	s_nop 0
	v_add_f32_e32 v112, 1.0, v112
	v_rcp_f32_e32 v112, v112
	s_nop 0
	v_mul_f32_e32 v111, v112, v111
	v_mul_f32_e32 v111, v113, v111
	v_cvt_pk_bf16_f32 v117, v110, v111
	v_lshlrev_b64 v[110:111], 13, v[218:219]
	v_lshl_add_u64 v[110:111], s[44:45], 0, v[110:111]
	v_lshl_add_u64 v[112:113], v[110:111], 0, v[216:217]
	v_lshlrev_b32_e32 v110, 16, v130
	v_mul_f32_e32 v111, 0xbfb8aa3b, v110
	v_exp_f32_e32 v111, v111
	global_store_dwordx4 v[112:113], v[114:117], off
	v_add_f32_e32 v111, 1.0, v111
	v_rcp_f32_e32 v111, v111
	s_nop 0
	v_mul_f32_e32 v110, v111, v110
	v_mul_f32_e32 v94, v94, v110
	v_and_b32_e32 v110, 0xffff0000, v130
	v_mul_f32_e32 v111, 0xbfb8aa3b, v110
	v_exp_f32_e32 v111, v111
	s_nop 0
	v_add_f32_e32 v111, 1.0, v111
	v_rcp_f32_e32 v111, v111
	s_nop 0
	v_mul_f32_e32 v110, v111, v110
	v_mul_f32_e32 v95, v95, v110
	v_cvt_pk_bf16_f32 v94, v94, v95
	v_lshlrev_b32_e32 v95, 16, v131
	v_mul_f32_e32 v110, 0xbfb8aa3b, v95
	v_exp_f32_e32 v110, v110
	s_nop 0
	v_add_f32_e32 v110, 1.0, v110
	v_rcp_f32_e32 v110, v110
	s_nop 0
	v_mul_f32_e32 v95, v110, v95
	v_mul_f32_e32 v95, v96, v95
	v_and_b32_e32 v96, 0xffff0000, v131
	v_mul_f32_e32 v110, 0xbfb8aa3b, v96
	v_exp_f32_e32 v110, v110
	s_nop 0
	v_add_f32_e32 v110, 1.0, v110
	v_rcp_f32_e32 v110, v110
	s_nop 0
	v_mul_f32_e32 v96, v110, v96
	v_mul_f32_e32 v96, v97, v96
	v_cvt_pk_bf16_f32 v95, v95, v96
	v_lshlrev_b32_e32 v96, 16, v132
	v_mul_f32_e32 v97, 0xbfb8aa3b, v96
	v_exp_f32_e32 v97, v97
	v_lshl_add_u64 v[110:111], v[166:167], 0, s[0:1]
	s_mov_b64 s[0:1], 0x140000
	v_lshl_add_u64 v[114:115], v[166:167], 0, s[0:1]
	v_add_f32_e32 v97, 1.0, v97
	v_rcp_f32_e32 v97, v97
	s_mov_b64 s[0:1], 0x160000
	v_mul_f32_e32 v96, v97, v96
	v_mul_f32_e32 v90, v90, v96
	v_and_b32_e32 v96, 0xffff0000, v132
	v_mul_f32_e32 v97, 0xbfb8aa3b, v96
	v_exp_f32_e32 v97, v97
	s_nop 0
	v_add_f32_e32 v97, 1.0, v97
	v_rcp_f32_e32 v97, v97
	s_nop 0
	v_mul_f32_e32 v96, v97, v96
	v_mul_f32_e32 v91, v91, v96
	v_cvt_pk_bf16_f32 v96, v90, v91
	v_lshlrev_b32_e32 v90, 16, v133
	v_mul_f32_e32 v91, 0xbfb8aa3b, v90
	v_exp_f32_e32 v91, v91
	s_nop 0
	v_add_f32_e32 v91, 1.0, v91
	v_rcp_f32_e32 v91, v91
	s_nop 0
	v_mul_f32_e32 v90, v91, v90
	v_and_b32_e32 v91, 0xffff0000, v133
	v_mul_f32_e32 v90, v92, v90
	v_mul_f32_e32 v92, 0xbfb8aa3b, v91
	v_exp_f32_e32 v92, v92
	s_nop 0
	v_add_f32_e32 v92, 1.0, v92
	v_rcp_f32_e32 v92, v92
	s_nop 0
	v_mul_f32_e32 v91, v92, v91
	v_mul_f32_e32 v91, v93, v91
	v_cvt_pk_bf16_f32 v97, v90, v91
	v_add_co_u32_e32 v90, vcc, s41, v166
	s_nop 1
	v_addc_co_u32_e32 v91, vcc, 0, v167, vcc
	global_store_dwordx4 v[90:91], v[94:97], off
	v_lshlrev_b32_e32 v90, 16, v118
	v_mul_f32_e32 v91, 0xbfb8aa3b, v90
	v_exp_f32_e32 v91, v91
	s_nop 0
	v_add_f32_e32 v91, 1.0, v91
	v_rcp_f32_e32 v91, v91
	s_nop 0
	v_mul_f32_e32 v90, v91, v90
	v_mul_f32_e32 v86, v86, v90
	v_and_b32_e32 v90, 0xffff0000, v118
	v_mul_f32_e32 v91, 0xbfb8aa3b, v90
	v_exp_f32_e32 v91, v91
	s_nop 0
	v_add_f32_e32 v91, 1.0, v91
	v_rcp_f32_e32 v91, v91
	s_nop 0
	v_mul_f32_e32 v90, v91, v90
	v_mul_f32_e32 v87, v87, v90
	v_cvt_pk_bf16_f32 v86, v86, v87
	v_lshlrev_b32_e32 v87, 16, v119
	v_mul_f32_e32 v90, 0xbfb8aa3b, v87
	v_exp_f32_e32 v90, v90
	s_nop 0
	v_add_f32_e32 v90, 1.0, v90
	v_rcp_f32_e32 v90, v90
	s_nop 0
	v_mul_f32_e32 v87, v90, v87
	v_mul_f32_e32 v87, v88, v87
	v_and_b32_e32 v88, 0xffff0000, v119
	v_mul_f32_e32 v90, 0xbfb8aa3b, v88
	v_exp_f32_e32 v90, v90
	s_nop 0
	v_add_f32_e32 v90, 1.0, v90
	v_rcp_f32_e32 v90, v90
	s_nop 0
	v_mul_f32_e32 v88, v90, v88
	v_mul_f32_e32 v88, v89, v88
	v_cvt_pk_bf16_f32 v87, v87, v88
	v_lshlrev_b32_e32 v88, 16, v120
	v_mul_f32_e32 v89, 0xbfb8aa3b, v88
	v_exp_f32_e32 v89, v89
	s_nop 0
	v_add_f32_e32 v89, 1.0, v89
	v_rcp_f32_e32 v89, v89
	s_nop 0
	v_mul_f32_e32 v88, v89, v88
	v_mul_f32_e32 v82, v82, v88
	v_and_b32_e32 v88, 0xffff0000, v120
	v_mul_f32_e32 v89, 0xbfb8aa3b, v88
	v_exp_f32_e32 v89, v89
	s_nop 0
	v_add_f32_e32 v89, 1.0, v89
	v_rcp_f32_e32 v89, v89
	s_nop 0
	v_mul_f32_e32 v88, v89, v88
	v_mul_f32_e32 v83, v83, v88
	v_cvt_pk_bf16_f32 v88, v82, v83
	v_lshlrev_b32_e32 v82, 16, v121
	v_mul_f32_e32 v83, 0xbfb8aa3b, v82
	v_exp_f32_e32 v83, v83
	s_nop 0
	v_add_f32_e32 v83, 1.0, v83
	v_rcp_f32_e32 v83, v83
	s_nop 0
	v_mul_f32_e32 v82, v83, v82
	v_and_b32_e32 v83, 0xffff0000, v121
	v_mul_f32_e32 v82, v84, v82
	v_mul_f32_e32 v84, 0xbfb8aa3b, v83
	v_exp_f32_e32 v84, v84
	s_nop 0
	v_add_f32_e32 v84, 1.0, v84
	v_rcp_f32_e32 v84, v84
	s_nop 0
	v_mul_f32_e32 v83, v84, v83
	v_mul_f32_e32 v83, v85, v83
	v_cvt_pk_bf16_f32 v89, v82, v83
	v_add_co_u32_e32 v82, vcc, s65, v166
	s_nop 1
	v_addc_co_u32_e32 v83, vcc, 0, v167, vcc
	global_store_dwordx4 v[82:83], v[86:89], off
	v_lshlrev_b32_e32 v82, 16, v106
	v_mul_f32_e32 v83, 0xbfb8aa3b, v82
	v_exp_f32_e32 v83, v83
	s_nop 0
	v_add_f32_e32 v83, 1.0, v83
	v_rcp_f32_e32 v83, v83
	s_nop 0
	v_mul_f32_e32 v82, v83, v82
	v_mul_f32_e32 v78, v78, v82
	v_and_b32_e32 v82, 0xffff0000, v106
	v_mul_f32_e32 v83, 0xbfb8aa3b, v82
	v_exp_f32_e32 v83, v83
	s_nop 0
	v_add_f32_e32 v83, 1.0, v83
	v_rcp_f32_e32 v83, v83
	s_nop 0
	v_mul_f32_e32 v82, v83, v82
	v_mul_f32_e32 v79, v79, v82
	v_cvt_pk_bf16_f32 v78, v78, v79
	v_lshlrev_b32_e32 v79, 16, v107
	v_mul_f32_e32 v82, 0xbfb8aa3b, v79
	v_exp_f32_e32 v82, v82
	s_nop 0
	v_add_f32_e32 v82, 1.0, v82
	v_rcp_f32_e32 v82, v82
; __device__ __forceinline__ unsigned cvt_pk_bf16(float lo, float hi) { unsigned r; asm volatile("v_cvt_pk_bf16_f32 %0, %1, %2" : "=v"(r) : "v"(lo), "v"(hi)); return r; }
; __device__ __forceinline__ float bf_lo(unsigned w) { return __uint_as_float(w << 16); }
; __device__ __forceinline__ float bf_hi(unsigned w) { return __uint_as_float(w & 0xffff0000u); }
; __device__ __forceinline__ float fast_rcp(float x) { return __builtin_amdgcn_rcpf(x); }
; __device__ __forceinline__ float silu_f(float z) { return z * fast_rcp(1.0f + __builtin_amdgcn_exp2f(z * -1.44269504f)); }
;     __device__ __forceinline__ void operator()(const f32x4 (&acc)[2][2][4][2], const Unit& u, int wr, int wc, int fr, int fq, const Pre&) const {
;     ...
;         for (int bj = 0; bj < 2; ++bj) { const int c = col0 + bj * HALF;
;             u32x4 zv[8];
; #pragma unroll
;             for (int g8 = 0; g8 < 8; ++g8) zv[g8] = *(const u32x4*)(Z + (size_t)(row0 + (g8 >> 2) * HALF + (g8 & 3) * 16) * DE2 + c);
; #pragma unroll
;             for (int ai = 0; ai < 2; ++ai)
; #pragma unroll
;                 for (int m = 0; m < 4; ++m) { const int r = row0 + ai * HALF + m * 16;
;                     const u32x4 zw = zv[ai * 4 + m];
;                     const f32x4 a0 = acc[ai][bj][m][0] * sc[bj][0], a1 = acc[ai][bj][m][1] * sc[bj][1];
;                     u32x4 w;
;                     w.x = cvt_pk_bf16(a0[0] * silu_f(bf_lo(zw.x)), a0[1] * silu_f(bf_hi(zw.x)));
;                     w.y = cvt_pk_bf16(a0[2] * silu_f(bf_lo(zw.y)), a0[3] * silu_f(bf_hi(zw.y)));
;                     w.z = cvt_pk_bf16(a1[0] * silu_f(bf_lo(zw.z)), a1[1] * silu_f(bf_hi(zw.z)));
;                     w.w = cvt_pk_bf16(a1[2] * silu_f(bf_lo(zw.w)), a1[3] * silu_f(bf_hi(zw.w)));
;                     *(u32x4*)(O + (size_t)r * DE + c) = w; } }
	s_nop 0
	v_mul_f32_e32 v79, v82, v79
	v_mul_f32_e32 v79, v80, v79
	v_and_b32_e32 v80, 0xffff0000, v107
	v_mul_f32_e32 v82, 0xbfb8aa3b, v80
	v_exp_f32_e32 v82, v82
	v_lshl_add_u64 v[106:107], v[166:167], 0, s[0:1]
	s_mov_b64 s[0:1], s[54:55]
	v_add_f32_e32 v82, 1.0, v82
	v_rcp_f32_e32 v82, v82
	s_nop 0
	v_mul_f32_e32 v80, v82, v80
	v_mul_f32_e32 v80, v81, v80
	v_cvt_pk_bf16_f32 v79, v79, v80
	v_lshlrev_b32_e32 v80, 16, v108
	v_mul_f32_e32 v81, 0xbfb8aa3b, v80
	v_exp_f32_e32 v81, v81
	s_nop 0
	v_add_f32_e32 v81, 1.0, v81
	v_rcp_f32_e32 v81, v81
	s_nop 0
	v_mul_f32_e32 v80, v81, v80
	v_mul_f32_e32 v74, v74, v80
	v_and_b32_e32 v80, 0xffff0000, v108
	v_mul_f32_e32 v81, 0xbfb8aa3b, v80
	v_exp_f32_e32 v81, v81
	s_nop 0
	v_add_f32_e32 v81, 1.0, v81
	v_rcp_f32_e32 v81, v81
	s_nop 0
	v_mul_f32_e32 v80, v81, v80
	v_mul_f32_e32 v75, v75, v80
	v_cvt_pk_bf16_f32 v80, v74, v75
	v_lshlrev_b32_e32 v74, 16, v109
	v_mul_f32_e32 v75, 0xbfb8aa3b, v74
	v_exp_f32_e32 v75, v75
	s_nop 0
	v_add_f32_e32 v75, 1.0, v75
	v_rcp_f32_e32 v75, v75
	s_nop 0
	v_mul_f32_e32 v74, v75, v74
	v_and_b32_e32 v75, 0xffff0000, v109
	v_mul_f32_e32 v74, v76, v74
	v_mul_f32_e32 v76, 0xbfb8aa3b, v75
	v_exp_f32_e32 v76, v76
	s_nop 0
	v_add_f32_e32 v76, 1.0, v76
	v_rcp_f32_e32 v76, v76
	s_nop 0
	v_mul_f32_e32 v75, v76, v75
	v_mul_f32_e32 v75, v77, v75
	v_cvt_pk_bf16_f32 v81, v74, v75
	v_add_co_u32_e32 v74, vcc, s70, v166
	v_lshl_add_u64 v[76:77], s[46:47], 0, v[204:205]
	s_nop 0
	v_addc_co_u32_e32 v75, vcc, 0, v167, vcc
	global_store_dwordx4 v[74:75], v[78:81], off
	v_or_b32_e32 v74, 0x80, v200
	v_ashrrev_i32_e32 v75, 31, v74
	v_lshlrev_b64 v[74:75], 1, v[74:75]
	v_lshl_add_u64 v[76:77], v[76:77], 0, v[74:75]
	global_load_dwordx4 v[102:105], v[76:77], off
	v_lshl_add_u64 v[76:77], s[46:47], 0, v[198:199]
	v_lshl_add_u64 v[76:77], v[76:77], 0, v[74:75]
	global_load_dwordx4 v[98:101], v[76:77], off
	v_lshl_add_u64 v[76:77], s[46:47], 0, v[202:203]
	v_lshl_add_u64 v[76:77], v[76:77], 0, v[74:75]
	global_load_dwordx4 v[94:97], v[76:77], off
	v_lshl_add_u64 v[76:77], s[46:47], 0, v[206:207]
	v_lshl_add_u64 v[76:77], v[76:77], 0, v[74:75]
	global_load_dwordx4 v[90:93], v[76:77], off
	v_lshl_add_u64 v[76:77], s[46:47], 0, v[208:209]
	v_lshl_add_u64 v[76:77], v[76:77], 0, v[74:75]
	global_load_dwordx4 v[86:89], v[76:77], off
	v_lshl_add_u64 v[76:77], s[46:47], 0, v[210:211]
	v_lshl_add_u64 v[76:77], v[76:77], 0, v[74:75]
	global_load_dwordx4 v[82:85], v[76:77], off
	v_lshl_add_u64 v[76:77], s[46:47], 0, v[212:213]
	v_lshl_add_u64 v[76:77], v[76:77], 0, v[74:75]
	global_load_dwordx4 v[78:81], v[76:77], off
	v_lshl_add_u64 v[76:77], s[46:47], 0, v[214:215]
	v_lshl_add_u64 v[74:75], v[76:77], 0, v[74:75]
	global_load_dwordx4 v[74:77], v[74:75], off
	s_and_b64 vcc, exec, s[42:43]
	s_waitcnt vmcnt(0)
	v_lshlrev_b32_e32 v108, 16, v102
	v_mul_f32_e32 v109, 0xbfb8aa3b, v108
	v_exp_f32_e32 v109, v109
	v_and_b32_e32 v102, 0xffff0000, v102
	v_add_f32_e32 v109, 1.0, v109
	v_rcp_f32_e32 v109, v109
	s_nop 0
	v_mul_f32_e32 v108, v109, v108
	v_mul_f32_e32 v70, v70, v108
	v_mul_f32_e32 v108, 0xbfb8aa3b, v102
	v_exp_f32_e32 v108, v108
	s_nop 0
	v_add_f32_e32 v108, 1.0, v108
	v_rcp_f32_e32 v108, v108
	s_nop 0
	v_mul_f32_e32 v102, v108, v102
	v_mul_f32_e32 v71, v71, v102
	v_cvt_pk_bf16_f32 v70, v70, v71
	v_lshlrev_b32_e32 v71, 16, v103
	v_mul_f32_e32 v102, 0xbfb8aa3b, v71
	v_exp_f32_e32 v102, v102
	s_nop 0
	v_add_f32_e32 v102, 1.0, v102
	v_rcp_f32_e32 v102, v102
	s_nop 0
	v_mul_f32_e32 v71, v102, v71
	v_mul_f32_e32 v71, v72, v71
	v_and_b32_e32 v72, 0xffff0000, v103
	v_mul_f32_e32 v102, 0xbfb8aa3b, v72
	v_exp_f32_e32 v102, v102
	s_nop 0
	v_add_f32_e32 v102, 1.0, v102
	v_rcp_f32_e32 v102, v102
	s_nop 0
	v_mul_f32_e32 v72, v102, v72
	v_mul_f32_e32 v72, v73, v72
	v_cvt_pk_bf16_f32 v71, v71, v72
	v_lshlrev_b32_e32 v72, 16, v104
	v_mul_f32_e32 v73, 0xbfb8aa3b, v72
	v_exp_f32_e32 v73, v73
	s_nop 0
	v_add_f32_e32 v73, 1.0, v73
	v_rcp_f32_e32 v73, v73
	s_nop 0
	v_mul_f32_e32 v72, v73, v72
	v_mul_f32_e32 v66, v66, v72
	v_and_b32_e32 v72, 0xffff0000, v104
	v_mul_f32_e32 v73, 0xbfb8aa3b, v72
	v_exp_f32_e32 v73, v73
	s_nop 0
	v_add_f32_e32 v73, 1.0, v73
	v_rcp_f32_e32 v73, v73
	s_nop 0
	v_mul_f32_e32 v72, v73, v72
	v_mul_f32_e32 v67, v67, v72
	v_cvt_pk_bf16_f32 v72, v66, v67
	v_lshlrev_b32_e32 v66, 16, v105
	v_mul_f32_e32 v67, 0xbfb8aa3b, v66
	v_exp_f32_e32 v67, v67
	s_nop 0
	v_add_f32_e32 v67, 1.0, v67
	v_rcp_f32_e32 v67, v67
	s_nop 0
	v_mul_f32_e32 v66, v67, v66
	v_and_b32_e32 v67, 0xffff0000, v105
	v_mul_f32_e32 v66, v68, v66
	v_mul_f32_e32 v68, 0xbfb8aa3b, v67
	v_exp_f32_e32 v68, v68
	s_nop 0
	v_add_f32_e32 v68, 1.0, v68
	v_rcp_f32_e32 v68, v68
	s_nop 0
	v_mul_f32_e32 v67, v68, v67
	v_mul_f32_e32 v67, v69, v67
	v_cvt_pk_bf16_f32 v73, v66, v67
	v_lshlrev_b32_e32 v66, 16, v98
	v_mul_f32_e32 v67, 0xbfb8aa3b, v66
	v_exp_f32_e32 v67, v67
	global_store_dwordx4 v[166:167], v[70:73], off offset:256
	v_add_f32_e32 v67, 1.0, v67
	v_rcp_f32_e32 v67, v67
	s_nop 0
	v_mul_f32_e32 v66, v67, v66
	v_mul_f32_e32 v62, v62, v66
	v_and_b32_e32 v66, 0xffff0000, v98
	v_mul_f32_e32 v67, 0xbfb8aa3b, v66
	v_exp_f32_e32 v67, v67
	s_nop 0
	v_add_f32_e32 v67, 1.0, v67
	v_rcp_f32_e32 v67, v67
	s_nop 0
	v_mul_f32_e32 v66, v67, v66
	v_mul_f32_e32 v63, v63, v66
	v_cvt_pk_bf16_f32 v62, v62, v63
	v_lshlrev_b32_e32 v63, 16, v99
	v_mul_f32_e32 v66, 0xbfb8aa3b, v63
	v_exp_f32_e32 v66, v66
	s_nop 0
	v_add_f32_e32 v66, 1.0, v66
	v_rcp_f32_e32 v66, v66
	s_nop 0
	v_mul_f32_e32 v63, v66, v63
	v_mul_f32_e32 v63, v64, v63
	v_and_b32_e32 v64, 0xffff0000, v99
	v_mul_f32_e32 v66, 0xbfb8aa3b, v64
	v_exp_f32_e32 v66, v66
	s_nop 0
	v_add_f32_e32 v66, 1.0, v66
; __device__ __forceinline__ unsigned cvt_pk_bf16(float lo, float hi) { unsigned r; asm volatile("v_cvt_pk_bf16_f32 %0, %1, %2" : "=v"(r) : "v"(lo), "v"(hi)); return r; }
; __device__ __forceinline__ float bf_lo(unsigned w) { return __uint_as_float(w << 16); }
; __device__ __forceinline__ float bf_hi(unsigned w) { return __uint_as_float(w & 0xffff0000u); }
; __device__ __forceinline__ float fast_rcp(float x) { return __builtin_amdgcn_rcpf(x); }
; __device__ __forceinline__ float silu_f(float z) { return z * fast_rcp(1.0f + __builtin_amdgcn_exp2f(z * -1.44269504f)); }
;     __device__ __forceinline__ void operator()(const f32x4 (&acc)[2][2][4][2], const Unit& u, int wr, int wc, int fr, int fq, const Pre&) const {
;     ...
;             for (int ai = 0; ai < 2; ++ai)
; #pragma unroll
;                 for (int m = 0; m < 4; ++m) { const int r = row0 + ai * HALF + m * 16;
;                     const u32x4 zw = zv[ai * 4 + m];
;                     const f32x4 a0 = acc[ai][bj][m][0] * sc[bj][0], a1 = acc[ai][bj][m][1] * sc[bj][1];
;                     u32x4 w;
;                     w.x = cvt_pk_bf16(a0[0] * silu_f(bf_lo(zw.x)), a0[1] * silu_f(bf_hi(zw.x)));
;                     w.y = cvt_pk_bf16(a0[2] * silu_f(bf_lo(zw.y)), a0[3] * silu_f(bf_hi(zw.y)));
;                     w.z = cvt_pk_bf16(a1[0] * silu_f(bf_lo(zw.z)), a1[1] * silu_f(bf_hi(zw.z)));
;                     w.w = cvt_pk_bf16(a1[2] * silu_f(bf_lo(zw.w)), a1[3] * silu_f(bf_hi(zw.w)));
;                     *(u32x4*)(O + (size_t)r * DE + c) = w; } }
	v_rcp_f32_e32 v66, v66
	s_nop 0
	v_mul_f32_e32 v64, v66, v64
	v_mul_f32_e32 v64, v65, v64
	v_cvt_pk_bf16_f32 v63, v63, v64
	v_lshlrev_b32_e32 v64, 16, v100
	v_mul_f32_e32 v65, 0xbfb8aa3b, v64
	v_exp_f32_e32 v65, v65
	s_nop 0
	v_add_f32_e32 v65, 1.0, v65
	v_rcp_f32_e32 v65, v65
	s_nop 0
	v_mul_f32_e32 v64, v65, v64
	v_mul_f32_e32 v58, v58, v64
	v_and_b32_e32 v64, 0xffff0000, v100
	v_mul_f32_e32 v65, 0xbfb8aa3b, v64
	v_exp_f32_e32 v65, v65
	s_nop 0
	v_add_f32_e32 v65, 1.0, v65
	v_rcp_f32_e32 v65, v65
	s_nop 0
	v_mul_f32_e32 v64, v65, v64
	v_mul_f32_e32 v59, v59, v64
	v_cvt_pk_bf16_f32 v64, v58, v59
	v_lshlrev_b32_e32 v58, 16, v101
	v_mul_f32_e32 v59, 0xbfb8aa3b, v58
	v_exp_f32_e32 v59, v59
	s_nop 0
	v_add_f32_e32 v59, 1.0, v59
	v_rcp_f32_e32 v59, v59
	s_nop 0
	v_mul_f32_e32 v58, v59, v58
	v_and_b32_e32 v59, 0xffff0000, v101
	v_mul_f32_e32 v58, v60, v58
	v_mul_f32_e32 v60, 0xbfb8aa3b, v59
	v_exp_f32_e32 v60, v60
	s_nop 0
	v_add_f32_e32 v60, 1.0, v60
	v_rcp_f32_e32 v60, v60
	s_nop 0
	v_mul_f32_e32 v59, v60, v59
	v_mul_f32_e32 v59, v61, v59
	v_cvt_pk_bf16_f32 v65, v58, v59
	v_lshlrev_b32_e32 v58, 16, v94
	v_mul_f32_e32 v59, 0xbfb8aa3b, v58
	v_exp_f32_e32 v59, v59
	global_store_dwordx4 v[146:147], v[62:65], off offset:256
	v_add_f32_e32 v59, 1.0, v59
	v_rcp_f32_e32 v59, v59
	s_nop 0
	v_mul_f32_e32 v58, v59, v58
	v_mul_f32_e32 v54, v54, v58
	v_and_b32_e32 v58, 0xffff0000, v94
	v_mul_f32_e32 v59, 0xbfb8aa3b, v58
	v_exp_f32_e32 v59, v59
	s_nop 0
	v_add_f32_e32 v59, 1.0, v59
	v_rcp_f32_e32 v59, v59
	s_nop 0
	v_mul_f32_e32 v58, v59, v58
	v_mul_f32_e32 v55, v55, v58
	v_cvt_pk_bf16_f32 v54, v54, v55
	v_lshlrev_b32_e32 v55, 16, v95
	v_mul_f32_e32 v58, 0xbfb8aa3b, v55
	v_exp_f32_e32 v58, v58
	s_nop 0
	v_add_f32_e32 v58, 1.0, v58
	v_rcp_f32_e32 v58, v58
	s_nop 0
	v_mul_f32_e32 v55, v58, v55
	v_mul_f32_e32 v55, v56, v55
	v_and_b32_e32 v56, 0xffff0000, v95
	v_mul_f32_e32 v58, 0xbfb8aa3b, v56
	v_exp_f32_e32 v58, v58
	s_nop 0
	v_add_f32_e32 v58, 1.0, v58
	v_rcp_f32_e32 v58, v58
	s_nop 0
	v_mul_f32_e32 v56, v58, v56
	v_mul_f32_e32 v56, v57, v56
	v_cvt_pk_bf16_f32 v55, v55, v56
	v_lshlrev_b32_e32 v56, 16, v96
	v_mul_f32_e32 v57, 0xbfb8aa3b, v56
	v_exp_f32_e32 v57, v57
	s_nop 0
	v_add_f32_e32 v57, 1.0, v57
	v_rcp_f32_e32 v57, v57
	s_nop 0
	v_mul_f32_e32 v56, v57, v56
	v_mul_f32_e32 v50, v50, v56
	v_and_b32_e32 v56, 0xffff0000, v96
	v_mul_f32_e32 v57, 0xbfb8aa3b, v56
	v_exp_f32_e32 v57, v57
	s_nop 0
	v_add_f32_e32 v57, 1.0, v57
	v_rcp_f32_e32 v57, v57
	s_nop 0
	v_mul_f32_e32 v56, v57, v56
	v_mul_f32_e32 v51, v51, v56
	v_cvt_pk_bf16_f32 v56, v50, v51
	v_lshlrev_b32_e32 v50, 16, v97
	v_mul_f32_e32 v51, 0xbfb8aa3b, v50
	v_exp_f32_e32 v51, v51
	s_nop 0
	v_add_f32_e32 v51, 1.0, v51
	v_rcp_f32_e32 v51, v51
	s_nop 0
	v_mul_f32_e32 v50, v51, v50
	v_and_b32_e32 v51, 0xffff0000, v97
	v_mul_f32_e32 v50, v52, v50
	v_mul_f32_e32 v52, 0xbfb8aa3b, v51
	v_exp_f32_e32 v52, v52
	s_nop 0
	v_add_f32_e32 v52, 1.0, v52
	v_rcp_f32_e32 v52, v52
	s_nop 0
	v_mul_f32_e32 v51, v52, v51
	v_mul_f32_e32 v51, v53, v51
	v_cvt_pk_bf16_f32 v57, v50, v51
	v_lshlrev_b32_e32 v50, 16, v90
	v_mul_f32_e32 v51, 0xbfb8aa3b, v50
	v_exp_f32_e32 v51, v51
	global_store_dwordx4 v[134:135], v[54:57], off offset:256
	v_add_f32_e32 v51, 1.0, v51
	v_rcp_f32_e32 v51, v51
	s_nop 0
	v_mul_f32_e32 v50, v51, v50
	v_mul_f32_e32 v46, v46, v50
	v_and_b32_e32 v50, 0xffff0000, v90
	v_mul_f32_e32 v51, 0xbfb8aa3b, v50
	v_exp_f32_e32 v51, v51
	s_nop 0
	v_add_f32_e32 v51, 1.0, v51
	v_rcp_f32_e32 v51, v51
	s_nop 0
	v_mul_f32_e32 v50, v51, v50
	v_mul_f32_e32 v47, v47, v50
	v_cvt_pk_bf16_f32 v46, v46, v47
	v_lshlrev_b32_e32 v47, 16, v91
	v_mul_f32_e32 v50, 0xbfb8aa3b, v47
	v_exp_f32_e32 v50, v50
	s_nop 0
	v_add_f32_e32 v50, 1.0, v50
	v_rcp_f32_e32 v50, v50
	s_nop 0
	v_mul_f32_e32 v47, v50, v47
	v_mul_f32_e32 v47, v48, v47
	v_and_b32_e32 v48, 0xffff0000, v91
	v_mul_f32_e32 v50, 0xbfb8aa3b, v48
	v_exp_f32_e32 v50, v50
	s_nop 0
	v_add_f32_e32 v50, 1.0, v50
	v_rcp_f32_e32 v50, v50
	s_nop 0
	v_mul_f32_e32 v48, v50, v48
	v_mul_f32_e32 v48, v49, v48
	v_cvt_pk_bf16_f32 v47, v47, v48
	v_lshlrev_b32_e32 v48, 16, v92
	v_mul_f32_e32 v49, 0xbfb8aa3b, v48
	v_exp_f32_e32 v49, v49
	s_nop 0
	v_add_f32_e32 v49, 1.0, v49
	v_rcp_f32_e32 v49, v49
	s_nop 0
	v_mul_f32_e32 v48, v49, v48
	v_mul_f32_e32 v42, v42, v48
	v_and_b32_e32 v48, 0xffff0000, v92
	v_mul_f32_e32 v49, 0xbfb8aa3b, v48
	v_exp_f32_e32 v49, v49
	s_nop 0
	v_add_f32_e32 v49, 1.0, v49
	v_rcp_f32_e32 v49, v49
	s_nop 0
	v_mul_f32_e32 v48, v49, v48
	v_mul_f32_e32 v43, v43, v48
	v_cvt_pk_bf16_f32 v48, v42, v43
	v_lshlrev_b32_e32 v42, 16, v93
	v_mul_f32_e32 v43, 0xbfb8aa3b, v42
	v_exp_f32_e32 v43, v43
	s_nop 0
	v_add_f32_e32 v43, 1.0, v43
	v_rcp_f32_e32 v43, v43
	s_nop 0
	v_mul_f32_e32 v42, v43, v42
	v_and_b32_e32 v43, 0xffff0000, v93
	v_mul_f32_e32 v42, v44, v42
	v_mul_f32_e32 v44, 0xbfb8aa3b, v43
	v_exp_f32_e32 v44, v44
	s_nop 0
	v_add_f32_e32 v44, 1.0, v44
	v_rcp_f32_e32 v44, v44
	s_nop 0
	v_mul_f32_e32 v43, v44, v43
	v_mul_f32_e32 v43, v45, v43
	v_cvt_pk_bf16_f32 v49, v42, v43
	v_lshlrev_b32_e32 v42, 16, v86
	v_mul_f32_e32 v43, 0xbfb8aa3b, v42
	v_exp_f32_e32 v43, v43
	global_store_dwordx4 v[122:123], v[46:49], off offset:256
	v_add_f32_e32 v43, 1.0, v43
	v_rcp_f32_e32 v43, v43
	s_nop 0
	v_mul_f32_e32 v42, v43, v42
	v_mul_f32_e32 v30, v30, v42
	v_and_b32_e32 v42, 0xffff0000, v86
	v_mul_f32_e32 v43, 0xbfb8aa3b, v42
	v_exp_f32_e32 v43, v43
	s_nop 0
	v_add_f32_e32 v43, 1.0, v43
	v_rcp_f32_e32 v43, v43
	s_nop 0
	v_mul_f32_e32 v42, v43, v42
	v_mul_f32_e32 v31, v31, v42
	v_cvt_pk_bf16_f32 v30, v30, v31
	v_lshlrev_b32_e32 v31, 16, v87
	v_mul_f32_e32 v42, 0xbfb8aa3b, v31
	v_exp_f32_e32 v42, v42
; __device__ __forceinline__ unsigned cvt_pk_bf16(float lo, float hi) { unsigned r; asm volatile("v_cvt_pk_bf16_f32 %0, %1, %2" : "=v"(r) : "v"(lo), "v"(hi)); return r; }
; __device__ __forceinline__ float bf_lo(unsigned w) { return __uint_as_float(w << 16); }
; __device__ __forceinline__ float bf_hi(unsigned w) { return __uint_as_float(w & 0xffff0000u); }
; __device__ __forceinline__ float fast_rcp(float x) { return __builtin_amdgcn_rcpf(x); }
; __device__ __forceinline__ float silu_f(float z) { return z * fast_rcp(1.0f + __builtin_amdgcn_exp2f(z * -1.44269504f)); }
;     __device__ __forceinline__ void operator()(const f32x4 (&acc)[2][2][4][2], const Unit& u, int wr, int wc, int fr, int fq, const Pre&) const {
;     ...
;             for (int ai = 0; ai < 2; ++ai)
; #pragma unroll
;                 for (int m = 0; m < 4; ++m) { const int r = row0 + ai * HALF + m * 16;
;                     const u32x4 zw = zv[ai * 4 + m];
;                     const f32x4 a0 = acc[ai][bj][m][0] * sc[bj][0], a1 = acc[ai][bj][m][1] * sc[bj][1];
;                     u32x4 w;
;                     w.x = cvt_pk_bf16(a0[0] * silu_f(bf_lo(zw.x)), a0[1] * silu_f(bf_hi(zw.x)));
;                     w.y = cvt_pk_bf16(a0[2] * silu_f(bf_lo(zw.y)), a0[3] * silu_f(bf_hi(zw.y)));
;                     w.z = cvt_pk_bf16(a1[0] * silu_f(bf_lo(zw.z)), a1[1] * silu_f(bf_hi(zw.z)));
;                     w.w = cvt_pk_bf16(a1[2] * silu_f(bf_lo(zw.w)), a1[3] * silu_f(bf_hi(zw.w)));
;                     *(u32x4*)(O + (size_t)r * DE + c) = w; } }
	s_nop 0
	v_add_f32_e32 v42, 1.0, v42
	v_rcp_f32_e32 v42, v42
	s_nop 0
	v_mul_f32_e32 v31, v42, v31
	v_mul_f32_e32 v31, v32, v31
	v_and_b32_e32 v32, 0xffff0000, v87
	v_mul_f32_e32 v42, 0xbfb8aa3b, v32
	v_exp_f32_e32 v42, v42
	s_nop 0
	v_add_f32_e32 v42, 1.0, v42
	v_rcp_f32_e32 v42, v42
	s_nop 0
	v_mul_f32_e32 v32, v42, v32
	v_mul_f32_e32 v32, v33, v32
	v_cvt_pk_bf16_f32 v31, v31, v32
	v_lshlrev_b32_e32 v32, 16, v88
	v_mul_f32_e32 v33, 0xbfb8aa3b, v32
	v_exp_f32_e32 v33, v33
	s_nop 0
	v_add_f32_e32 v33, 1.0, v33
	v_rcp_f32_e32 v33, v33
	s_nop 0
	v_mul_f32_e32 v32, v33, v32
	v_mul_f32_e32 v26, v26, v32
	v_and_b32_e32 v32, 0xffff0000, v88
	v_mul_f32_e32 v33, 0xbfb8aa3b, v32
	v_exp_f32_e32 v33, v33
	s_nop 0
	v_add_f32_e32 v33, 1.0, v33
	v_rcp_f32_e32 v33, v33
	s_nop 0
	v_mul_f32_e32 v32, v33, v32
	v_mul_f32_e32 v27, v27, v32
	v_cvt_pk_bf16_f32 v32, v26, v27
	v_lshlrev_b32_e32 v26, 16, v89
	v_mul_f32_e32 v27, 0xbfb8aa3b, v26
	v_exp_f32_e32 v27, v27
	s_nop 0
	v_add_f32_e32 v27, 1.0, v27
	v_rcp_f32_e32 v27, v27
	s_nop 0
	v_mul_f32_e32 v26, v27, v26
	v_and_b32_e32 v27, 0xffff0000, v89
	v_mul_f32_e32 v26, v28, v26
	v_mul_f32_e32 v28, 0xbfb8aa3b, v27
	v_exp_f32_e32 v28, v28
	s_nop 0
	v_add_f32_e32 v28, 1.0, v28
	v_rcp_f32_e32 v28, v28
	s_nop 0
	v_mul_f32_e32 v27, v28, v27
	v_mul_f32_e32 v27, v29, v27
	v_cvt_pk_bf16_f32 v33, v26, v27
	v_lshlrev_b32_e32 v26, 16, v82
	v_mul_f32_e32 v27, 0xbfb8aa3b, v26
	v_exp_f32_e32 v27, v27
	global_store_dwordx4 v[112:113], v[30:33], off offset:256
	v_add_f32_e32 v27, 1.0, v27
	v_rcp_f32_e32 v27, v27
	s_nop 0
	v_mul_f32_e32 v26, v27, v26
	v_mul_f32_e32 v22, v22, v26
	v_and_b32_e32 v26, 0xffff0000, v82
	v_mul_f32_e32 v27, 0xbfb8aa3b, v26
	v_exp_f32_e32 v27, v27
	s_nop 0
	v_add_f32_e32 v27, 1.0, v27
	v_rcp_f32_e32 v27, v27
	s_nop 0
	v_mul_f32_e32 v26, v27, v26
	v_mul_f32_e32 v23, v23, v26
	v_cvt_pk_bf16_f32 v22, v22, v23
	v_lshlrev_b32_e32 v23, 16, v83
	v_mul_f32_e32 v26, 0xbfb8aa3b, v23
	v_exp_f32_e32 v26, v26
	s_nop 0
	v_add_f32_e32 v26, 1.0, v26
	v_rcp_f32_e32 v26, v26
	s_nop 0
	v_mul_f32_e32 v23, v26, v23
	v_mul_f32_e32 v23, v24, v23
	v_and_b32_e32 v24, 0xffff0000, v83
	v_mul_f32_e32 v26, 0xbfb8aa3b, v24
	v_exp_f32_e32 v26, v26
	s_nop 0
	v_add_f32_e32 v26, 1.0, v26
	v_rcp_f32_e32 v26, v26
	s_nop 0
	v_mul_f32_e32 v24, v26, v24
	v_mul_f32_e32 v24, v25, v24
	v_cvt_pk_bf16_f32 v23, v23, v24
	v_lshlrev_b32_e32 v24, 16, v84
	v_mul_f32_e32 v25, 0xbfb8aa3b, v24
	v_exp_f32_e32 v25, v25
	s_nop 0
	v_add_f32_e32 v25, 1.0, v25
	v_rcp_f32_e32 v25, v25
	s_nop 0
	v_mul_f32_e32 v24, v25, v24
	v_mul_f32_e32 v18, v18, v24
	v_and_b32_e32 v24, 0xffff0000, v84
	v_mul_f32_e32 v25, 0xbfb8aa3b, v24
	v_exp_f32_e32 v25, v25
	s_nop 0
	v_add_f32_e32 v25, 1.0, v25
	v_rcp_f32_e32 v25, v25
	s_nop 0
	v_mul_f32_e32 v24, v25, v24
	v_mul_f32_e32 v19, v19, v24
	v_cvt_pk_bf16_f32 v24, v18, v19
	v_lshlrev_b32_e32 v18, 16, v85
	v_mul_f32_e32 v19, 0xbfb8aa3b, v18
	v_exp_f32_e32 v19, v19
	s_nop 0
	v_add_f32_e32 v19, 1.0, v19
	v_rcp_f32_e32 v19, v19
	s_nop 0
	v_mul_f32_e32 v18, v19, v18
	v_and_b32_e32 v19, 0xffff0000, v85
	v_mul_f32_e32 v18, v20, v18
	v_mul_f32_e32 v20, 0xbfb8aa3b, v19
	v_exp_f32_e32 v20, v20
	s_nop 0
	v_add_f32_e32 v20, 1.0, v20
	v_rcp_f32_e32 v20, v20
	s_nop 0
	v_mul_f32_e32 v19, v20, v19
	v_mul_f32_e32 v19, v21, v19
	v_cvt_pk_bf16_f32 v25, v18, v19
	v_lshlrev_b32_e32 v18, 16, v78
	v_mul_f32_e32 v19, 0xbfb8aa3b, v18
	v_exp_f32_e32 v19, v19
	global_store_dwordx4 v[110:111], v[22:25], off offset:256
	v_add_f32_e32 v19, 1.0, v19
	v_rcp_f32_e32 v19, v19
	s_nop 0
	v_mul_f32_e32 v18, v19, v18
	v_mul_f32_e32 v14, v14, v18
	v_and_b32_e32 v18, 0xffff0000, v78
	v_mul_f32_e32 v19, 0xbfb8aa3b, v18
	v_exp_f32_e32 v19, v19
; __device__ __forceinline__ unsigned cvt_pk_bf16(float lo, float hi) { unsigned r; asm volatile("v_cvt_pk_bf16_f32 %0, %1, %2" : "=v"(r) : "v"(lo), "v"(hi)); return r; }
; __device__ __forceinline__ float bf_lo(unsigned w) { return __uint_as_float(w << 16); }
; __device__ __forceinline__ float bf_hi(unsigned w) { return __uint_as_float(w & 0xffff0000u); }
; __device__ __forceinline__ float silu_f(float z) { return z * fast_rcp(1.0f + __builtin_amdgcn_exp2f(z * -1.44269504f)); }
; #define PG8_WAIT_V(n) asm volatile("s_waitcnt vmcnt(" #n ")" ::: "memory")
; #define PG8_BAR __builtin_amdgcn_s_barrier()
; template <class Epi>
; __device__ __forceinline__ void gemm_phase(LAS unsigned char* lds, const Gemm g, const StaticOrder& S, const Epi& E) {
;     ...
;     PG8_WAIT_V(0);
;     if (wr == 0) PG8_BAR;
;     PG8_BAR;
;     __device__ __forceinline__ void operator()(const f32x4 (&acc)[2][2][4][2], const Unit& u, int wr, int wc, int fr, int fq, const Pre&) const {
;     ...
;             for (int ai = 0; ai < 2; ++ai)
; #pragma unroll
;                 for (int m = 0; m < 4; ++m) { const int r = row0 + ai * HALF + m * 16;
;                     const u32x4 zw = zv[ai * 4 + m];
;                     const f32x4 a0 = acc[ai][bj][m][0] * sc[bj][0], a1 = acc[ai][bj][m][1] * sc[bj][1];
;                     u32x4 w;
;                     w.x = cvt_pk_bf16(a0[0] * silu_f(bf_lo(zw.x)), a0[1] * silu_f(bf_hi(zw.x)));
;                     w.y = cvt_pk_bf16(a0[2] * silu_f(bf_lo(zw.y)), a0[3] * silu_f(bf_hi(zw.y)));
;                     w.z = cvt_pk_bf16(a1[0] * silu_f(bf_lo(zw.z)), a1[1] * silu_f(bf_hi(zw.z)));
;                     w.w = cvt_pk_bf16(a1[2] * silu_f(bf_lo(zw.w)), a1[3] * silu_f(bf_hi(zw.w)));
;                     *(u32x4*)(O + (size_t)r * DE + c) = w; } }
	s_nop 0
	v_add_f32_e32 v19, 1.0, v19
	v_rcp_f32_e32 v19, v19
	s_nop 0
	v_mul_f32_e32 v18, v19, v18
	v_mul_f32_e32 v15, v15, v18
	v_cvt_pk_bf16_f32 v14, v14, v15
	v_lshlrev_b32_e32 v15, 16, v79
	v_mul_f32_e32 v18, 0xbfb8aa3b, v15
	v_exp_f32_e32 v18, v18
	s_nop 0
	v_add_f32_e32 v18, 1.0, v18
	v_rcp_f32_e32 v18, v18
	s_nop 0
	v_mul_f32_e32 v15, v18, v15
	v_mul_f32_e32 v15, v16, v15
	v_and_b32_e32 v16, 0xffff0000, v79
	v_mul_f32_e32 v18, 0xbfb8aa3b, v16
	v_exp_f32_e32 v18, v18
	s_nop 0
	v_add_f32_e32 v18, 1.0, v18
	v_rcp_f32_e32 v18, v18
	s_nop 0
	v_mul_f32_e32 v16, v18, v16
	v_mul_f32_e32 v16, v17, v16
	v_cvt_pk_bf16_f32 v15, v15, v16
	v_lshlrev_b32_e32 v16, 16, v80
	v_mul_f32_e32 v17, 0xbfb8aa3b, v16
	v_exp_f32_e32 v17, v17
	s_nop 0
	v_add_f32_e32 v17, 1.0, v17
	v_rcp_f32_e32 v17, v17
	s_nop 0
	v_mul_f32_e32 v16, v17, v16
	v_mul_f32_e32 v10, v10, v16
	v_and_b32_e32 v16, 0xffff0000, v80
	v_mul_f32_e32 v17, 0xbfb8aa3b, v16
	v_exp_f32_e32 v17, v17
	s_nop 0
	v_add_f32_e32 v17, 1.0, v17
	v_rcp_f32_e32 v17, v17
	s_nop 0
	v_mul_f32_e32 v16, v17, v16
	v_mul_f32_e32 v11, v11, v16
	v_cvt_pk_bf16_f32 v16, v10, v11
	v_lshlrev_b32_e32 v10, 16, v81
	v_mul_f32_e32 v11, 0xbfb8aa3b, v10
	v_exp_f32_e32 v11, v11
	s_nop 0
	v_add_f32_e32 v11, 1.0, v11
	v_rcp_f32_e32 v11, v11
	s_nop 0
	v_mul_f32_e32 v10, v11, v10
	v_and_b32_e32 v11, 0xffff0000, v81
	v_mul_f32_e32 v10, v12, v10
	v_mul_f32_e32 v12, 0xbfb8aa3b, v11
	v_exp_f32_e32 v12, v12
	s_nop 0
	v_add_f32_e32 v12, 1.0, v12
	v_rcp_f32_e32 v12, v12
	s_nop 0
	v_mul_f32_e32 v11, v12, v11
	v_mul_f32_e32 v11, v13, v11
	v_cvt_pk_bf16_f32 v17, v10, v11
	v_lshlrev_b32_e32 v10, 16, v74
	v_mul_f32_e32 v11, 0xbfb8aa3b, v10
	v_exp_f32_e32 v11, v11
	global_store_dwordx4 v[114:115], v[14:17], off offset:256
	v_add_f32_e32 v11, 1.0, v11
	v_rcp_f32_e32 v11, v11
	s_nop 0
	v_mul_f32_e32 v10, v11, v10
	v_mul_f32_e32 v6, v6, v10
	v_and_b32_e32 v10, 0xffff0000, v74
	v_mul_f32_e32 v11, 0xbfb8aa3b, v10
	v_exp_f32_e32 v11, v11
	s_nop 0
	v_add_f32_e32 v11, 1.0, v11
	v_rcp_f32_e32 v11, v11
	s_nop 0
	v_mul_f32_e32 v10, v11, v10
	v_mul_f32_e32 v7, v7, v10
	v_cvt_pk_bf16_f32 v6, v6, v7
	v_lshlrev_b32_e32 v7, 16, v75
	v_mul_f32_e32 v10, 0xbfb8aa3b, v7
	v_exp_f32_e32 v10, v10
	s_nop 0
	v_add_f32_e32 v10, 1.0, v10
	v_rcp_f32_e32 v10, v10
	s_nop 0
	v_mul_f32_e32 v7, v10, v7
	v_mul_f32_e32 v7, v8, v7
	v_and_b32_e32 v8, 0xffff0000, v75
	v_mul_f32_e32 v10, 0xbfb8aa3b, v8
	v_exp_f32_e32 v10, v10
	s_nop 0
	v_add_f32_e32 v10, 1.0, v10
	v_rcp_f32_e32 v10, v10
	s_nop 0
	v_mul_f32_e32 v8, v10, v8
	v_mul_f32_e32 v8, v9, v8
	v_cvt_pk_bf16_f32 v7, v7, v8
	v_lshlrev_b32_e32 v8, 16, v76
	v_mul_f32_e32 v9, 0xbfb8aa3b, v8
	v_exp_f32_e32 v9, v9
	s_nop 0
	v_add_f32_e32 v9, 1.0, v9
	v_rcp_f32_e32 v9, v9
	s_nop 0
	v_mul_f32_e32 v8, v9, v8
	v_mul_f32_e32 v2, v2, v8
	v_and_b32_e32 v8, 0xffff0000, v76
	v_mul_f32_e32 v9, 0xbfb8aa3b, v8
	v_exp_f32_e32 v9, v9
	s_nop 0
	v_add_f32_e32 v9, 1.0, v9
	v_rcp_f32_e32 v9, v9
	s_nop 0
	v_mul_f32_e32 v8, v9, v8
	v_mul_f32_e32 v3, v3, v8
	v_cvt_pk_bf16_f32 v8, v2, v3
	v_lshlrev_b32_e32 v2, 16, v77
	v_mul_f32_e32 v3, 0xbfb8aa3b, v2
	v_exp_f32_e32 v3, v3
	s_nop 0
	v_add_f32_e32 v3, 1.0, v3
	v_rcp_f32_e32 v3, v3
	s_nop 0
	v_mul_f32_e32 v2, v3, v2
	v_and_b32_e32 v3, 0xffff0000, v77
	v_mul_f32_e32 v2, v4, v2
	v_mul_f32_e32 v4, 0xbfb8aa3b, v3
	v_exp_f32_e32 v4, v4
	s_nop 0
	v_add_f32_e32 v4, 1.0, v4
	v_rcp_f32_e32 v4, v4
	s_nop 0
	v_mul_f32_e32 v3, v4, v3
	v_mul_f32_e32 v3, v5, v3
	v_cvt_pk_bf16_f32 v9, v2, v3
	global_store_dwordx4 v[106:107], v[6:9], off offset:256
	s_cbranch_vccz .LBB0_596
	s_waitcnt vmcnt(0)
	s_cmpk_gt_u32 s14, 0xff
	s_mov_b64 s[36:37], s[96:97]
	s_cbranch_scc1 .LBB0_607
	s_barrier

; #define PG8_STAGE(bufoff, gbase, voff) do { _Pragma("unroll") for (int _i = 0; _i < 2; ++_i) \
;         __builtin_amdgcn_global_load_lds((const unsigned*)((const char*)(gbase) + (voff)[_i]), (LAS unsigned*)(lds + (bufoff) + ldsw + _i * 8192), 16, 0, 0); } while (0)
; #define PG8_LDA(dst, b, h) do { _Pragma("unroll") for (int m = 0; m < 4; ++m) _Pragma("unroll") for (int k = 0; k < 2; ++k) dst[m][k] = *(const LAS bf16x8*)(lds + PG8_SA(b, h) + aoff + m * 2048 + k * 1024); } while (0)
; #define PG8_LDB(dst, b, h) do { _Pragma("unroll") for (int n = 0; n < 2; ++n) _Pragma("unroll") for (int k = 0; k < 2; ++k) dst[n][k] = *(const LAS bf16x8*)(lds + PG8_SB(b, h) + boff + n * 2048 + k * 1024); } while (0)
; #define PG8_MMA(ai, bj, At, Bt) do { __builtin_amdgcn_s_setprio(1); _Pragma("unroll") for (int m = 0; m < 4; ++m) _Pragma("unroll") for (int n = 0; n < 2; ++n) _Pragma("unroll") for (int k = 0; k < 2; ++k) \
;         acc[ai][bj][m][n] = __builtin_amdgcn_mfma_f32_16x16x32_bf16(Bt[n][k], At[m][k], acc[ai][bj][m][n], 0, 0, 0); __builtin_amdgcn_s_setprio(0); } while (0)
; #define PG8_WAIT_V(n) asm volatile("s_waitcnt vmcnt(" #n ")" ::: "memory")
; #define PG8_WAIT_L(n) asm volatile("s_waitcnt lgkmcnt(" #n ")" ::: "memory")
; #define PG8_BAR __builtin_amdgcn_s_barrier()
; #define PG8_SCHED __builtin_amdgcn_sched_barrier(0)
; template <class Epi>
; __device__ __forceinline__ void gemm_phase(LAS unsigned char* lds, const Gemm g, const StaticOrder& S, const Epi& E) {
;     ...
;             PG8_LDB(B0, 0, 0); PG8_SCHED; PG8_LDA(At, 0, 0); PG8_STAGE(PG8_SA(1, 1), a1 + hstepA, voffA);
;             PG8_WAIT_L(8); PG8_BAR; PG8_WAIT_L(0); PG8_MMA(0, 0, At, B0); PG8_BAR; PG8_SCHED;
;             PG8_LDB(B1, 0, 1); PG8_STAGE(PG8_SB(0, 0), b2, voffB);
;             PG8_BAR; PG8_WAIT_L(0); PG8_MMA(0, 1, At, B1); PG8_BAR;
;             PG8_LDA(At, 0, 1); PG8_STAGE(PG8_SA(0, 0), a2, voffA);
;             PG8_BAR; PG8_WAIT_L(0); PG8_MMA(1, 0, At, B0); PG8_BAR; PG8_SCHED;
;             PG8_STAGE(PG8_SB(0, 1), b2 + hstepB, voffB);
;             PG8_WAIT_V(6); PG8_BAR; PG8_MMA(1, 1, At, B1); PG8_BAR;
.LBB0_796:
	s_add_u32 s4, s8, 0x103400
	s_addc_u32 s5, s9, 0
	s_cmp_eq_u32 s57, 60
	s_cselect_b32 s16, s38, s4
	s_cselect_b32 s17, s37, s5
	s_cselect_b32 s4, s49, s51
	s_cselect_b32 s5, s39, s56
	s_add_u32 s14, s16, 0x104400
	s_addc_u32 s15, s17, 0
	s_add_i32 s58, 0, 0x10000
	v_add_u32_e32 v102, s58, v245
	ds_read_b128 v[26:29], v102
	ds_read_b128 v[30:33], v102 offset:1024
	ds_read_b128 v[98:101], v102 offset:2048
	ds_read_b128 v[102:105], v102 offset:3072
	s_add_i32 m0, s22, 0xc000
	ds_read_b128 v[130:133], v247
	ds_read_b128 v[142:145], v247 offset:1024
	ds_read_b128 v[146:149], v247 offset:2048
	ds_read_b128 v[150:153], v247 offset:3072
	ds_read_b128 v[154:157], v247 offset:4096
	ds_read_b128 v[166:169], v247 offset:5120
	ds_read_b128 v[170:173], v247 offset:6144
	ds_read_b128 v[174:177], v247 offset:7168
	global_load_lds_dwordx4 v196, s[8:9]
	s_add_i32 m0, s22, 0xe000
	s_nop 0
	global_load_lds_dwordx4 v198, s[8:9]
	s_waitcnt lgkmcnt(8)
	s_barrier
	s_waitcnt lgkmcnt(0)
	v_mfma_f32_16x16x32_bf16 v[162:165], v[26:29], v[130:133], v[162:165]
	v_mfma_f32_16x16x32_bf16 v[158:161], v[98:101], v[130:133], v[158:161]
	v_mfma_f32_16x16x32_bf16 v[138:141], v[26:29], v[146:149], v[138:141]
	v_mfma_f32_16x16x32_bf16 v[134:137], v[98:101], v[146:149], v[134:137]
	v_mfma_f32_16x16x32_bf16 v[126:129], v[26:29], v[154:157], v[126:129]
	v_mfma_f32_16x16x32_bf16 v[122:125], v[98:101], v[154:157], v[122:125]
	v_mfma_f32_16x16x32_bf16 v[118:121], v[26:29], v[170:173], v[118:121]
	v_mfma_f32_16x16x32_bf16 v[114:117], v[98:101], v[170:173], v[114:117]
	v_mfma_f32_16x16x32_bf16 v[162:165], v[30:33], v[142:145], v[162:165]
	v_mfma_f32_16x16x32_bf16 v[158:161], v[102:105], v[142:145], v[158:161]
	v_mfma_f32_16x16x32_bf16 v[138:141], v[30:33], v[150:153], v[138:141]
	v_mfma_f32_16x16x32_bf16 v[134:137], v[102:105], v[150:153], v[134:137]
	v_mfma_f32_16x16x32_bf16 v[126:129], v[30:33], v[166:169], v[126:129]
	v_mfma_f32_16x16x32_bf16 v[122:125], v[102:105], v[166:169], v[122:125]
	v_mfma_f32_16x16x32_bf16 v[118:121], v[30:33], v[174:177], v[118:121]
	v_mfma_f32_16x16x32_bf16 v[114:117], v[102:105], v[174:177], v[114:117]
	s_barrier
	s_add_i32 s60, 0, 0x14000
	s_add_i32 s58, s58, s21
	v_add_u32_e32 v208, s60, v245
	s_add_u32 s100, s4, s6
	s_addc_u32 s101, s5, s7
	s_mov_b32 m0, s58
	ds_read_b128 v[184:187], v208
	ds_read_b128 v[200:203], v208 offset:1024
	ds_read_b128 v[204:207], v208 offset:2048
	ds_read_b128 v[208:211], v208 offset:3072
	global_load_lds_dwordx4 v0, s[4:5]
	s_add_i32 m0, s58, 0x2000
	s_nop 0
	global_load_lds_dwordx4 v188, s[4:5]
	s_barrier
	s_waitcnt lgkmcnt(0)
	v_mfma_f32_16x16x32_bf16 v[70:73], v[184:187], v[130:133], v[70:73]
	v_mfma_f32_16x16x32_bf16 v[66:69], v[204:207], v[130:133], v[66:69]
	v_mfma_f32_16x16x32_bf16 v[62:65], v[184:187], v[146:149], v[62:65]
	v_mfma_f32_16x16x32_bf16 v[58:61], v[204:207], v[146:149], v[58:61]
	v_mfma_f32_16x16x32_bf16 v[54:57], v[184:187], v[154:157], v[54:57]
	v_mfma_f32_16x16x32_bf16 v[50:53], v[204:207], v[154:157], v[50:53]
	v_mfma_f32_16x16x32_bf16 v[46:49], v[184:187], v[170:173], v[46:49]
	v_mfma_f32_16x16x32_bf16 v[42:45], v[204:207], v[170:173], v[42:45]
	v_mfma_f32_16x16x32_bf16 v[70:73], v[200:203], v[142:145], v[70:73]
	v_mfma_f32_16x16x32_bf16 v[66:69], v[208:211], v[142:145], v[66:69]
	v_mfma_f32_16x16x32_bf16 v[62:65], v[200:203], v[150:153], v[62:65]
	v_mfma_f32_16x16x32_bf16 v[58:61], v[208:211], v[150:153], v[58:61]
	v_mfma_f32_16x16x32_bf16 v[54:57], v[200:203], v[166:169], v[54:57]
	v_mfma_f32_16x16x32_bf16 v[50:53], v[208:211], v[166:169], v[50:53]
	v_mfma_f32_16x16x32_bf16 v[46:49], v[200:203], v[174:177], v[46:49]
	v_mfma_f32_16x16x32_bf16 v[42:45], v[208:211], v[174:177], v[42:45]
	s_mov_b32 m0, s22
	s_barrier
	ds_read_b128 v[130:133], v247 offset:16384
	ds_read_b128 v[142:145], v247 offset:17408
	ds_read_b128 v[146:149], v247 offset:18432
	ds_read_b128 v[150:153], v247 offset:19456
	ds_read_b128 v[154:157], v247 offset:20480
	ds_read_b128 v[166:169], v247 offset:21504
	ds_read_b128 v[170:173], v247 offset:22528
	ds_read_b128 v[174:177], v247 offset:23552
	global_load_lds_dwordx4 v192, s[16:17]
	s_mov_b32 m0, s23
	s_nop 0
	global_load_lds_dwordx4 v190, s[16:17]
	s_barrier
	s_waitcnt lgkmcnt(0)
	v_mfma_f32_16x16x32_bf16 v[110:113], v[26:29], v[130:133], v[110:113]
	v_mfma_f32_16x16x32_bf16 v[106:109], v[98:101], v[130:133], v[106:109]
	v_mfma_f32_16x16x32_bf16 v[94:97], v[26:29], v[146:149], v[94:97]
	v_mfma_f32_16x16x32_bf16 v[90:93], v[98:101], v[146:149], v[90:93]
	v_mfma_f32_16x16x32_bf16 v[86:89], v[26:29], v[154:157], v[86:89]
	v_mfma_f32_16x16x32_bf16 v[82:85], v[98:101], v[154:157], v[82:85]
	v_mfma_f32_16x16x32_bf16 v[26:29], v[26:29], v[170:173], v[78:81]
	v_mfma_f32_16x16x32_bf16 v[110:113], v[30:33], v[142:145], v[110:113]
	v_mfma_f32_16x16x32_bf16 v[106:109], v[102:105], v[142:145], v[106:109]
	v_mfma_f32_16x16x32_bf16 v[94:97], v[30:33], v[150:153], v[94:97]
	v_mfma_f32_16x16x32_bf16 v[90:93], v[102:105], v[150:153], v[90:93]
	v_mfma_f32_16x16x32_bf16 v[86:89], v[30:33], v[166:169], v[86:89]
	v_mfma_f32_16x16x32_bf16 v[82:85], v[102:105], v[166:169], v[82:85]
	v_mfma_f32_16x16x32_bf16 v[26:29], v[30:33], v[174:177], v[26:29]
	v_mfma_f32_16x16x32_bf16 v[30:33], v[98:101], v[170:173], v[74:77]
	v_mfma_f32_16x16x32_bf16 v[30:33], v[102:105], v[174:177], v[30:33]
	s_barrier
	s_add_u32 s58, s4, 0x100000
	s_addc_u32 s59, s5, 0
	s_add_i32 s60, s60, s21
	s_mov_b32 m0, s60
	s_nop 0
	global_load_lds_dwordx4 v0, s[58:59]
	s_add_i32 m0, s60, 0x2000
	s_nop 0
	global_load_lds_dwordx4 v188, s[58:59]
	s_waitcnt vmcnt(6)
	s_barrier
; #define PG8_STAGE(bufoff, gbase, voff) do { _Pragma("unroll") for (int _i = 0; _i < 2; ++_i) \
;         __builtin_amdgcn_global_load_lds((const unsigned*)((const char*)(gbase) + (voff)[_i]), (LAS unsigned*)(lds + (bufoff) + ldsw + _i * 8192), 16, 0, 0); } while (0)
; #define PG8_LDA(dst, b, h) do { _Pragma("unroll") for (int m = 0; m < 4; ++m) _Pragma("unroll") for (int k = 0; k < 2; ++k) dst[m][k] = *(const LAS bf16x8*)(lds + PG8_SA(b, h) + aoff + m * 2048 + k * 1024); } while (0)
; #define PG8_LDB(dst, b, h) do { _Pragma("unroll") for (int n = 0; n < 2; ++n) _Pragma("unroll") for (int k = 0; k < 2; ++k) dst[n][k] = *(const LAS bf16x8*)(lds + PG8_SB(b, h) + boff + n * 2048 + k * 1024); } while (0)
; #define PG8_MMA(ai, bj, At, Bt) do { __builtin_amdgcn_s_setprio(1); _Pragma("unroll") for (int m = 0; m < 4; ++m) _Pragma("unroll") for (int n = 0; n < 2; ++n) _Pragma("unroll") for (int k = 0; k < 2; ++k) \
;         acc[ai][bj][m][n] = __builtin_amdgcn_mfma_f32_16x16x32_bf16(Bt[n][k], At[m][k], acc[ai][bj][m][n], 0, 0, 0); __builtin_amdgcn_s_setprio(0); } while (0)
; #define PG8_WAIT_V(n) asm volatile("s_waitcnt vmcnt(" #n ")" ::: "memory")
; #define PG8_WAIT_L(n) asm volatile("s_waitcnt lgkmcnt(" #n ")" ::: "memory")
; #define PG8_BAR __builtin_amdgcn_s_barrier()
; #define PG8_SCHED __builtin_amdgcn_sched_barrier(0)
; template <class Epi>
; __device__ __forceinline__ void gemm_phase(LAS unsigned char* lds, const Gemm g, const StaticOrder& S, const Epi& E) {
;     ...
;             PG8_WAIT_V(6); PG8_BAR; PG8_MMA(1, 1, At, B1); PG8_BAR;
;             PG8_LDB(B0, 1, 0); PG8_SCHED; PG8_LDA(At, 1, 0); PG8_STAGE(PG8_SA(0, 1), a2 + hstepA, voffA);
;             PG8_WAIT_L(8); PG8_BAR; PG8_WAIT_L(0); PG8_MMA(0, 0, At, B0); PG8_BAR; PG8_SCHED;
;             PG8_LDB(B1, 1, 1); PG8_STAGE(PG8_SB(1, 0), b3, voffB);
;             PG8_BAR; PG8_WAIT_L(0); PG8_MMA(0, 1, At, B1); PG8_BAR;
;             PG8_LDA(At, 1, 1); PG8_STAGE(PG8_SA(1, 0), a3, voffA);
	v_mfma_f32_16x16x32_bf16 v[38:41], v[184:187], v[130:133], v[38:41]
	v_mfma_f32_16x16x32_bf16 v[34:37], v[204:207], v[130:133], v[34:37]
	v_mfma_f32_16x16x32_bf16 v[22:25], v[184:187], v[146:149], v[22:25]
	v_mfma_f32_16x16x32_bf16 v[18:21], v[204:207], v[146:149], v[18:21]
	v_mfma_f32_16x16x32_bf16 v[14:17], v[184:187], v[154:157], v[14:17]
	v_mfma_f32_16x16x32_bf16 v[10:13], v[204:207], v[154:157], v[10:13]
	v_mfma_f32_16x16x32_bf16 v[6:9], v[184:187], v[170:173], v[6:9]
	v_mfma_f32_16x16x32_bf16 v[2:5], v[204:207], v[170:173], v[2:5]
	v_mfma_f32_16x16x32_bf16 v[38:41], v[200:203], v[142:145], v[38:41]
	v_mfma_f32_16x16x32_bf16 v[34:37], v[208:211], v[142:145], v[34:37]
	v_mfma_f32_16x16x32_bf16 v[22:25], v[200:203], v[150:153], v[22:25]
	v_mfma_f32_16x16x32_bf16 v[18:21], v[208:211], v[150:153], v[18:21]
	v_mfma_f32_16x16x32_bf16 v[14:17], v[200:203], v[166:169], v[14:17]
	v_mfma_f32_16x16x32_bf16 v[10:13], v[208:211], v[166:169], v[10:13]
	v_mfma_f32_16x16x32_bf16 v[6:9], v[200:203], v[174:177], v[6:9]
	v_mfma_f32_16x16x32_bf16 v[2:5], v[208:211], v[174:177], v[2:5]
	s_add_i32 s58, 0, 0x18000
	v_add_u32_e32 v102, s58, v245
	s_barrier
	ds_read_b128 v[74:77], v102
	ds_read_b128 v[78:81], v102 offset:1024
	ds_read_b128 v[98:101], v102 offset:2048
	ds_read_b128 v[102:105], v102 offset:3072
	s_add_u32 s16, s16, 0x1000
	s_addc_u32 s17, s17, 0
	s_mov_b32 m0, s24
	ds_read_b128 v[130:133], v247 offset:32768
	ds_read_b128 v[142:145], v247 offset:33792
	ds_read_b128 v[146:149], v247 offset:34816
	ds_read_b128 v[150:153], v247 offset:35840
	ds_read_b128 v[154:157], v247 offset:36864
	ds_read_b128 v[166:169], v247 offset:37888
	ds_read_b128 v[170:173], v247 offset:38912
	ds_read_b128 v[174:177], v247 offset:39936
	global_load_lds_dwordx4 v192, s[16:17]
	s_mov_b32 m0, s25
	s_nop 0
	global_load_lds_dwordx4 v190, s[16:17]
	s_waitcnt lgkmcnt(8)
	s_barrier
	s_waitcnt lgkmcnt(0)
	v_mfma_f32_16x16x32_bf16 v[162:165], v[74:77], v[130:133], v[162:165]
	v_mfma_f32_16x16x32_bf16 v[158:161], v[98:101], v[130:133], v[158:161]
	v_mfma_f32_16x16x32_bf16 v[138:141], v[74:77], v[146:149], v[138:141]
	v_mfma_f32_16x16x32_bf16 v[134:137], v[98:101], v[146:149], v[134:137]
	v_mfma_f32_16x16x32_bf16 v[126:129], v[74:77], v[154:157], v[126:129]
	v_mfma_f32_16x16x32_bf16 v[122:125], v[98:101], v[154:157], v[122:125]
	v_mfma_f32_16x16x32_bf16 v[118:121], v[74:77], v[170:173], v[118:121]
	v_mfma_f32_16x16x32_bf16 v[114:117], v[98:101], v[170:173], v[114:117]
	v_mfma_f32_16x16x32_bf16 v[162:165], v[78:81], v[142:145], v[162:165]
	v_mfma_f32_16x16x32_bf16 v[158:161], v[102:105], v[142:145], v[158:161]
	v_mfma_f32_16x16x32_bf16 v[138:141], v[78:81], v[150:153], v[138:141]
	v_mfma_f32_16x16x32_bf16 v[134:137], v[102:105], v[150:153], v[134:137]
	v_mfma_f32_16x16x32_bf16 v[126:129], v[78:81], v[166:169], v[126:129]
	v_mfma_f32_16x16x32_bf16 v[122:125], v[102:105], v[166:169], v[122:125]
	v_mfma_f32_16x16x32_bf16 v[118:121], v[78:81], v[174:177], v[118:121]
	v_mfma_f32_16x16x32_bf16 v[114:117], v[102:105], v[174:177], v[114:117]
	s_barrier
	s_add_i32 s16, 0, 0x1c000
	s_add_i32 s17, s58, s21
	v_add_u32_e32 v208, s16, v245
	s_mov_b32 m0, s17
	ds_read_b128 v[184:187], v208
	ds_read_b128 v[200:203], v208 offset:1024
	ds_read_b128 v[204:207], v208 offset:2048
	ds_read_b128 v[208:211], v208 offset:3072
	global_load_lds_dwordx4 v0, s[100:101]
	s_add_i32 m0, s17, 0x2000
	s_nop 0
	global_load_lds_dwordx4 v188, s[100:101]
	s_barrier
	s_waitcnt lgkmcnt(0)
	v_mfma_f32_16x16x32_bf16 v[70:73], v[184:187], v[130:133], v[70:73]
	v_mfma_f32_16x16x32_bf16 v[66:69], v[204:207], v[130:133], v[66:69]
	v_mfma_f32_16x16x32_bf16 v[62:65], v[184:187], v[146:149], v[62:65]
	v_mfma_f32_16x16x32_bf16 v[58:61], v[204:207], v[146:149], v[58:61]
	v_mfma_f32_16x16x32_bf16 v[54:57], v[184:187], v[154:157], v[54:57]
	v_mfma_f32_16x16x32_bf16 v[50:53], v[204:207], v[154:157], v[50:53]
	v_mfma_f32_16x16x32_bf16 v[46:49], v[184:187], v[170:173], v[46:49]
	v_mfma_f32_16x16x32_bf16 v[42:45], v[204:207], v[170:173], v[42:45]
	v_mfma_f32_16x16x32_bf16 v[70:73], v[200:203], v[142:145], v[70:73]
	v_mfma_f32_16x16x32_bf16 v[66:69], v[208:211], v[142:145], v[66:69]
	v_mfma_f32_16x16x32_bf16 v[62:65], v[200:203], v[150:153], v[62:65]
	v_mfma_f32_16x16x32_bf16 v[58:61], v[208:211], v[150:153], v[58:61]
	v_mfma_f32_16x16x32_bf16 v[54:57], v[200:203], v[166:169], v[54:57]
	v_mfma_f32_16x16x32_bf16 v[50:53], v[208:211], v[166:169], v[50:53]
	v_mfma_f32_16x16x32_bf16 v[46:49], v[200:203], v[174:177], v[46:49]
	v_mfma_f32_16x16x32_bf16 v[42:45], v[208:211], v[174:177], v[42:45]
	s_mov_b32 m0, s26
	s_barrier
	ds_read_b128 v[130:133], v247 offset:49152
	ds_read_b128 v[142:145], v247 offset:50176
	ds_read_b128 v[146:149], v247 offset:51200
	ds_read_b128 v[150:153], v247 offset:52224
	ds_read_b128 v[154:157], v247 offset:53248
	ds_read_b128 v[166:169], v247 offset:54272
	ds_read_b128 v[170:173], v247 offset:55296
	ds_read_b128 v[174:177], v247 offset:56320
	global_load_lds_dwordx4 v192, s[14:15]
	s_mov_b32 m0, s27
	s_nop 0
	global_load_lds_dwordx4 v190, s[14:15]
	s_barrier
; #define PG8_STAGE(bufoff, gbase, voff) do { _Pragma("unroll") for (int _i = 0; _i < 2; ++_i) \
;         __builtin_amdgcn_global_load_lds((const unsigned*)((const char*)(gbase) + (voff)[_i]), (LAS unsigned*)(lds + (bufoff) + ldsw + _i * 8192), 16, 0, 0); } while (0)
; #define PG8_MMA(ai, bj, At, Bt) do { __builtin_amdgcn_s_setprio(1); _Pragma("unroll") for (int m = 0; m < 4; ++m) _Pragma("unroll") for (int n = 0; n < 2; ++n) _Pragma("unroll") for (int k = 0; k < 2; ++k) \
;         acc[ai][bj][m][n] = __builtin_amdgcn_mfma_f32_16x16x32_bf16(Bt[n][k], At[m][k], acc[ai][bj][m][n], 0, 0, 0); __builtin_amdgcn_s_setprio(0); } while (0)
; #define PG8_WAIT_V(n) asm volatile("s_waitcnt vmcnt(" #n ")" ::: "memory")
; #define PG8_WAIT_L(n) asm volatile("s_waitcnt lgkmcnt(" #n ")" ::: "memory")
; #define PG8_BAR __builtin_amdgcn_s_barrier()
; #define PG8_SCHED __builtin_amdgcn_sched_barrier(0)
; template <class Epi>
; __device__ __forceinline__ void gemm_phase(LAS unsigned char* lds, const Gemm g, const StaticOrder& S, const Epi& E) {
;     ...
;             PG8_BAR; PG8_WAIT_L(0); PG8_MMA(1, 0, At, B0); PG8_BAR; PG8_SCHED;
;             PG8_STAGE(PG8_SB(1, 1), b3 + hstepB, voffB);
;             PG8_WAIT_V(6); PG8_BAR; PG8_MMA(1, 1, At, B1); PG8_BAR;
;     __device__ __forceinline__ void operator()(const f32x4 (&acc)[2][2][4][2], const Unit& u, int wr, int wc, int fr, int fq, const Pre&) const {
;         const int row0 = u.pm * BM + wr * 64 + fr, col0 = u.pn * BM + wc * 32 + 8 * fq;
;         f32x4 bs[2][2];
; #pragma unroll
;         for (int bj = 0; bj < 2; ++bj) { bs[bj][0] = *(const f32x4*)(bias + col0 + bj * HALF); bs[bj][1] = *(const f32x4*)(bias + col0 + bj * HALF + 4); }
; #pragma unroll
;         for (int bj = 0; bj < 2; ++bj) { const int c = col0 + bj * HALF;
; #pragma unroll
;             for (int ai = 0; ai < 2; ++ai) { u32x4 zv[4], gv[4];
; #pragma unroll
;                 for (int m = 0; m < 4; ++m) { const int r = row0 + ai * HALF + m * 16; zv[m] = *(const u32x4*)(Z + (size_t)r * DE2 + c); gv[m] = *(const u32x4*)(Gm + (size_t)(c >> 4) * GSTR + r * 16 + (c & 15)); }
	s_waitcnt lgkmcnt(0)
	v_mfma_f32_16x16x32_bf16 v[110:113], v[74:77], v[130:133], v[110:113]
	v_mfma_f32_16x16x32_bf16 v[94:97], v[74:77], v[146:149], v[94:97]
	v_mfma_f32_16x16x32_bf16 v[86:89], v[74:77], v[154:157], v[86:89]
	v_mfma_f32_16x16x32_bf16 v[26:29], v[74:77], v[170:173], v[26:29]
	v_mfma_f32_16x16x32_bf16 v[110:113], v[78:81], v[142:145], v[110:113]
	v_mfma_f32_16x16x32_bf16 v[106:109], v[98:101], v[130:133], v[106:109]
	v_mfma_f32_16x16x32_bf16 v[94:97], v[78:81], v[150:153], v[94:97]
	v_mfma_f32_16x16x32_bf16 v[90:93], v[98:101], v[146:149], v[90:93]
	v_mfma_f32_16x16x32_bf16 v[86:89], v[78:81], v[166:169], v[86:89]
	v_mfma_f32_16x16x32_bf16 v[82:85], v[98:101], v[154:157], v[82:85]
	v_mfma_f32_16x16x32_bf16 v[78:81], v[78:81], v[174:177], v[26:29]
	v_mfma_f32_16x16x32_bf16 v[26:29], v[98:101], v[170:173], v[30:33]
	v_mfma_f32_16x16x32_bf16 v[106:109], v[102:105], v[142:145], v[106:109]
	v_mfma_f32_16x16x32_bf16 v[90:93], v[102:105], v[150:153], v[90:93]
	v_mfma_f32_16x16x32_bf16 v[82:85], v[102:105], v[166:169], v[82:85]
	v_mfma_f32_16x16x32_bf16 v[74:77], v[102:105], v[174:177], v[26:29]
	s_barrier
	s_add_u32 s4, s4, 0x100080
	s_addc_u32 s5, s5, 0
	s_add_i32 s14, s16, s21
	s_mov_b32 m0, s14
	s_nop 0
	global_load_lds_dwordx4 v0, s[4:5]
	s_add_i32 m0, s14, 0x2000
	s_nop 0
	global_load_lds_dwordx4 v188, s[4:5]
	s_waitcnt vmcnt(6)
	s_barrier
	v_mfma_f32_16x16x32_bf16 v[26:29], v[184:187], v[130:133], v[38:41]
	v_mfma_f32_16x16x32_bf16 v[38:41], v[200:203], v[142:145], v[26:29]
	v_mfma_f32_16x16x32_bf16 v[26:29], v[204:207], v[130:133], v[34:37]
	v_mfma_f32_16x16x32_bf16 v[22:25], v[184:187], v[146:149], v[22:25]
	v_mfma_f32_16x16x32_bf16 v[18:21], v[204:207], v[146:149], v[18:21]
	v_mfma_f32_16x16x32_bf16 v[14:17], v[184:187], v[154:157], v[14:17]
	v_mfma_f32_16x16x32_bf16 v[10:13], v[204:207], v[154:157], v[10:13]
	v_mfma_f32_16x16x32_bf16 v[6:9], v[184:187], v[170:173], v[6:9]
	v_mfma_f32_16x16x32_bf16 v[2:5], v[204:207], v[170:173], v[2:5]
	v_mfma_f32_16x16x32_bf16 v[34:37], v[208:211], v[142:145], v[26:29]
	v_mfma_f32_16x16x32_bf16 v[22:25], v[200:203], v[150:153], v[22:25]
	v_mfma_f32_16x16x32_bf16 v[18:21], v[208:211], v[150:153], v[18:21]
	v_mfma_f32_16x16x32_bf16 v[14:17], v[200:203], v[166:169], v[14:17]
	v_mfma_f32_16x16x32_bf16 v[10:13], v[208:211], v[166:169], v[10:13]
	v_mfma_f32_16x16x32_bf16 v[6:9], v[200:203], v[174:177], v[6:9]
	v_mfma_f32_16x16x32_bf16 v[2:5], v[208:211], v[174:177], v[2:5]
	s_add_i32 s57, s57, 2
	s_add_u32 s51, s51, 0x100
	s_addc_u32 s56, s56, 0
	s_add_u32 s8, s8, 0x208800
	s_addc_u32 s9, s9, 0
	s_cmp_gt_u32 s57, 61
	s_barrier
	s_cbranch_scc0 .LBB0_796
	v_lshl_or_b32 v200, s36, 8, v246
	v_ashrrev_i32_e32 v201, 31, v200
	v_lshl_add_u32 v224, s35, 8, v244
	v_lshlrev_b64 v[204:205], 1, v[200:201]
	v_ashrrev_i32_e32 v225, 31, v224
	v_ashrrev_i32_e32 v130, 4, v200
	v_lshl_add_u64 v[222:223], s[46:47], 0, v[204:205]
	v_lshlrev_b64 v[202:203], 14, v[224:225]
	v_lshl_add_u64 v[30:31], v[200:201], 2, s[10:11]
	v_mad_i64_i32 v[220:221], s[4:5], v130, s94, v[194:195]
	v_lshl_add_u64 v[130:131], v[222:223], 0, v[202:203]
	global_load_dwordx4 v[98:101], v[30:31], off offset:16
	global_load_dwordx4 v[102:105], v[30:31], off
	global_load_dwordx4 v[26:29], v[30:31], off offset:528
	s_nop 0
	global_load_dwordx4 v[30:33], v[30:31], off offset:512
	v_or_b32_e32 v226, 48, v224
	global_load_dwordx4 v[170:173], v[130:131], off
	v_lshlrev_b32_e32 v142, 4, v226
	v_ashrrev_i32_e32 v143, 31, v142
	v_lshlrev_b64 v[218:219], 1, v[142:143]
	v_lshl_add_u64 v[142:143], v[220:221], 0, v[218:219]
	global_load_dwordx4 v[142:145], v[142:143], off
	v_lshlrev_b32_e32 v130, 4, v224
	v_ashrrev_i32_e32 v131, 31, v130
	v_lshlrev_b64 v[206:207], 1, v[130:131]
	v_lshl_add_u64 v[130:131], v[220:221], 0, v[206:207]
	global_load_dwordx4 v[174:177], v[130:131], off
	v_or_b32_e32 v230, 16, v224
	v_ashrrev_i32_e32 v231, 31, v230
	v_lshlrev_b64 v[210:211], 14, v[230:231]
	v_lshl_add_u64 v[130:131], v[222:223], 0, v[210:211]
	global_load_dwordx4 v[154:157], v[130:131], off
	v_lshlrev_b32_e32 v130, 4, v230
	v_ashrrev_i32_e32 v131, 31, v130
	v_or_b32_e32 v228, 32, v224
	v_lshlrev_b64 v[208:209], 1, v[130:131]
	v_ashrrev_i32_e32 v229, 31, v228
	v_lshl_add_u64 v[130:131], v[220:221], 0, v[208:209]
	v_lshlrev_b64 v[214:215], 14, v[228:229]
	global_load_dwordx4 v[166:169], v[130:131], off
	v_lshl_add_u64 v[130:131], v[222:223], 0, v[214:215]
	global_load_dwordx4 v[146:149], v[130:131], off
	v_lshlrev_b32_e32 v130, 4, v228
	v_ashrrev_i32_e32 v131, 31, v130
	v_lshlrev_b64 v[212:213], 1, v[130:131]
	v_ashrrev_i32_e32 v227, 31, v226
	v_lshl_add_u64 v[130:131], v[220:221], 0, v[212:213]
	v_lshlrev_b64 v[216:217], 14, v[226:227]
	global_load_dwordx4 v[150:153], v[130:131], off
	v_lshl_add_u64 v[130:131], v[222:223], 0, v[216:217]
	global_load_dwordx4 v[130:133], v[130:131], off
	s_and_b64 vcc, exec, s[40:41]
	s_mov_b32 s35, s50
	s_mov_b32 s36, s48
	s_mov_b64 s[8:9], s[54:55]
	s_mov_b64 s[14:15], s[52:53]
	s_waitcnt vmcnt(0)
; __device__ __forceinline__ unsigned cvt_pk_bf16(float lo, float hi) { unsigned r; asm volatile("v_cvt_pk_bf16_f32 %0, %1, %2" : "=v"(r) : "v"(lo), "v"(hi)); return r; }
; __device__ __forceinline__ float bf_lo(unsigned w) { return __uint_as_float(w << 16); }
; __device__ __forceinline__ float bf_hi(unsigned w) { return __uint_as_float(w & 0xffff0000u); }
;     __device__ __forceinline__ void operator()(const f32x4 (&acc)[2][2][4][2], const Unit& u, int wr, int wc, int fr, int fq, const Pre&) const {
;     ...
;         for (int bj = 0; bj < 2; ++bj) { const int c = col0 + bj * HALF;
; #pragma unroll
;             for (int ai = 0; ai < 2; ++ai) { u32x4 zv[4], gv[4];
; #pragma unroll
;                 for (int m = 0; m < 4; ++m) { const int r = row0 + ai * HALF + m * 16; zv[m] = *(const u32x4*)(Z + (size_t)r * DE2 + c); gv[m] = *(const u32x4*)(Gm + (size_t)(c >> 4) * GSTR + r * 16 + (c & 15)); }
; #pragma unroll
;                 for (int m = 0; m < 4; ++m) { const int r = row0 + ai * HALF + m * 16;
;                     const u32x4 zw = zv[m], gw = gv[m];
;                     const f32x4 a0 = acc[ai][bj][m][0] + bs[bj][0], a1 = acc[ai][bj][m][1] + bs[bj][1];
;                     u32x4 w;
;                     w.x = cvt_pk_bf16(glu_gate_f(bf_lo(gw.x), a0[0], bf_lo(zw.x)), glu_gate_f(bf_hi(gw.x), a0[1], bf_hi(zw.x)));
;                     w.y = cvt_pk_bf16(glu_gate_f(bf_lo(gw.y), a0[2], bf_lo(zw.y)), glu_gate_f(bf_hi(gw.y), a0[3], bf_hi(zw.y)));
;                     w.z = cvt_pk_bf16(glu_gate_f(bf_lo(gw.z), a1[0], bf_lo(zw.z)), glu_gate_f(bf_hi(gw.z), a1[1], bf_hi(zw.z)));
;                     w.w = cvt_pk_bf16(glu_gate_f(bf_lo(gw.w), a1[2], bf_lo(zw.w)), glu_gate_f(bf_hi(gw.w), a1[3], bf_hi(zw.w)));
;                     *(u32x4*)(O + (size_t)r * DE + c) = w; } } }
	v_pk_add_f32 v[134:135], v[134:135], v[98:99]
	v_pk_add_f32 v[184:185], v[162:163], v[102:103]
	v_pk_add_f32 v[162:163], v[160:161], v[100:101]
	v_pk_add_f32 v[160:161], v[158:159], v[98:99]
	v_mul_f32_e32 v158, 0xbfb8aa3b, v184
	v_lshlrev_b32_e32 v186, 16, v170
	v_mul_f32_e32 v159, 0xbfb8aa3b, v186
	v_exp_f32_e32 v158, v158
	v_exp_f32_e32 v159, v159
	v_and_b32_e32 v170, 0xffff0000, v170
	v_pk_add_f32 v[164:165], v[164:165], v[104:105]
	v_mul_f32_e32 v160, 0xbfb8aa3b, v160
	v_pk_add_f32 v[158:159], v[158:159], 1.0 op_sel_hi:[1,0]
	v_mul_f32_e32 v164, 0xbfb8aa3b, v164
	v_mul_f32_e32 v158, v158, v159
	v_rcp_f32_e32 v158, v158
	v_lshlrev_b32_e32 v187, 16, v174
	v_mul_f32_e32 v184, v187, v186
	v_mul_f32_e32 v159, 0xbfb8aa3b, v170
	v_mul_f32_e32 v184, v184, v158
	v_mul_f32_e32 v158, 0xbfb8aa3b, v185
	v_exp_f32_e32 v158, v158
	v_exp_f32_e32 v159, v159
	v_and_b32_e32 v174, 0xffff0000, v174
	v_mul_f32_e32 v170, v174, v170
	v_mul_f32_e32 v162, 0xbfb8aa3b, v162
	v_pk_add_f32 v[158:159], v[158:159], 1.0 op_sel_hi:[1,0]
	v_pk_add_f32 v[138:139], v[138:139], v[102:103]
	v_mul_f32_e32 v158, v158, v159
	v_rcp_f32_e32 v158, v158
	v_lshlrev_b32_e32 v159, 16, v171
	v_and_b32_e32 v171, 0xffff0000, v171
	v_mul_f32_e32 v138, 0xbfb8aa3b, v138
	v_mul_f32_e32 v158, v170, v158
	v_cvt_pk_bf16_f32 v158, v184, v158
	v_exp_f32_e32 v184, v164
	v_mul_f32_e32 v164, 0xbfb8aa3b, v159
	v_exp_f32_e32 v185, v164
	v_lshlrev_b32_e32 v170, 16, v175
	v_mul_f32_e32 v159, v170, v159
	v_and_b32_e32 v170, 0xffff0000, v175
	v_pk_add_f32 v[184:185], v[184:185], 1.0 op_sel_hi:[1,0]
	v_mul_f32_e32 v170, v170, v171
	v_mul_f32_e32 v164, v184, v185
	v_rcp_f32_e32 v164, v164
	v_pk_add_f32 v[140:141], v[140:141], v[104:105]
	v_mul_f32_e32 v134, 0xbfb8aa3b, v134
	v_mul_f32_e32 v140, 0xbfb8aa3b, v140
	v_mul_f32_e32 v159, v159, v164
	v_mul_f32_e32 v164, 0xbfb8aa3b, v165
	v_mul_f32_e32 v165, 0xbfb8aa3b, v171
	v_exp_f32_e32 v164, v164
	v_exp_f32_e32 v165, v165
	v_lshlrev_b32_e32 v171, 16, v176
	v_pk_add_f32 v[136:137], v[136:137], v[100:101]
	v_pk_add_f32 v[126:127], v[126:127], v[102:103]
	v_pk_add_f32 v[164:165], v[164:165], 1.0 op_sel_hi:[1,0]
	v_mul_f32_e32 v126, 0xbfb8aa3b, v126
	v_mul_f32_e32 v164, v164, v165
	v_rcp_f32_e32 v164, v164
	v_pk_add_f32 v[128:129], v[128:129], v[104:105]
	v_pk_add_f32 v[122:123], v[122:123], v[98:99]
	v_mul_f32_e32 v128, 0xbfb8aa3b, v128
	v_mul_f32_e32 v164, v170, v164
	v_lshlrev_b32_e32 v170, 16, v172
	v_cvt_pk_bf16_f32 v159, v159, v164
	v_exp_f32_e32 v164, v160
	v_mul_f32_e32 v160, 0xbfb8aa3b, v170
	v_exp_f32_e32 v165, v160
	v_mul_f32_e32 v160, v171, v170
	v_and_b32_e32 v170, 0xffff0000, v172
	v_mul_f32_e32 v122, 0xbfb8aa3b, v122
	v_pk_add_f32 v[164:165], v[164:165], 1.0 op_sel_hi:[1,0]
	v_pk_add_f32 v[124:125], v[124:125], v[100:101]
	v_mul_f32_e32 v164, v164, v165
	v_rcp_f32_e32 v164, v164
	v_and_b32_e32 v165, 0xffff0000, v176
	v_mul_f32_e32 v165, v165, v170
	v_pk_add_f32 v[118:119], v[118:119], v[102:103]
	v_mul_f32_e32 v164, v160, v164
	v_mul_f32_e32 v160, 0xbfb8aa3b, v161
	v_mul_f32_e32 v161, 0xbfb8aa3b, v170
	v_exp_f32_e32 v160, v160
	v_exp_f32_e32 v161, v161
	v_lshlrev_b32_e32 v170, 16, v177
	v_mul_f32_e32 v118, 0xbfb8aa3b, v118
	v_pk_add_f32 v[120:121], v[120:121], v[104:105]
	v_pk_add_f32 v[160:161], v[160:161], 1.0 op_sel_hi:[1,0]
	v_mul_f32_e32 v120, 0xbfb8aa3b, v120
	v_mul_f32_e32 v160, v160, v161
	v_rcp_f32_e32 v160, v160
	v_lshlrev_b32_e32 v161, 16, v173
	v_pk_add_f32 v[114:115], v[114:115], v[98:99]
	v_pk_add_f32 v[116:117], v[116:117], v[100:101]
	v_mul_f32_e32 v160, v165, v160
	v_cvt_pk_bf16_f32 v160, v164, v160
	v_exp_f32_e32 v164, v162
	v_mul_f32_e32 v162, 0xbfb8aa3b, v161
	v_exp_f32_e32 v165, v162
	v_mul_f32_e32 v161, v170, v161
	v_mul_f32_e32 v114, 0xbfb8aa3b, v114
	v_add_u32_e32 v176, 0x80, v224
	v_pk_add_f32 v[164:165], v[164:165], 1.0 op_sel_hi:[1,0]
	v_add_u32_e32 v170, 0xb0, v224
	v_mul_f32_e32 v162, v164, v165
	v_rcp_f32_e32 v162, v162
	v_and_b32_e32 v165, 0xffff0000, v173
	v_and_b32_e32 v164, 0xffff0000, v177
	v_mul_f32_e32 v164, v164, v165
	v_mul_f32_e32 v161, v161, v162
	v_mul_f32_e32 v162, 0xbfb8aa3b, v163
	v_mul_f32_e32 v163, 0xbfb8aa3b, v165
	v_exp_f32_e32 v162, v162
	v_exp_f32_e32 v163, v163
	v_ashrrev_i32_e32 v177, 31, v176
	v_pk_add_f32 v[110:111], v[110:111], v[102:103]
	v_add_u32_e32 v174, 0x90, v224
	v_pk_add_f32 v[162:163], v[162:163], 1.0 op_sel_hi:[1,0]
	v_mul_f32_e32 v110, 0xbfb8aa3b, v110
	v_mul_f32_e32 v162, v162, v163
	v_rcp_f32_e32 v162, v162
	v_exp_f32_e32 v184, v110
	v_ashrrev_i32_e32 v175, 31, v174
	v_add_u32_e32 v172, 0xa0, v224
	v_mul_f32_e32 v162, v164, v162
	v_cvt_pk_bf16_f32 v161, v161, v162
	v_lshlrev_b64 v[162:163], 13, v[224:225]
	v_lshl_add_u64 v[162:163], s[44:45], 0, v[162:163]
	v_lshl_add_u64 v[162:163], v[162:163], 0, v[204:205]
	global_store_dwordx4 v[162:163], v[158:161], off
	v_ashrrev_i32_e32 v173, 31, v172
	v_ashrrev_i32_e32 v171, 31, v170
	v_lshlrev_b32_e32 v160, 16, v154
	v_exp_f32_e32 v158, v138
	v_mul_f32_e32 v138, 0xbfb8aa3b, v160
	v_exp_f32_e32 v159, v138
	v_lshlrev_b32_e32 v161, 16, v166
	v_mul_f32_e32 v138, v161, v160
	v_and_b32_e32 v154, 0xffff0000, v154
	v_pk_add_f32 v[158:159], v[158:159], 1.0 op_sel_hi:[1,0]
	v_lshlrev_b64 v[160:161], 14, v[172:173]
	v_mul_f32_e32 v158, v158, v159
	v_rcp_f32_e32 v158, v158
	v_and_b32_e32 v159, 0xffff0000, v166
	v_pk_add_f32 v[112:113], v[112:113], v[104:105]
	v_pk_add_f32 v[106:107], v[106:107], v[98:99]
	v_mul_f32_e32 v158, v138, v158
	v_mul_f32_e32 v138, 0xbfb8aa3b, v139
	v_mul_f32_e32 v139, 0xbfb8aa3b, v154
	v_exp_f32_e32 v138, v138
	v_exp_f32_e32 v139, v139
	v_mul_f32_e32 v154, v159, v154
	v_mul_f32_e32 v112, 0xbfb8aa3b, v112
; __device__ __forceinline__ unsigned cvt_pk_bf16(float lo, float hi) { unsigned r; asm volatile("v_cvt_pk_bf16_f32 %0, %1, %2" : "=v"(r) : "v"(lo), "v"(hi)); return r; }
; __device__ __forceinline__ float bf_lo(unsigned w) { return __uint_as_float(w << 16); }
; __device__ __forceinline__ float bf_hi(unsigned w) { return __uint_as_float(w & 0xffff0000u); }
;     __device__ __forceinline__ void operator()(const f32x4 (&acc)[2][2][4][2], const Unit& u, int wr, int wc, int fr, int fq, const Pre&) const {
;     ...
;         for (int bj = 0; bj < 2; ++bj) { const int c = col0 + bj * HALF;
; #pragma unroll
;             for (int ai = 0; ai < 2; ++ai) { u32x4 zv[4], gv[4];
; #pragma unroll
;                 for (int m = 0; m < 4; ++m) { const int r = row0 + ai * HALF + m * 16; zv[m] = *(const u32x4*)(Z + (size_t)r * DE2 + c); gv[m] = *(const u32x4*)(Gm + (size_t)(c >> 4) * GSTR + r * 16 + (c & 15)); }
; #pragma unroll
;                 for (int m = 0; m < 4; ++m) { const int r = row0 + ai * HALF + m * 16;
;                     const u32x4 zw = zv[m], gw = gv[m];
;                     const f32x4 a0 = acc[ai][bj][m][0] + bs[bj][0], a1 = acc[ai][bj][m][1] + bs[bj][1];
;                     u32x4 w;
;                     w.x = cvt_pk_bf16(glu_gate_f(bf_lo(gw.x), a0[0], bf_lo(zw.x)), glu_gate_f(bf_hi(gw.x), a0[1], bf_hi(zw.x)));
;                     w.y = cvt_pk_bf16(glu_gate_f(bf_lo(gw.y), a0[2], bf_lo(zw.y)), glu_gate_f(bf_hi(gw.y), a0[3], bf_hi(zw.y)));
;                     w.z = cvt_pk_bf16(glu_gate_f(bf_lo(gw.z), a1[0], bf_lo(zw.z)), glu_gate_f(bf_hi(gw.z), a1[1], bf_hi(zw.z)));
;                     w.w = cvt_pk_bf16(glu_gate_f(bf_lo(gw.w), a1[2], bf_lo(zw.w)), glu_gate_f(bf_hi(gw.w), a1[3], bf_hi(zw.w)));
;                     *(u32x4*)(O + (size_t)r * DE + c) = w; } } }
	v_mul_f32_e32 v106, 0xbfb8aa3b, v106
	v_pk_add_f32 v[138:139], v[138:139], 1.0 op_sel_hi:[1,0]
	v_pk_add_f32 v[108:109], v[108:109], v[100:101]
	v_mul_f32_e32 v138, v138, v139
	v_rcp_f32_e32 v138, v138
	v_lshlrev_b32_e32 v139, 16, v155
	v_and_b32_e32 v155, 0xffff0000, v155
	v_pk_add_f32 v[94:95], v[94:95], v[102:103]
	v_mul_f32_e32 v138, v154, v138
	v_cvt_pk_bf16_f32 v138, v158, v138
	v_exp_f32_e32 v158, v140
	v_mul_f32_e32 v140, 0xbfb8aa3b, v139
	v_exp_f32_e32 v159, v140
	v_lshlrev_b32_e32 v154, 16, v167
	v_mul_f32_e32 v139, v154, v139
	v_and_b32_e32 v154, 0xffff0000, v167
	v_pk_add_f32 v[158:159], v[158:159], 1.0 op_sel_hi:[1,0]
	v_mul_f32_e32 v154, v154, v155
	v_mul_f32_e32 v140, v158, v159
	v_rcp_f32_e32 v140, v140
	v_lshlrev_b64 v[166:167], 14, v[170:171]
	v_mul_f32_e32 v94, 0xbfb8aa3b, v94
	v_pk_add_f32 v[96:97], v[96:97], v[104:105]
	v_mul_f32_e32 v139, v139, v140
	v_mul_f32_e32 v140, 0xbfb8aa3b, v141
	v_mul_f32_e32 v141, 0xbfb8aa3b, v155
	v_exp_f32_e32 v140, v140
	v_exp_f32_e32 v141, v141
	v_lshlrev_b32_e32 v155, 16, v168
	v_mul_f32_e32 v96, 0xbfb8aa3b, v96
	v_pk_add_f32 v[90:91], v[90:91], v[98:99]
	v_pk_add_f32 v[140:141], v[140:141], 1.0 op_sel_hi:[1,0]
	v_mul_f32_e32 v90, 0xbfb8aa3b, v90
	v_mul_f32_e32 v140, v140, v141
	v_rcp_f32_e32 v140, v140
	v_pk_add_f32 v[92:93], v[92:93], v[100:101]
	v_pk_add_f32 v[86:87], v[86:87], v[102:103]
	v_pk_add_f32 v[88:89], v[88:89], v[104:105]
	v_mul_f32_e32 v140, v154, v140
	v_lshlrev_b32_e32 v154, 16, v156
	v_cvt_pk_bf16_f32 v139, v139, v140
	v_exp_f32_e32 v140, v134
	v_mul_f32_e32 v134, 0xbfb8aa3b, v154
	v_exp_f32_e32 v141, v134
	v_mul_f32_e32 v134, v155, v154
	v_and_b32_e32 v154, 0xffff0000, v156
	v_mul_f32_e32 v86, 0xbfb8aa3b, v86
	v_pk_add_f32 v[140:141], v[140:141], 1.0 op_sel_hi:[1,0]
	v_mul_f32_e32 v88, 0xbfb8aa3b, v88
	v_mul_f32_e32 v140, v140, v141
	v_rcp_f32_e32 v140, v140
	v_and_b32_e32 v141, 0xffff0000, v168
	v_mul_f32_e32 v141, v141, v154
	v_pk_add_f32 v[82:83], v[82:83], v[98:99]
	v_mul_f32_e32 v140, v134, v140
	v_mul_f32_e32 v134, 0xbfb8aa3b, v135
	v_mul_f32_e32 v135, 0xbfb8aa3b, v154
	v_exp_f32_e32 v134, v134
	v_exp_f32_e32 v135, v135
	v_lshlrev_b32_e32 v154, 16, v169
	v_mul_f32_e32 v82, 0xbfb8aa3b, v82
	v_pk_add_f32 v[84:85], v[84:85], v[100:101]
	v_pk_add_f32 v[134:135], v[134:135], 1.0 op_sel_hi:[1,0]
	v_pk_add_f32 v[78:79], v[78:79], v[102:103]
	v_mul_f32_e32 v134, v134, v135
	v_rcp_f32_e32 v134, v134
	v_mul_f32_e32 v78, 0xbfb8aa3b, v78
	v_pk_add_f32 v[80:81], v[80:81], v[104:105]
	v_pk_add_f32 v[74:75], v[74:75], v[98:99]
	v_mul_f32_e32 v134, v141, v134
	v_lshlrev_b32_e32 v141, 16, v157
	v_cvt_pk_bf16_f32 v140, v140, v134
	v_mul_f32_e32 v134, 0xbfb8aa3b, v136
	v_mul_f32_e32 v135, 0xbfb8aa3b, v141
	v_exp_f32_e32 v134, v134
	v_exp_f32_e32 v135, v135
	v_mul_f32_e32 v136, v154, v141
	v_and_b32_e32 v154, 0xffff0000, v157
	v_and_b32_e32 v141, 0xffff0000, v169
	v_pk_add_f32 v[134:135], v[134:135], 1.0 op_sel_hi:[1,0]
	v_lshlrev_b64 v[156:157], 14, v[174:175]
	v_mul_f32_e32 v134, v134, v135
	v_rcp_f32_e32 v134, v134
	v_mul_f32_e32 v135, 0xbfb8aa3b, v154
	v_exp_f32_e32 v135, v135
	v_mul_f32_e32 v80, 0xbfb8aa3b, v80
	v_mul_f32_e32 v136, v136, v134
	v_mul_f32_e32 v134, 0xbfb8aa3b, v137
	v_exp_f32_e32 v134, v134
	v_mul_f32_e32 v137, v141, v154
	v_mul_f32_e32 v74, 0xbfb8aa3b, v74
	v_pk_add_f32 v[76:77], v[76:77], v[100:101]
	v_pk_add_f32 v[134:135], v[134:135], 1.0 op_sel_hi:[1,0]
	v_pk_add_f32 v[70:71], v[70:71], v[30:31]
	v_mul_f32_e32 v134, v134, v135
	v_rcp_f32_e32 v134, v134
	v_mul_f32_e32 v70, 0xbfb8aa3b, v70
	v_pk_add_f32 v[72:73], v[72:73], v[32:33]
	v_pk_add_f32 v[66:67], v[66:67], v[26:27]
	v_mul_f32_e32 v134, v137, v134
	v_cvt_pk_bf16_f32 v141, v136, v134
	v_lshlrev_b64 v[134:135], 13, v[230:231]
	v_lshl_add_u64 v[134:135], s[44:45], 0, v[134:135]
	v_lshlrev_b32_e32 v136, 16, v146
	v_lshl_add_u64 v[154:155], v[134:135], 0, v[204:205]
	v_exp_f32_e32 v134, v126
	v_mul_f32_e32 v126, 0xbfb8aa3b, v136
	v_exp_f32_e32 v135, v126
	v_lshlrev_b32_e32 v137, 16, v150
	v_mul_f32_e32 v126, v137, v136
	v_and_b32_e32 v136, 0xffff0000, v146
	v_pk_add_f32 v[134:135], v[134:135], 1.0 op_sel_hi:[1,0]
	global_store_dwordx4 v[154:155], v[138:141], off
	v_mul_f32_e32 v134, v134, v135
	v_rcp_f32_e32 v134, v134
	v_and_b32_e32 v135, 0xffff0000, v150
	v_mul_f32_e32 v135, v135, v136
	v_mul_f32_e32 v72, 0xbfb8aa3b, v72
	v_mul_f32_e32 v134, v126, v134
	v_mul_f32_e32 v126, 0xbfb8aa3b, v127
	v_mul_f32_e32 v127, 0xbfb8aa3b, v136
	v_exp_f32_e32 v126, v126
	v_exp_f32_e32 v127, v127
	v_lshlrev_b32_e32 v136, 16, v151
	v_mul_f32_e32 v66, 0xbfb8aa3b, v66
	v_pk_add_f32 v[68:69], v[68:69], v[28:29]
	v_pk_add_f32 v[126:127], v[126:127], 1.0 op_sel_hi:[1,0]
	v_pk_add_f32 v[62:63], v[62:63], v[30:31]
	v_mul_f32_e32 v126, v126, v127
	v_rcp_f32_e32 v126, v126
	v_lshlrev_b32_e32 v127, 16, v147
	v_mul_f32_e32 v62, 0xbfb8aa3b, v62
	v_pk_add_f32 v[64:65], v[64:65], v[32:33]
	v_mul_f32_e32 v126, v135, v126
	v_cvt_pk_bf16_f32 v126, v134, v126
	v_exp_f32_e32 v134, v128
	v_mul_f32_e32 v128, 0xbfb8aa3b, v127
	v_exp_f32_e32 v135, v128
	v_mul_f32_e32 v127, v136, v127
	v_mul_f32_e32 v64, 0xbfb8aa3b, v64
	v_pk_add_f32 v[58:59], v[58:59], v[26:27]
	v_pk_add_f32 v[134:135], v[134:135], 1.0 op_sel_hi:[1,0]
	v_mul_f32_e32 v58, 0xbfb8aa3b, v58
	v_mul_f32_e32 v128, v134, v135
	v_rcp_f32_e32 v128, v128
	v_and_b32_e32 v135, 0xffff0000, v147
	v_and_b32_e32 v134, 0xffff0000, v151
	v_mul_f32_e32 v134, v134, v135
	v_mul_f32_e32 v127, v127, v128
	v_mul_f32_e32 v128, 0xbfb8aa3b, v129
	v_mul_f32_e32 v129, 0xbfb8aa3b, v135
	v_exp_f32_e32 v128, v128
	v_exp_f32_e32 v129, v129
	v_lshlrev_b32_e32 v135, 16, v152
	v_lshlrev_b64 v[150:151], 14, v[176:177]
; __device__ __forceinline__ unsigned cvt_pk_bf16(float lo, float hi) { unsigned r; asm volatile("v_cvt_pk_bf16_f32 %0, %1, %2" : "=v"(r) : "v"(lo), "v"(hi)); return r; }
; __device__ __forceinline__ float bf_lo(unsigned w) { return __uint_as_float(w << 16); }
; __device__ __forceinline__ float bf_hi(unsigned w) { return __uint_as_float(w & 0xffff0000u); }
;     __device__ __forceinline__ void operator()(const f32x4 (&acc)[2][2][4][2], const Unit& u, int wr, int wc, int fr, int fq, const Pre&) const {
;     ...
;         for (int bj = 0; bj < 2; ++bj) { const int c = col0 + bj * HALF;
; #pragma unroll
;             for (int ai = 0; ai < 2; ++ai) { u32x4 zv[4], gv[4];
; #pragma unroll
;                 for (int m = 0; m < 4; ++m) { const int r = row0 + ai * HALF + m * 16; zv[m] = *(const u32x4*)(Z + (size_t)r * DE2 + c); gv[m] = *(const u32x4*)(Gm + (size_t)(c >> 4) * GSTR + r * 16 + (c & 15)); }
; #pragma unroll
;                 for (int m = 0; m < 4; ++m) { const int r = row0 + ai * HALF + m * 16;
;                     const u32x4 zw = zv[m], gw = gv[m];
;                     const f32x4 a0 = acc[ai][bj][m][0] + bs[bj][0], a1 = acc[ai][bj][m][1] + bs[bj][1];
;                     u32x4 w;
;                     w.x = cvt_pk_bf16(glu_gate_f(bf_lo(gw.x), a0[0], bf_lo(zw.x)), glu_gate_f(bf_hi(gw.x), a0[1], bf_hi(zw.x)));
;                     w.y = cvt_pk_bf16(glu_gate_f(bf_lo(gw.y), a0[2], bf_lo(zw.y)), glu_gate_f(bf_hi(gw.y), a0[3], bf_hi(zw.y)));
;                     w.z = cvt_pk_bf16(glu_gate_f(bf_lo(gw.z), a1[0], bf_lo(zw.z)), glu_gate_f(bf_hi(gw.z), a1[1], bf_hi(zw.z)));
;                     w.w = cvt_pk_bf16(glu_gate_f(bf_lo(gw.w), a1[2], bf_lo(zw.w)), glu_gate_f(bf_hi(gw.w), a1[3], bf_hi(zw.w)));
;                     *(u32x4*)(O + (size_t)r * DE + c) = w; } } }
	v_pk_add_f32 v[60:61], v[60:61], v[28:29]
	v_pk_add_f32 v[128:129], v[128:129], 1.0 op_sel_hi:[1,0]
	v_pk_add_f32 v[54:55], v[54:55], v[30:31]
	v_mul_f32_e32 v128, v128, v129
	v_rcp_f32_e32 v128, v128
	v_mul_f32_e32 v54, 0xbfb8aa3b, v54
	v_pk_add_f32 v[56:57], v[56:57], v[32:33]
	v_pk_add_f32 v[50:51], v[50:51], v[26:27]
	v_mul_f32_e32 v128, v134, v128
	v_lshlrev_b32_e32 v134, 16, v148
	v_cvt_pk_bf16_f32 v127, v127, v128
	v_exp_f32_e32 v128, v122
	v_mul_f32_e32 v122, 0xbfb8aa3b, v134
	v_exp_f32_e32 v129, v122
	v_mul_f32_e32 v122, v135, v134
	v_and_b32_e32 v134, 0xffff0000, v148
	v_mul_f32_e32 v56, 0xbfb8aa3b, v56
	v_pk_add_f32 v[128:129], v[128:129], 1.0 op_sel_hi:[1,0]
	v_mul_f32_e32 v50, 0xbfb8aa3b, v50
	v_mul_f32_e32 v128, v128, v129
	v_rcp_f32_e32 v128, v128
	v_and_b32_e32 v129, 0xffff0000, v152
	v_mul_f32_e32 v129, v129, v134
	v_pk_add_f32 v[52:53], v[52:53], v[28:29]
	v_mul_f32_e32 v128, v122, v128
	v_mul_f32_e32 v122, 0xbfb8aa3b, v123
	v_mul_f32_e32 v123, 0xbfb8aa3b, v134
	v_exp_f32_e32 v122, v122
	v_exp_f32_e32 v123, v123
	v_lshlrev_b32_e32 v134, 16, v153
	v_pk_add_f32 v[46:47], v[46:47], v[30:31]
	v_pk_add_f32 v[48:49], v[48:49], v[32:33]
	v_pk_add_f32 v[122:123], v[122:123], 1.0 op_sel_hi:[1,0]
	v_mul_f32_e32 v46, 0xbfb8aa3b, v46
	v_mul_f32_e32 v122, v122, v123
	v_rcp_f32_e32 v122, v122
	v_mul_f32_e32 v48, 0xbfb8aa3b, v48
	v_pk_add_f32 v[42:43], v[42:43], v[26:27]
	v_pk_add_f32 v[44:45], v[44:45], v[28:29]
	v_mul_f32_e32 v122, v129, v122
	v_lshlrev_b32_e32 v129, 16, v149
	v_cvt_pk_bf16_f32 v128, v128, v122
	v_mul_f32_e32 v122, 0xbfb8aa3b, v124
	v_mul_f32_e32 v123, 0xbfb8aa3b, v129
	v_exp_f32_e32 v122, v122
	v_exp_f32_e32 v123, v123
	v_mul_f32_e32 v124, v134, v129
	v_and_b32_e32 v134, 0xffff0000, v149
	v_and_b32_e32 v129, 0xffff0000, v153
	v_pk_add_f32 v[122:123], v[122:123], 1.0 op_sel_hi:[1,0]
	v_mul_f32_e32 v42, 0xbfb8aa3b, v42
	v_mul_f32_e32 v122, v122, v123
	v_rcp_f32_e32 v122, v122
	v_mul_f32_e32 v123, 0xbfb8aa3b, v134
	v_exp_f32_e32 v123, v123
	v_pk_add_f32 v[38:39], v[38:39], v[30:31]
	v_mul_f32_e32 v124, v124, v122
	v_mul_f32_e32 v122, 0xbfb8aa3b, v125
	v_exp_f32_e32 v122, v122
	v_mul_f32_e32 v125, v129, v134
	v_mul_f32_e32 v38, 0xbfb8aa3b, v38
	v_pk_add_f32 v[40:41], v[40:41], v[32:33]
	v_pk_add_f32 v[122:123], v[122:123], 1.0 op_sel_hi:[1,0]
	v_mul_f32_e32 v40, 0xbfb8aa3b, v40
	v_mul_f32_e32 v122, v122, v123
	v_rcp_f32_e32 v122, v122
	v_pk_add_f32 v[34:35], v[34:35], v[26:27]
	v_pk_add_f32 v[36:37], v[36:37], v[28:29]
	v_mul_f32_e32 v34, 0xbfb8aa3b, v34
	v_mul_f32_e32 v122, v125, v122
	v_cvt_pk_bf16_f32 v129, v124, v122
	v_lshlrev_b64 v[122:123], 13, v[228:229]
	v_lshl_add_u64 v[122:123], s[44:45], 0, v[122:123]
	v_lshlrev_b32_e32 v124, 16, v130
	v_lshl_add_u64 v[146:147], v[122:123], 0, v[204:205]
	v_exp_f32_e32 v122, v118
	v_mul_f32_e32 v118, 0xbfb8aa3b, v124
	v_exp_f32_e32 v123, v118
	v_lshlrev_b32_e32 v125, 16, v142
	v_mul_f32_e32 v118, v125, v124
	v_and_b32_e32 v124, 0xffff0000, v130
	v_pk_add_f32 v[122:123], v[122:123], 1.0 op_sel_hi:[1,0]
	global_store_dwordx4 v[146:147], v[126:129], off
	v_mul_f32_e32 v122, v122, v123
	v_rcp_f32_e32 v122, v122
	v_and_b32_e32 v123, 0xffff0000, v142
	v_mul_f32_e32 v123, v123, v124
	v_pk_add_f32 v[22:23], v[22:23], v[30:31]
	v_mul_f32_e32 v122, v118, v122
	v_mul_f32_e32 v118, 0xbfb8aa3b, v119
	v_mul_f32_e32 v119, 0xbfb8aa3b, v124
	v_exp_f32_e32 v118, v118
	v_exp_f32_e32 v119, v119
	v_lshlrev_b32_e32 v124, 16, v143
	v_mul_f32_e32 v22, 0xbfb8aa3b, v22
	v_pk_add_f32 v[24:25], v[24:25], v[32:33]
	v_pk_add_f32 v[118:119], v[118:119], 1.0 op_sel_hi:[1,0]
	v_mul_f32_e32 v24, 0xbfb8aa3b, v24
	v_mul_f32_e32 v118, v118, v119
	v_rcp_f32_e32 v118, v118
	v_lshlrev_b32_e32 v119, 16, v131
	v_pk_add_f32 v[18:19], v[18:19], v[26:27]
	v_pk_add_f32 v[20:21], v[20:21], v[28:29]
	v_mul_f32_e32 v118, v123, v118
	v_cvt_pk_bf16_f32 v118, v122, v118
	v_exp_f32_e32 v122, v120
	v_mul_f32_e32 v120, 0xbfb8aa3b, v119
	v_exp_f32_e32 v123, v120
	v_mul_f32_e32 v119, v124, v119
	v_mul_f32_e32 v18, 0xbfb8aa3b, v18
	v_pk_add_f32 v[14:15], v[14:15], v[30:31]
	v_pk_add_f32 v[122:123], v[122:123], 1.0 op_sel_hi:[1,0]
	v_mul_f32_e32 v14, 0xbfb8aa3b, v14
	v_mul_f32_e32 v120, v122, v123
	v_rcp_f32_e32 v120, v120
	v_and_b32_e32 v123, 0xffff0000, v131
	v_and_b32_e32 v122, 0xffff0000, v143
	v_mul_f32_e32 v122, v122, v123
	v_mul_f32_e32 v119, v119, v120
	v_mul_f32_e32 v120, 0xbfb8aa3b, v121
	v_mul_f32_e32 v121, 0xbfb8aa3b, v123
	v_exp_f32_e32 v120, v120
	v_exp_f32_e32 v121, v121
	v_lshlrev_b32_e32 v123, 16, v144
	v_pk_add_f32 v[16:17], v[16:17], v[32:33]
	v_pk_add_f32 v[10:11], v[10:11], v[26:27]
	v_pk_add_f32 v[120:121], v[120:121], 1.0 op_sel_hi:[1,0]
	v_mul_f32_e32 v16, 0xbfb8aa3b, v16
	v_mul_f32_e32 v120, v120, v121
	v_rcp_f32_e32 v120, v120
	v_mul_f32_e32 v10, 0xbfb8aa3b, v10
	v_pk_add_f32 v[12:13], v[12:13], v[28:29]
	v_pk_add_f32 v[6:7], v[6:7], v[30:31]
	v_mul_f32_e32 v120, v122, v120
	v_lshlrev_b32_e32 v122, 16, v132
	v_cvt_pk_bf16_f32 v119, v119, v120
	v_exp_f32_e32 v120, v114
	v_mul_f32_e32 v114, 0xbfb8aa3b, v122
	v_exp_f32_e32 v121, v114
	v_mul_f32_e32 v114, v123, v122
	v_and_b32_e32 v122, 0xffff0000, v132
	v_mul_f32_e32 v6, 0xbfb8aa3b, v6
	v_pk_add_f32 v[120:121], v[120:121], 1.0 op_sel_hi:[1,0]
	v_pk_add_f32 v[8:9], v[8:9], v[32:33]
	v_mul_f32_e32 v120, v120, v121
	v_rcp_f32_e32 v120, v120
	v_and_b32_e32 v121, 0xffff0000, v144
	v_mul_f32_e32 v121, v121, v122
	v_mul_f32_e32 v8, 0xbfb8aa3b, v8
	v_mul_f32_e32 v120, v114, v120
	v_mul_f32_e32 v114, 0xbfb8aa3b, v115
	v_mul_f32_e32 v115, 0xbfb8aa3b, v122
	v_exp_f32_e32 v114, v114
	v_exp_f32_e32 v115, v115
	v_lshlrev_b32_e32 v122, 16, v145
	v_pk_add_f32 v[2:3], v[2:3], v[26:27]
; __device__ __forceinline__ unsigned cvt_pk_bf16(float lo, float hi) { unsigned r; asm volatile("v_cvt_pk_bf16_f32 %0, %1, %2" : "=v"(r) : "v"(lo), "v"(hi)); return r; }
; __device__ __forceinline__ float bf_lo(unsigned w) { return __uint_as_float(w << 16); }
; __device__ __forceinline__ float bf_hi(unsigned w) { return __uint_as_float(w & 0xffff0000u); }
;     __device__ __forceinline__ void operator()(const f32x4 (&acc)[2][2][4][2], const Unit& u, int wr, int wc, int fr, int fq, const Pre&) const {
;     ...
;         for (int bj = 0; bj < 2; ++bj) { const int c = col0 + bj * HALF;
; #pragma unroll
;             for (int ai = 0; ai < 2; ++ai) { u32x4 zv[4], gv[4];
; #pragma unroll
;                 for (int m = 0; m < 4; ++m) { const int r = row0 + ai * HALF + m * 16; zv[m] = *(const u32x4*)(Z + (size_t)r * DE2 + c); gv[m] = *(const u32x4*)(Gm + (size_t)(c >> 4) * GSTR + r * 16 + (c & 15)); }
; #pragma unroll
;                 for (int m = 0; m < 4; ++m) { const int r = row0 + ai * HALF + m * 16;
;                     const u32x4 zw = zv[m], gw = gv[m];
;                     const f32x4 a0 = acc[ai][bj][m][0] + bs[bj][0], a1 = acc[ai][bj][m][1] + bs[bj][1];
;                     u32x4 w;
;                     w.x = cvt_pk_bf16(glu_gate_f(bf_lo(gw.x), a0[0], bf_lo(zw.x)), glu_gate_f(bf_hi(gw.x), a0[1], bf_hi(zw.x)));
;                     w.y = cvt_pk_bf16(glu_gate_f(bf_lo(gw.y), a0[2], bf_lo(zw.y)), glu_gate_f(bf_hi(gw.y), a0[3], bf_hi(zw.y)));
;                     w.z = cvt_pk_bf16(glu_gate_f(bf_lo(gw.z), a1[0], bf_lo(zw.z)), glu_gate_f(bf_hi(gw.z), a1[1], bf_hi(zw.z)));
;                     w.w = cvt_pk_bf16(glu_gate_f(bf_lo(gw.w), a1[2], bf_lo(zw.w)), glu_gate_f(bf_hi(gw.w), a1[3], bf_hi(zw.w)));
;                     *(u32x4*)(O + (size_t)r * DE + c) = w; } } }
	v_pk_add_f32 v[4:5], v[4:5], v[28:29]
	v_pk_add_f32 v[114:115], v[114:115], 1.0 op_sel_hi:[1,0]
	v_mul_f32_e32 v2, 0xbfb8aa3b, v2
	v_mul_f32_e32 v114, v114, v115
	v_rcp_f32_e32 v114, v114
	s_nop 0
	v_mul_f32_e32 v114, v121, v114
	v_lshlrev_b32_e32 v121, 16, v133
	v_cvt_pk_bf16_f32 v120, v120, v114
	v_mul_f32_e32 v114, 0xbfb8aa3b, v116
	v_mul_f32_e32 v115, 0xbfb8aa3b, v121
	v_exp_f32_e32 v114, v114
	v_exp_f32_e32 v115, v115
	v_mul_f32_e32 v116, v122, v121
	v_and_b32_e32 v122, 0xffff0000, v133
	v_and_b32_e32 v121, 0xffff0000, v145
	v_pk_add_f32 v[114:115], v[114:115], 1.0 op_sel_hi:[1,0]
	s_nop 0
	v_mul_f32_e32 v114, v114, v115
	v_rcp_f32_e32 v114, v114
	v_mul_f32_e32 v115, 0xbfb8aa3b, v122
	v_exp_f32_e32 v115, v115
	v_mul_f32_e32 v116, v116, v114
	v_mul_f32_e32 v114, 0xbfb8aa3b, v117
	v_exp_f32_e32 v114, v114
	v_mul_f32_e32 v117, v121, v122
	v_pk_add_f32 v[114:115], v[114:115], 1.0 op_sel_hi:[1,0]
	s_nop 0
	v_mul_f32_e32 v114, v114, v115
	v_rcp_f32_e32 v114, v114
	s_nop 0
	v_mul_f32_e32 v114, v117, v114
	v_cvt_pk_bf16_f32 v121, v116, v114
	v_lshlrev_b64 v[114:115], 13, v[226:227]
	v_lshl_add_u64 v[114:115], s[44:45], 0, v[114:115]
	v_lshl_add_u64 v[148:149], v[114:115], 0, v[204:205]
	global_store_dwordx4 v[148:149], v[118:121], off
	v_lshl_add_u64 v[114:115], v[222:223], 0, v[150:151]
	global_load_dwordx4 v[138:141], v[114:115], off
	v_lshlrev_b32_e32 v118, 4, v170
	v_ashrrev_i32_e32 v119, 31, v118
	v_lshlrev_b64 v[168:169], 1, v[118:119]
	v_lshl_add_u64 v[118:119], v[220:221], 0, v[168:169]
	global_load_dwordx4 v[118:121], v[118:119], off
	v_lshlrev_b32_e32 v114, 4, v176
	v_ashrrev_i32_e32 v115, 31, v114
	v_lshlrev_b64 v[152:153], 1, v[114:115]
	v_lshl_add_u64 v[114:115], v[220:221], 0, v[152:153]
	global_load_dwordx4 v[142:145], v[114:115], off
	v_lshl_add_u64 v[114:115], v[222:223], 0, v[156:157]
	global_load_dwordx4 v[130:133], v[114:115], off
	v_lshlrev_b32_e32 v114, 4, v174
	v_ashrrev_i32_e32 v115, 31, v114
	v_lshlrev_b64 v[158:159], 1, v[114:115]
	v_lshl_add_u64 v[114:115], v[220:221], 0, v[158:159]
	global_load_dwordx4 v[134:137], v[114:115], off
	v_lshl_add_u64 v[114:115], v[222:223], 0, v[160:161]
	global_load_dwordx4 v[122:125], v[114:115], off
	v_lshlrev_b32_e32 v114, 4, v172
	v_ashrrev_i32_e32 v115, 31, v114
	v_lshlrev_b64 v[164:165], 1, v[114:115]
	v_lshl_add_u64 v[114:115], v[220:221], 0, v[164:165]
	global_load_dwordx4 v[126:129], v[114:115], off
	v_lshl_add_u64 v[114:115], v[222:223], 0, v[166:167]
	global_load_dwordx4 v[114:117], v[114:115], off
	s_waitcnt vmcnt(0)
	v_lshlrev_b32_e32 v186, 16, v138
	v_mul_f32_e32 v110, 0xbfb8aa3b, v186
	v_exp_f32_e32 v185, v110
	v_and_b32_e32 v138, 0xffff0000, v138
	v_pk_add_f32 v[184:185], v[184:185], 1.0 op_sel_hi:[1,0]
	s_nop 0
	v_mul_f32_e32 v184, v184, v185
	v_rcp_f32_e32 v184, v184
	v_lshlrev_b32_e32 v187, 16, v142
	v_mul_f32_e32 v110, v187, v186
	v_mul_f32_e32 v184, v110, v184
	v_mul_f32_e32 v110, 0xbfb8aa3b, v111
	v_mul_f32_e32 v111, 0xbfb8aa3b, v138
	v_exp_f32_e32 v110, v110
	v_exp_f32_e32 v111, v111
	v_and_b32_e32 v142, 0xffff0000, v142
	v_mul_f32_e32 v138, v142, v138
	v_pk_add_f32 v[110:111], v[110:111], 1.0 op_sel_hi:[1,0]
	s_nop 0
	v_mul_f32_e32 v110, v110, v111
	v_rcp_f32_e32 v110, v110
	v_lshlrev_b32_e32 v111, 16, v139
	v_and_b32_e32 v139, 0xffff0000, v139
	v_mul_f32_e32 v110, v138, v110
	v_cvt_pk_bf16_f32 v110, v184, v110
	v_exp_f32_e32 v184, v112
	v_mul_f32_e32 v112, 0xbfb8aa3b, v111
	v_exp_f32_e32 v185, v112
	v_lshlrev_b32_e32 v138, 16, v143
	v_mul_f32_e32 v111, v138, v111
	v_and_b32_e32 v138, 0xffff0000, v143
	v_pk_add_f32 v[184:185], v[184:185], 1.0 op_sel_hi:[1,0]
	v_mul_f32_e32 v138, v138, v139
	v_mul_f32_e32 v112, v184, v185
	v_rcp_f32_e32 v112, v112
	s_nop 0
	v_mul_f32_e32 v111, v111, v112
	v_mul_f32_e32 v112, 0xbfb8aa3b, v113
	v_mul_f32_e32 v113, 0xbfb8aa3b, v139
	v_exp_f32_e32 v112, v112
	v_exp_f32_e32 v113, v113
	v_lshlrev_b32_e32 v139, 16, v144
	v_pk_add_f32 v[112:113], v[112:113], 1.0 op_sel_hi:[1,0]
	s_nop 0
	v_mul_f32_e32 v112, v112, v113
	v_rcp_f32_e32 v112, v112
	s_nop 0
	v_mul_f32_e32 v112, v138, v112
	v_lshlrev_b32_e32 v138, 16, v140
	v_cvt_pk_bf16_f32 v111, v111, v112
	v_exp_f32_e32 v112, v106
	v_mul_f32_e32 v106, 0xbfb8aa3b, v138
	v_exp_f32_e32 v113, v106
	v_mul_f32_e32 v106, v139, v138
	v_and_b32_e32 v138, 0xffff0000, v140
	v_pk_add_f32 v[112:113], v[112:113], 1.0 op_sel_hi:[1,0]
	s_nop 0
	v_mul_f32_e32 v112, v112, v113
	v_rcp_f32_e32 v112, v112
	v_and_b32_e32 v113, 0xffff0000, v144
	v_mul_f32_e32 v113, v113, v138
	v_mul_f32_e32 v112, v106, v112
	v_mul_f32_e32 v106, 0xbfb8aa3b, v107
	v_mul_f32_e32 v107, 0xbfb8aa3b, v138
	v_exp_f32_e32 v106, v106
	v_exp_f32_e32 v107, v107
	v_lshlrev_b32_e32 v138, 16, v145
	v_pk_add_f32 v[106:107], v[106:107], 1.0 op_sel_hi:[1,0]
	s_nop 0
	v_mul_f32_e32 v106, v106, v107
	v_rcp_f32_e32 v106, v106
	s_nop 0
	v_mul_f32_e32 v106, v113, v106
	v_lshlrev_b32_e32 v113, 16, v141
	v_cvt_pk_bf16_f32 v112, v112, v106
	v_mul_f32_e32 v106, 0xbfb8aa3b, v108
	v_mul_f32_e32 v107, 0xbfb8aa3b, v113
	v_exp_f32_e32 v106, v106
	v_exp_f32_e32 v107, v107
	v_mul_f32_e32 v108, v138, v113
	v_and_b32_e32 v138, 0xffff0000, v141
	v_and_b32_e32 v113, 0xffff0000, v145
	v_pk_add_f32 v[106:107], v[106:107], 1.0 op_sel_hi:[1,0]
	s_nop 0
	v_mul_f32_e32 v106, v106, v107
	v_rcp_f32_e32 v106, v106
	v_mul_f32_e32 v107, 0xbfb8aa3b, v138
	v_exp_f32_e32 v107, v107
	v_mul_f32_e32 v108, v108, v106
	v_mul_f32_e32 v106, 0xbfb8aa3b, v109
	v_exp_f32_e32 v106, v106
	v_mul_f32_e32 v109, v113, v138
	v_pk_add_f32 v[106:107], v[106:107], 1.0 op_sel_hi:[1,0]
	s_nop 0
	v_mul_f32_e32 v106, v106, v107
	v_rcp_f32_e32 v106, v106
	s_nop 0
	v_mul_f32_e32 v106, v109, v106
; __device__ __forceinline__ unsigned cvt_pk_bf16(float lo, float hi) { unsigned r; asm volatile("v_cvt_pk_bf16_f32 %0, %1, %2" : "=v"(r) : "v"(lo), "v"(hi)); return r; }
; __device__ __forceinline__ float bf_lo(unsigned w) { return __uint_as_float(w << 16); }
; __device__ __forceinline__ float bf_hi(unsigned w) { return __uint_as_float(w & 0xffff0000u); }
;     __device__ __forceinline__ void operator()(const f32x4 (&acc)[2][2][4][2], const Unit& u, int wr, int wc, int fr, int fq, const Pre&) const {
;     ...
;         for (int bj = 0; bj < 2; ++bj) { const int c = col0 + bj * HALF;
; #pragma unroll
;             for (int ai = 0; ai < 2; ++ai) { u32x4 zv[4], gv[4];
; #pragma unroll
;                 for (int m = 0; m < 4; ++m) { const int r = row0 + ai * HALF + m * 16; zv[m] = *(const u32x4*)(Z + (size_t)r * DE2 + c); gv[m] = *(const u32x4*)(Gm + (size_t)(c >> 4) * GSTR + r * 16 + (c & 15)); }
; #pragma unroll
;                 for (int m = 0; m < 4; ++m) { const int r = row0 + ai * HALF + m * 16;
;                     const u32x4 zw = zv[m], gw = gv[m];
;                     const f32x4 a0 = acc[ai][bj][m][0] + bs[bj][0], a1 = acc[ai][bj][m][1] + bs[bj][1];
;                     u32x4 w;
;                     w.x = cvt_pk_bf16(glu_gate_f(bf_lo(gw.x), a0[0], bf_lo(zw.x)), glu_gate_f(bf_hi(gw.x), a0[1], bf_hi(zw.x)));
;                     w.y = cvt_pk_bf16(glu_gate_f(bf_lo(gw.y), a0[2], bf_lo(zw.y)), glu_gate_f(bf_hi(gw.y), a0[3], bf_hi(zw.y)));
;                     w.z = cvt_pk_bf16(glu_gate_f(bf_lo(gw.z), a1[0], bf_lo(zw.z)), glu_gate_f(bf_hi(gw.z), a1[1], bf_hi(zw.z)));
;                     w.w = cvt_pk_bf16(glu_gate_f(bf_lo(gw.w), a1[2], bf_lo(zw.w)), glu_gate_f(bf_hi(gw.w), a1[3], bf_hi(zw.w)));
;                     *(u32x4*)(O + (size_t)r * DE + c) = w; } } }
	v_cvt_pk_bf16_f32 v113, v108, v106
	v_lshlrev_b64 v[106:107], 13, v[176:177]
	v_lshl_add_u64 v[106:107], s[44:45], 0, v[106:107]
	v_lshl_add_u64 v[106:107], v[106:107], 0, v[204:205]
	global_store_dwordx4 v[106:107], v[110:113], off
	v_exp_f32_e32 v108, v94
	s_nop 0
	v_lshlrev_b32_e32 v110, 16, v130
	v_mul_f32_e32 v94, 0xbfb8aa3b, v110
	v_exp_f32_e32 v109, v94
	v_lshlrev_b32_e32 v111, 16, v134
	v_mul_f32_e32 v94, v111, v110
	v_and_b32_e32 v110, 0xffff0000, v130
	v_pk_add_f32 v[108:109], v[108:109], 1.0 op_sel_hi:[1,0]
	s_nop 0
	v_mul_f32_e32 v108, v108, v109
	v_rcp_f32_e32 v108, v108
	v_and_b32_e32 v109, 0xffff0000, v134
	v_mul_f32_e32 v109, v109, v110
	v_mul_f32_e32 v108, v94, v108
	v_mul_f32_e32 v94, 0xbfb8aa3b, v95
	v_mul_f32_e32 v95, 0xbfb8aa3b, v110
	v_exp_f32_e32 v94, v94
	v_exp_f32_e32 v95, v95
	v_lshlrev_b32_e32 v110, 16, v135
	v_pk_add_f32 v[94:95], v[94:95], 1.0 op_sel_hi:[1,0]
	s_nop 0
	v_mul_f32_e32 v94, v94, v95
	v_rcp_f32_e32 v94, v94
	v_lshlrev_b32_e32 v95, 16, v131
	v_mul_f32_e32 v94, v109, v94
	v_cvt_pk_bf16_f32 v94, v108, v94
	v_exp_f32_e32 v108, v96
	v_mul_f32_e32 v96, 0xbfb8aa3b, v95
	v_exp_f32_e32 v109, v96
	v_mul_f32_e32 v95, v110, v95
	v_pk_add_f32 v[108:109], v[108:109], 1.0 op_sel_hi:[1,0]
	s_nop 0
	v_mul_f32_e32 v96, v108, v109
	v_rcp_f32_e32 v96, v96
	v_and_b32_e32 v109, 0xffff0000, v131
	v_and_b32_e32 v108, 0xffff0000, v135
	v_mul_f32_e32 v108, v108, v109
	v_mul_f32_e32 v95, v95, v96
	v_mul_f32_e32 v96, 0xbfb8aa3b, v97
	v_mul_f32_e32 v97, 0xbfb8aa3b, v109
	v_exp_f32_e32 v96, v96
	v_exp_f32_e32 v97, v97
	v_lshlrev_b32_e32 v109, 16, v136
	v_pk_add_f32 v[96:97], v[96:97], 1.0 op_sel_hi:[1,0]
	s_nop 0
	v_mul_f32_e32 v96, v96, v97
	v_rcp_f32_e32 v96, v96
	s_nop 0
	v_mul_f32_e32 v96, v108, v96
	v_lshlrev_b32_e32 v108, 16, v132
	v_cvt_pk_bf16_f32 v95, v95, v96
	v_exp_f32_e32 v96, v90
	v_mul_f32_e32 v90, 0xbfb8aa3b, v108
	v_exp_f32_e32 v97, v90
	v_mul_f32_e32 v90, v109, v108
	v_and_b32_e32 v108, 0xffff0000, v132
	v_pk_add_f32 v[96:97], v[96:97], 1.0 op_sel_hi:[1,0]
	s_nop 0
	v_mul_f32_e32 v96, v96, v97
	v_rcp_f32_e32 v96, v96
	v_and_b32_e32 v97, 0xffff0000, v136
	v_mul_f32_e32 v97, v97, v108
	v_mul_f32_e32 v96, v90, v96
	v_mul_f32_e32 v90, 0xbfb8aa3b, v91
	v_mul_f32_e32 v91, 0xbfb8aa3b, v108
	v_exp_f32_e32 v90, v90
	v_exp_f32_e32 v91, v91
	v_lshlrev_b32_e32 v108, 16, v137
	v_pk_add_f32 v[90:91], v[90:91], 1.0 op_sel_hi:[1,0]
	s_nop 0
	v_mul_f32_e32 v90, v90, v91
	v_rcp_f32_e32 v90, v90
	s_nop 0
	v_mul_f32_e32 v90, v97, v90
	v_lshlrev_b32_e32 v97, 16, v133
	v_cvt_pk_bf16_f32 v96, v96, v90
	v_mul_f32_e32 v90, 0xbfb8aa3b, v92
	v_mul_f32_e32 v91, 0xbfb8aa3b, v97
	v_exp_f32_e32 v90, v90
	v_exp_f32_e32 v91, v91
	v_mul_f32_e32 v92, v108, v97
	v_and_b32_e32 v108, 0xffff0000, v133
	v_and_b32_e32 v97, 0xffff0000, v137
	v_pk_add_f32 v[90:91], v[90:91], 1.0 op_sel_hi:[1,0]
	s_nop 0
	v_mul_f32_e32 v90, v90, v91
	v_rcp_f32_e32 v90, v90
	v_mul_f32_e32 v91, 0xbfb8aa3b, v108
	v_exp_f32_e32 v91, v91
	v_mul_f32_e32 v92, v92, v90
	v_mul_f32_e32 v90, 0xbfb8aa3b, v93
	v_exp_f32_e32 v90, v90
	v_mul_f32_e32 v93, v97, v108
	v_pk_add_f32 v[90:91], v[90:91], 1.0 op_sel_hi:[1,0]
	s_nop 0
	v_mul_f32_e32 v90, v90, v91
	v_rcp_f32_e32 v90, v90
	s_nop 0
	v_mul_f32_e32 v90, v93, v90
	v_cvt_pk_bf16_f32 v97, v92, v90
	v_lshlrev_b64 v[90:91], 13, v[174:175]
	v_lshl_add_u64 v[90:91], s[44:45], 0, v[90:91]
	v_lshlrev_b32_e32 v92, 16, v122
	v_lshl_add_u64 v[108:109], v[90:91], 0, v[204:205]
	v_exp_f32_e32 v90, v86
	v_mul_f32_e32 v86, 0xbfb8aa3b, v92
	v_exp_f32_e32 v91, v86
	v_lshlrev_b32_e32 v93, 16, v126
	v_mul_f32_e32 v86, v93, v92
	v_and_b32_e32 v92, 0xffff0000, v122
	v_pk_add_f32 v[90:91], v[90:91], 1.0 op_sel_hi:[1,0]
	global_store_dwordx4 v[108:109], v[94:97], off
	v_mul_f32_e32 v90, v90, v91
	v_rcp_f32_e32 v90, v90
	v_and_b32_e32 v91, 0xffff0000, v126
	v_mul_f32_e32 v91, v91, v92
	v_mul_f32_e32 v90, v86, v90
	v_mul_f32_e32 v86, 0xbfb8aa3b, v87
	v_mul_f32_e32 v87, 0xbfb8aa3b, v92
	v_exp_f32_e32 v86, v86
	v_exp_f32_e32 v87, v87
	v_lshlrev_b32_e32 v92, 16, v127
	v_pk_add_f32 v[86:87], v[86:87], 1.0 op_sel_hi:[1,0]
	s_nop 0
	v_mul_f32_e32 v86, v86, v87
	v_rcp_f32_e32 v86, v86
	v_lshlrev_b32_e32 v87, 16, v123
	v_mul_f32_e32 v86, v91, v86
	v_cvt_pk_bf16_f32 v86, v90, v86
	v_exp_f32_e32 v90, v88
	v_mul_f32_e32 v88, 0xbfb8aa3b, v87
	v_exp_f32_e32 v91, v88
	v_mul_f32_e32 v87, v92, v87
	v_pk_add_f32 v[90:91], v[90:91], 1.0 op_sel_hi:[1,0]
	s_nop 0
	v_mul_f32_e32 v88, v90, v91
	v_rcp_f32_e32 v88, v88
	v_and_b32_e32 v91, 0xffff0000, v123
	v_and_b32_e32 v90, 0xffff0000, v127
	v_mul_f32_e32 v90, v90, v91
	v_mul_f32_e32 v87, v87, v88
	v_mul_f32_e32 v88, 0xbfb8aa3b, v89
	v_mul_f32_e32 v89, 0xbfb8aa3b, v91
	v_exp_f32_e32 v88, v88
	v_exp_f32_e32 v89, v89
	v_lshlrev_b32_e32 v91, 16, v128
	v_pk_add_f32 v[88:89], v[88:89], 1.0 op_sel_hi:[1,0]
	s_nop 0
	v_mul_f32_e32 v88, v88, v89
	v_rcp_f32_e32 v88, v88
	s_nop 0
	v_mul_f32_e32 v88, v90, v88
	v_lshlrev_b32_e32 v90, 16, v124
	v_cvt_pk_bf16_f32 v87, v87, v88
	v_exp_f32_e32 v88, v82
	v_mul_f32_e32 v82, 0xbfb8aa3b, v90
	v_exp_f32_e32 v89, v82
	v_mul_f32_e32 v82, v91, v90
	v_and_b32_e32 v90, 0xffff0000, v124
	v_pk_add_f32 v[88:89], v[88:89], 1.0 op_sel_hi:[1,0]
	s_nop 0
	v_mul_f32_e32 v88, v88, v89
	v_rcp_f32_e32 v88, v88
	v_and_b32_e32 v89, 0xffff0000, v128
	v_mul_f32_e32 v89, v89, v90
	v_mul_f32_e32 v88, v82, v88
	v_mul_f32_e32 v82, 0xbfb8aa3b, v83
	v_mul_f32_e32 v83, 0xbfb8aa3b, v90
	v_exp_f32_e32 v82, v82
	v_exp_f32_e32 v83, v83
	v_lshlrev_b32_e32 v90, 16, v129
	v_pk_add_f32 v[82:83], v[82:83], 1.0 op_sel_hi:[1,0]
	s_nop 0
	v_mul_f32_e32 v82, v82, v83
	v_rcp_f32_e32 v82, v82
	s_nop 0
	v_mul_f32_e32 v82, v89, v82
; __device__ __forceinline__ unsigned cvt_pk_bf16(float lo, float hi) { unsigned r; asm volatile("v_cvt_pk_bf16_f32 %0, %1, %2" : "=v"(r) : "v"(lo), "v"(hi)); return r; }
; __device__ __forceinline__ float bf_lo(unsigned w) { return __uint_as_float(w << 16); }
; __device__ __forceinline__ float bf_hi(unsigned w) { return __uint_as_float(w & 0xffff0000u); }
;     __device__ __forceinline__ void operator()(const f32x4 (&acc)[2][2][4][2], const Unit& u, int wr, int wc, int fr, int fq, const Pre&) const {
;     ...
;         for (int bj = 0; bj < 2; ++bj) { const int c = col0 + bj * HALF;
; #pragma unroll
;             for (int ai = 0; ai < 2; ++ai) { u32x4 zv[4], gv[4];
; #pragma unroll
;                 for (int m = 0; m < 4; ++m) { const int r = row0 + ai * HALF + m * 16; zv[m] = *(const u32x4*)(Z + (size_t)r * DE2 + c); gv[m] = *(const u32x4*)(Gm + (size_t)(c >> 4) * GSTR + r * 16 + (c & 15)); }
; #pragma unroll
;                 for (int m = 0; m < 4; ++m) { const int r = row0 + ai * HALF + m * 16;
;                     const u32x4 zw = zv[m], gw = gv[m];
;                     const f32x4 a0 = acc[ai][bj][m][0] + bs[bj][0], a1 = acc[ai][bj][m][1] + bs[bj][1];
;                     u32x4 w;
;                     w.x = cvt_pk_bf16(glu_gate_f(bf_lo(gw.x), a0[0], bf_lo(zw.x)), glu_gate_f(bf_hi(gw.x), a0[1], bf_hi(zw.x)));
;                     w.y = cvt_pk_bf16(glu_gate_f(bf_lo(gw.y), a0[2], bf_lo(zw.y)), glu_gate_f(bf_hi(gw.y), a0[3], bf_hi(zw.y)));
;                     w.z = cvt_pk_bf16(glu_gate_f(bf_lo(gw.z), a1[0], bf_lo(zw.z)), glu_gate_f(bf_hi(gw.z), a1[1], bf_hi(zw.z)));
;                     w.w = cvt_pk_bf16(glu_gate_f(bf_lo(gw.w), a1[2], bf_lo(zw.w)), glu_gate_f(bf_hi(gw.w), a1[3], bf_hi(zw.w)));
;                     *(u32x4*)(O + (size_t)r * DE + c) = w; } } }
	v_lshlrev_b32_e32 v89, 16, v125
	v_cvt_pk_bf16_f32 v88, v88, v82
	v_mul_f32_e32 v82, 0xbfb8aa3b, v84
	v_mul_f32_e32 v83, 0xbfb8aa3b, v89
	v_exp_f32_e32 v82, v82
	v_exp_f32_e32 v83, v83
	v_mul_f32_e32 v84, v90, v89
	v_and_b32_e32 v90, 0xffff0000, v125
	v_and_b32_e32 v89, 0xffff0000, v129
	v_pk_add_f32 v[82:83], v[82:83], 1.0 op_sel_hi:[1,0]
	s_nop 0
	v_mul_f32_e32 v82, v82, v83
	v_rcp_f32_e32 v82, v82
	v_mul_f32_e32 v83, 0xbfb8aa3b, v90
	v_exp_f32_e32 v83, v83
	v_mul_f32_e32 v84, v84, v82
	v_mul_f32_e32 v82, 0xbfb8aa3b, v85
	v_exp_f32_e32 v82, v82
	v_mul_f32_e32 v85, v89, v90
	v_pk_add_f32 v[82:83], v[82:83], 1.0 op_sel_hi:[1,0]
	s_nop 0
	v_mul_f32_e32 v82, v82, v83
	v_rcp_f32_e32 v82, v82
	s_nop 0
	v_mul_f32_e32 v82, v85, v82
	v_cvt_pk_bf16_f32 v89, v84, v82
	v_lshlrev_b64 v[82:83], 13, v[172:173]
	v_lshl_add_u64 v[82:83], s[44:45], 0, v[82:83]
	v_lshlrev_b32_e32 v84, 16, v114
	v_lshl_add_u64 v[110:111], v[82:83], 0, v[204:205]
	v_exp_f32_e32 v82, v78
	v_mul_f32_e32 v78, 0xbfb8aa3b, v84
	v_exp_f32_e32 v83, v78
	v_lshlrev_b32_e32 v85, 16, v118
	v_mul_f32_e32 v78, v85, v84
	v_and_b32_e32 v84, 0xffff0000, v114
	v_pk_add_f32 v[82:83], v[82:83], 1.0 op_sel_hi:[1,0]
	global_store_dwordx4 v[110:111], v[86:89], off
	v_mul_f32_e32 v82, v82, v83
	v_rcp_f32_e32 v82, v82
	v_and_b32_e32 v83, 0xffff0000, v118
	v_mul_f32_e32 v83, v83, v84
	v_exp_f32_e32 v118, v70
	v_mul_f32_e32 v82, v78, v82
	v_mul_f32_e32 v78, 0xbfb8aa3b, v79
	v_mul_f32_e32 v79, 0xbfb8aa3b, v84
	v_exp_f32_e32 v78, v78
	v_exp_f32_e32 v79, v79
	v_lshlrev_b32_e32 v84, 16, v119
	v_pk_add_f32 v[78:79], v[78:79], 1.0 op_sel_hi:[1,0]
	s_nop 0
	v_mul_f32_e32 v78, v78, v79
	v_rcp_f32_e32 v78, v78
	v_lshlrev_b32_e32 v79, 16, v115
	v_mul_f32_e32 v78, v83, v78
	v_cvt_pk_bf16_f32 v78, v82, v78
	v_exp_f32_e32 v82, v80
	v_mul_f32_e32 v80, 0xbfb8aa3b, v79
	v_exp_f32_e32 v83, v80
	v_mul_f32_e32 v79, v84, v79
	v_pk_add_f32 v[82:83], v[82:83], 1.0 op_sel_hi:[1,0]
	s_nop 0
	v_mul_f32_e32 v80, v82, v83
	v_rcp_f32_e32 v80, v80
	v_and_b32_e32 v83, 0xffff0000, v115
	v_and_b32_e32 v82, 0xffff0000, v119
	v_mul_f32_e32 v82, v82, v83
	v_mul_f32_e32 v79, v79, v80
	v_mul_f32_e32 v80, 0xbfb8aa3b, v81
	v_mul_f32_e32 v81, 0xbfb8aa3b, v83
	v_exp_f32_e32 v80, v80
	v_exp_f32_e32 v81, v81
	v_lshlrev_b32_e32 v83, 16, v120
	v_pk_add_f32 v[80:81], v[80:81], 1.0 op_sel_hi:[1,0]
	s_nop 0
	v_mul_f32_e32 v80, v80, v81
	v_rcp_f32_e32 v80, v80
	s_nop 0
	v_mul_f32_e32 v80, v82, v80
	v_lshlrev_b32_e32 v82, 16, v116
	v_cvt_pk_bf16_f32 v79, v79, v80
	v_exp_f32_e32 v80, v74
	v_mul_f32_e32 v74, 0xbfb8aa3b, v82
	v_exp_f32_e32 v81, v74
	v_mul_f32_e32 v74, v83, v82
	v_and_b32_e32 v82, 0xffff0000, v116
	v_pk_add_f32 v[80:81], v[80:81], 1.0 op_sel_hi:[1,0]
	s_nop 0
	v_mul_f32_e32 v80, v80, v81
	v_rcp_f32_e32 v80, v80
	v_and_b32_e32 v81, 0xffff0000, v120
	v_mul_f32_e32 v81, v81, v82
	v_mul_f32_e32 v80, v74, v80
	v_mul_f32_e32 v74, 0xbfb8aa3b, v75
	v_mul_f32_e32 v75, 0xbfb8aa3b, v82
	v_exp_f32_e32 v74, v74
	v_exp_f32_e32 v75, v75
	v_lshlrev_b32_e32 v82, 16, v121
	v_pk_add_f32 v[74:75], v[74:75], 1.0 op_sel_hi:[1,0]
	s_nop 0
	v_mul_f32_e32 v74, v74, v75
	v_rcp_f32_e32 v74, v74
	s_nop 0
	v_mul_f32_e32 v74, v81, v74
	v_lshlrev_b32_e32 v81, 16, v117
	v_cvt_pk_bf16_f32 v80, v80, v74
	v_mul_f32_e32 v74, 0xbfb8aa3b, v76
	v_mul_f32_e32 v75, 0xbfb8aa3b, v81
	v_exp_f32_e32 v74, v74
	v_exp_f32_e32 v75, v75
	v_mul_f32_e32 v76, v82, v81
	v_and_b32_e32 v82, 0xffff0000, v117
	v_and_b32_e32 v81, 0xffff0000, v121
	v_pk_add_f32 v[74:75], v[74:75], 1.0 op_sel_hi:[1,0]
	s_nop 0
	v_mul_f32_e32 v74, v74, v75
	v_rcp_f32_e32 v74, v74
	v_mul_f32_e32 v75, 0xbfb8aa3b, v82
	v_exp_f32_e32 v75, v75
	v_mul_f32_e32 v76, v76, v74
	v_mul_f32_e32 v74, 0xbfb8aa3b, v77
	v_exp_f32_e32 v74, v74
	v_mul_f32_e32 v77, v81, v82
	v_pk_add_f32 v[74:75], v[74:75], 1.0 op_sel_hi:[1,0]
	s_nop 0
	v_mul_f32_e32 v74, v74, v75
	v_rcp_f32_e32 v74, v74
	s_nop 0
	v_mul_f32_e32 v74, v77, v74
	v_cvt_pk_bf16_f32 v81, v76, v74
	v_lshlrev_b64 v[74:75], 13, v[170:171]
	v_lshl_add_u64 v[74:75], s[44:45], 0, v[74:75]
	v_lshl_add_u64 v[112:113], v[74:75], 0, v[204:205]
	v_or_b32_e32 v74, 0x80, v200
	v_ashrrev_i32_e32 v75, 31, v74
	v_ashrrev_i32_e32 v76, 4, v74
	v_mad_i64_i32 v[114:115], s[4:5], v76, s94, v[194:195]
	v_lshl_add_u64 v[76:77], s[46:47], 0, v[202:203]
	v_lshlrev_b64 v[116:117], 1, v[74:75]
	v_lshl_add_u64 v[74:75], v[76:77], 0, v[116:117]
	global_load_dwordx4 v[98:101], v[74:75], off
	s_nop 0
	global_store_dwordx4 v[112:113], v[78:81], off
	s_nop 1
	v_lshl_add_u64 v[78:79], v[114:115], 0, v[218:219]
	global_load_dwordx4 v[78:81], v[78:79], off
	v_lshl_add_u64 v[74:75], v[114:115], 0, v[206:207]
	global_load_dwordx4 v[102:105], v[74:75], off
	v_lshl_add_u64 v[74:75], s[46:47], 0, v[210:211]
	v_lshl_add_u64 v[74:75], v[74:75], 0, v[116:117]
	global_load_dwordx4 v[90:93], v[74:75], off
	v_lshl_add_u64 v[74:75], v[114:115], 0, v[208:209]
	global_load_dwordx4 v[94:97], v[74:75], off
	v_lshl_add_u64 v[74:75], s[46:47], 0, v[214:215]
	v_lshl_add_u64 v[74:75], v[74:75], 0, v[116:117]
	global_load_dwordx4 v[82:85], v[74:75], off
	v_lshl_add_u64 v[74:75], v[114:115], 0, v[212:213]
	global_load_dwordx4 v[86:89], v[74:75], off
	v_lshl_add_u64 v[74:75], s[46:47], 0, v[216:217]
	v_lshl_add_u64 v[74:75], v[74:75], 0, v[116:117]
	global_load_dwordx4 v[74:77], v[74:75], off
	s_waitcnt vmcnt(0)
; __device__ __forceinline__ unsigned cvt_pk_bf16(float lo, float hi) { unsigned r; asm volatile("v_cvt_pk_bf16_f32 %0, %1, %2" : "=v"(r) : "v"(lo), "v"(hi)); return r; }
; __device__ __forceinline__ float bf_lo(unsigned w) { return __uint_as_float(w << 16); }
; __device__ __forceinline__ float bf_hi(unsigned w) { return __uint_as_float(w & 0xffff0000u); }
;     __device__ __forceinline__ void operator()(const f32x4 (&acc)[2][2][4][2], const Unit& u, int wr, int wc, int fr, int fq, const Pre&) const {
;     ...
;         for (int bj = 0; bj < 2; ++bj) { const int c = col0 + bj * HALF;
; #pragma unroll
;             for (int ai = 0; ai < 2; ++ai) { u32x4 zv[4], gv[4];
; #pragma unroll
;                 for (int m = 0; m < 4; ++m) { const int r = row0 + ai * HALF + m * 16; zv[m] = *(const u32x4*)(Z + (size_t)r * DE2 + c); gv[m] = *(const u32x4*)(Gm + (size_t)(c >> 4) * GSTR + r * 16 + (c & 15)); }
; #pragma unroll
;                 for (int m = 0; m < 4; ++m) { const int r = row0 + ai * HALF + m * 16;
;                     const u32x4 zw = zv[m], gw = gv[m];
;                     const f32x4 a0 = acc[ai][bj][m][0] + bs[bj][0], a1 = acc[ai][bj][m][1] + bs[bj][1];
;                     u32x4 w;
;                     w.x = cvt_pk_bf16(glu_gate_f(bf_lo(gw.x), a0[0], bf_lo(zw.x)), glu_gate_f(bf_hi(gw.x), a0[1], bf_hi(zw.x)));
;                     w.y = cvt_pk_bf16(glu_gate_f(bf_lo(gw.y), a0[2], bf_lo(zw.y)), glu_gate_f(bf_hi(gw.y), a0[3], bf_hi(zw.y)));
;                     w.z = cvt_pk_bf16(glu_gate_f(bf_lo(gw.z), a1[0], bf_lo(zw.z)), glu_gate_f(bf_hi(gw.z), a1[1], bf_hi(zw.z)));
;                     w.w = cvt_pk_bf16(glu_gate_f(bf_lo(gw.w), a1[2], bf_lo(zw.w)), glu_gate_f(bf_hi(gw.w), a1[3], bf_hi(zw.w)));
;                     *(u32x4*)(O + (size_t)r * DE + c) = w; } } }
	v_lshlrev_b32_e32 v120, 16, v98
	v_mul_f32_e32 v70, 0xbfb8aa3b, v120
	v_exp_f32_e32 v119, v70
	v_and_b32_e32 v98, 0xffff0000, v98
	v_pk_add_f32 v[118:119], v[118:119], 1.0 op_sel_hi:[1,0]
	s_nop 0
	v_mul_f32_e32 v118, v118, v119
	v_rcp_f32_e32 v118, v118
	v_lshlrev_b32_e32 v121, 16, v102
	v_mul_f32_e32 v70, v121, v120
	v_and_b32_e32 v102, 0xffff0000, v102
	v_mul_f32_e32 v118, v70, v118
	v_mul_f32_e32 v70, 0xbfb8aa3b, v71
	v_mul_f32_e32 v71, 0xbfb8aa3b, v98
	v_exp_f32_e32 v70, v70
	v_exp_f32_e32 v71, v71
	v_mul_f32_e32 v98, v102, v98
	v_pk_add_f32 v[70:71], v[70:71], 1.0 op_sel_hi:[1,0]
	s_nop 0
	v_mul_f32_e32 v70, v70, v71
	v_rcp_f32_e32 v70, v70
	v_lshlrev_b32_e32 v71, 16, v99
	v_and_b32_e32 v99, 0xffff0000, v99
	v_mul_f32_e32 v70, v98, v70
	v_cvt_pk_bf16_f32 v70, v118, v70
	v_exp_f32_e32 v118, v72
	v_mul_f32_e32 v72, 0xbfb8aa3b, v71
	v_exp_f32_e32 v119, v72
	v_lshlrev_b32_e32 v98, 16, v103
	v_mul_f32_e32 v71, v98, v71
	v_and_b32_e32 v98, 0xffff0000, v103
	v_pk_add_f32 v[118:119], v[118:119], 1.0 op_sel_hi:[1,0]
	v_mul_f32_e32 v98, v98, v99
	v_mul_f32_e32 v72, v118, v119
	v_rcp_f32_e32 v72, v72
	s_nop 0
	v_mul_f32_e32 v71, v71, v72
	v_mul_f32_e32 v72, 0xbfb8aa3b, v73
	v_mul_f32_e32 v73, 0xbfb8aa3b, v99
	v_exp_f32_e32 v72, v72
	v_exp_f32_e32 v73, v73
	v_lshlrev_b32_e32 v99, 16, v104
	v_pk_add_f32 v[72:73], v[72:73], 1.0 op_sel_hi:[1,0]
	s_nop 0
	v_mul_f32_e32 v72, v72, v73
	v_rcp_f32_e32 v72, v72
	s_nop 0
	v_mul_f32_e32 v72, v98, v72
	v_lshlrev_b32_e32 v98, 16, v100
	v_cvt_pk_bf16_f32 v71, v71, v72
	v_exp_f32_e32 v72, v66
	v_mul_f32_e32 v66, 0xbfb8aa3b, v98
	v_exp_f32_e32 v73, v66
	v_mul_f32_e32 v66, v99, v98
	v_and_b32_e32 v98, 0xffff0000, v100
	v_pk_add_f32 v[72:73], v[72:73], 1.0 op_sel_hi:[1,0]
	s_nop 0
	v_mul_f32_e32 v72, v72, v73
	v_rcp_f32_e32 v72, v72
	v_and_b32_e32 v73, 0xffff0000, v104
	v_mul_f32_e32 v73, v73, v98
	v_mul_f32_e32 v72, v66, v72
	v_mul_f32_e32 v66, 0xbfb8aa3b, v67
	v_mul_f32_e32 v67, 0xbfb8aa3b, v98
	v_exp_f32_e32 v66, v66
	v_exp_f32_e32 v67, v67
	v_lshlrev_b32_e32 v98, 16, v105
	v_pk_add_f32 v[66:67], v[66:67], 1.0 op_sel_hi:[1,0]
	s_nop 0
	v_mul_f32_e32 v66, v66, v67
	v_rcp_f32_e32 v66, v66
	s_nop 0
	v_mul_f32_e32 v66, v73, v66
	v_lshlrev_b32_e32 v73, 16, v101
	v_cvt_pk_bf16_f32 v72, v72, v66
	v_mul_f32_e32 v66, 0xbfb8aa3b, v68
	v_mul_f32_e32 v67, 0xbfb8aa3b, v73
	v_exp_f32_e32 v66, v66
	v_exp_f32_e32 v67, v67
	v_mul_f32_e32 v68, v98, v73
	v_and_b32_e32 v98, 0xffff0000, v101
	v_and_b32_e32 v73, 0xffff0000, v105
	v_pk_add_f32 v[66:67], v[66:67], 1.0 op_sel_hi:[1,0]
	s_nop 0
	v_mul_f32_e32 v66, v66, v67
	v_rcp_f32_e32 v66, v66
	v_mul_f32_e32 v67, 0xbfb8aa3b, v98
	v_exp_f32_e32 v67, v67
	v_mul_f32_e32 v68, v68, v66
	v_mul_f32_e32 v66, 0xbfb8aa3b, v69
	v_exp_f32_e32 v66, v66
	v_mul_f32_e32 v69, v73, v98
	v_pk_add_f32 v[66:67], v[66:67], 1.0 op_sel_hi:[1,0]
	s_nop 0
	v_mul_f32_e32 v66, v66, v67
	v_rcp_f32_e32 v66, v66
	s_nop 0
	v_mul_f32_e32 v66, v69, v66
	v_cvt_pk_bf16_f32 v73, v68, v66
	v_lshlrev_b32_e32 v68, 16, v90
	v_exp_f32_e32 v66, v62
	v_mul_f32_e32 v62, 0xbfb8aa3b, v68
	v_exp_f32_e32 v67, v62
	v_lshlrev_b32_e32 v69, 16, v94
	v_mul_f32_e32 v62, v69, v68
	v_and_b32_e32 v68, 0xffff0000, v90
	v_pk_add_f32 v[66:67], v[66:67], 1.0 op_sel_hi:[1,0]
	global_store_dwordx4 v[162:163], v[70:73], off offset:256
	v_mul_f32_e32 v66, v66, v67
	v_rcp_f32_e32 v66, v66
	v_and_b32_e32 v67, 0xffff0000, v94
	v_mul_f32_e32 v67, v67, v68
	v_mul_f32_e32 v66, v62, v66
	v_mul_f32_e32 v62, 0xbfb8aa3b, v63
	v_mul_f32_e32 v63, 0xbfb8aa3b, v68
	v_exp_f32_e32 v62, v62
	v_exp_f32_e32 v63, v63
	v_lshlrev_b32_e32 v68, 16, v95
	v_pk_add_f32 v[62:63], v[62:63], 1.0 op_sel_hi:[1,0]
	s_nop 0
	v_mul_f32_e32 v62, v62, v63
	v_rcp_f32_e32 v62, v62
	v_lshlrev_b32_e32 v63, 16, v91
	v_mul_f32_e32 v62, v67, v62
	v_cvt_pk_bf16_f32 v62, v66, v62
	v_exp_f32_e32 v66, v64
	v_mul_f32_e32 v64, 0xbfb8aa3b, v63
	v_exp_f32_e32 v67, v64
	v_mul_f32_e32 v63, v68, v63
	v_pk_add_f32 v[66:67], v[66:67], 1.0 op_sel_hi:[1,0]
	s_nop 0
	v_mul_f32_e32 v64, v66, v67
	v_rcp_f32_e32 v64, v64
	v_and_b32_e32 v67, 0xffff0000, v91
	v_and_b32_e32 v66, 0xffff0000, v95
	v_mul_f32_e32 v66, v66, v67
	v_mul_f32_e32 v63, v63, v64
	v_mul_f32_e32 v64, 0xbfb8aa3b, v65
	v_mul_f32_e32 v65, 0xbfb8aa3b, v67
	v_exp_f32_e32 v64, v64
	v_exp_f32_e32 v65, v65
	v_lshlrev_b32_e32 v67, 16, v96
	v_pk_add_f32 v[64:65], v[64:65], 1.0 op_sel_hi:[1,0]
	s_nop 0
	v_mul_f32_e32 v64, v64, v65
	v_rcp_f32_e32 v64, v64
	s_nop 0
	v_mul_f32_e32 v64, v66, v64
	v_lshlrev_b32_e32 v66, 16, v92
	v_cvt_pk_bf16_f32 v63, v63, v64
	v_exp_f32_e32 v64, v58
	v_mul_f32_e32 v58, 0xbfb8aa3b, v66
	v_exp_f32_e32 v65, v58
	v_mul_f32_e32 v58, v67, v66
	v_and_b32_e32 v66, 0xffff0000, v92
	v_pk_add_f32 v[64:65], v[64:65], 1.0 op_sel_hi:[1,0]
	s_nop 0
	v_mul_f32_e32 v64, v64, v65
	v_rcp_f32_e32 v64, v64
	v_and_b32_e32 v65, 0xffff0000, v96
	v_mul_f32_e32 v65, v65, v66
	v_mul_f32_e32 v64, v58, v64
	v_mul_f32_e32 v58, 0xbfb8aa3b, v59
	v_mul_f32_e32 v59, 0xbfb8aa3b, v66
	v_exp_f32_e32 v58, v58
	v_exp_f32_e32 v59, v59
	v_lshlrev_b32_e32 v66, 16, v97
	v_pk_add_f32 v[58:59], v[58:59], 1.0 op_sel_hi:[1,0]
	s_nop 0
	v_mul_f32_e32 v58, v58, v59
	v_rcp_f32_e32 v58, v58
	s_nop 0
	v_mul_f32_e32 v58, v65, v58
	v_lshlrev_b32_e32 v65, 16, v93
	v_cvt_pk_bf16_f32 v64, v64, v58
	v_mul_f32_e32 v58, 0xbfb8aa3b, v60
	v_mul_f32_e32 v59, 0xbfb8aa3b, v65
	v_exp_f32_e32 v58, v58
	v_exp_f32_e32 v59, v59
	v_mul_f32_e32 v60, v66, v65
	v_and_b32_e32 v66, 0xffff0000, v93
	v_and_b32_e32 v65, 0xffff0000, v97
	v_pk_add_f32 v[58:59], v[58:59], 1.0 op_sel_hi:[1,0]
	s_nop 0
	v_mul_f32_e32 v58, v58, v59
	v_rcp_f32_e32 v58, v58
	v_mul_f32_e32 v59, 0xbfb8aa3b, v66
; __device__ __forceinline__ unsigned cvt_pk_bf16(float lo, float hi) { unsigned r; asm volatile("v_cvt_pk_bf16_f32 %0, %1, %2" : "=v"(r) : "v"(lo), "v"(hi)); return r; }
; __device__ __forceinline__ float bf_lo(unsigned w) { return __uint_as_float(w << 16); }
; __device__ __forceinline__ float bf_hi(unsigned w) { return __uint_as_float(w & 0xffff0000u); }
;     __device__ __forceinline__ void operator()(const f32x4 (&acc)[2][2][4][2], const Unit& u, int wr, int wc, int fr, int fq, const Pre&) const {
;     ...
;         for (int bj = 0; bj < 2; ++bj) { const int c = col0 + bj * HALF;
; #pragma unroll
;             for (int ai = 0; ai < 2; ++ai) { u32x4 zv[4], gv[4];
; #pragma unroll
;                 for (int m = 0; m < 4; ++m) { const int r = row0 + ai * HALF + m * 16; zv[m] = *(const u32x4*)(Z + (size_t)r * DE2 + c); gv[m] = *(const u32x4*)(Gm + (size_t)(c >> 4) * GSTR + r * 16 + (c & 15)); }
; #pragma unroll
;                 for (int m = 0; m < 4; ++m) { const int r = row0 + ai * HALF + m * 16;
;                     const u32x4 zw = zv[m], gw = gv[m];
;                     const f32x4 a0 = acc[ai][bj][m][0] + bs[bj][0], a1 = acc[ai][bj][m][1] + bs[bj][1];
;                     u32x4 w;
;                     w.x = cvt_pk_bf16(glu_gate_f(bf_lo(gw.x), a0[0], bf_lo(zw.x)), glu_gate_f(bf_hi(gw.x), a0[1], bf_hi(zw.x)));
;                     w.y = cvt_pk_bf16(glu_gate_f(bf_lo(gw.y), a0[2], bf_lo(zw.y)), glu_gate_f(bf_hi(gw.y), a0[3], bf_hi(zw.y)));
;                     w.z = cvt_pk_bf16(glu_gate_f(bf_lo(gw.z), a1[0], bf_lo(zw.z)), glu_gate_f(bf_hi(gw.z), a1[1], bf_hi(zw.z)));
;                     w.w = cvt_pk_bf16(glu_gate_f(bf_lo(gw.w), a1[2], bf_lo(zw.w)), glu_gate_f(bf_hi(gw.w), a1[3], bf_hi(zw.w)));
;                     *(u32x4*)(O + (size_t)r * DE + c) = w; } } }
	v_exp_f32_e32 v59, v59
	v_mul_f32_e32 v60, v60, v58
	v_mul_f32_e32 v58, 0xbfb8aa3b, v61
	v_exp_f32_e32 v58, v58
	v_mul_f32_e32 v61, v65, v66
	v_pk_add_f32 v[58:59], v[58:59], 1.0 op_sel_hi:[1,0]
	s_nop 0
	v_mul_f32_e32 v58, v58, v59
	v_rcp_f32_e32 v58, v58
	s_nop 0
	v_mul_f32_e32 v58, v61, v58
	v_cvt_pk_bf16_f32 v65, v60, v58
	v_lshlrev_b32_e32 v60, 16, v82
	v_exp_f32_e32 v58, v54
	v_mul_f32_e32 v54, 0xbfb8aa3b, v60
	v_exp_f32_e32 v59, v54
	v_lshlrev_b32_e32 v61, 16, v86
	v_mul_f32_e32 v54, v61, v60
	v_and_b32_e32 v60, 0xffff0000, v82
	v_pk_add_f32 v[58:59], v[58:59], 1.0 op_sel_hi:[1,0]
	global_store_dwordx4 v[154:155], v[62:65], off offset:256
	v_mul_f32_e32 v58, v58, v59
	v_rcp_f32_e32 v58, v58
	v_and_b32_e32 v59, 0xffff0000, v86
	v_mul_f32_e32 v59, v59, v60
	v_mul_f32_e32 v58, v54, v58
	v_mul_f32_e32 v54, 0xbfb8aa3b, v55
	v_mul_f32_e32 v55, 0xbfb8aa3b, v60
	v_exp_f32_e32 v54, v54
	v_exp_f32_e32 v55, v55
	v_lshlrev_b32_e32 v60, 16, v87
	v_pk_add_f32 v[54:55], v[54:55], 1.0 op_sel_hi:[1,0]
	s_nop 0
	v_mul_f32_e32 v54, v54, v55
	v_rcp_f32_e32 v54, v54
	v_lshlrev_b32_e32 v55, 16, v83
	v_mul_f32_e32 v54, v59, v54
	v_cvt_pk_bf16_f32 v54, v58, v54
	v_exp_f32_e32 v58, v56
	v_mul_f32_e32 v56, 0xbfb8aa3b, v55
	v_exp_f32_e32 v59, v56
	v_mul_f32_e32 v55, v60, v55
	v_pk_add_f32 v[58:59], v[58:59], 1.0 op_sel_hi:[1,0]
	s_nop 0
	v_mul_f32_e32 v56, v58, v59
	v_rcp_f32_e32 v56, v56
	v_and_b32_e32 v59, 0xffff0000, v83
	v_and_b32_e32 v58, 0xffff0000, v87
	v_mul_f32_e32 v58, v58, v59
	v_mul_f32_e32 v55, v55, v56
	v_mul_f32_e32 v56, 0xbfb8aa3b, v57
	v_mul_f32_e32 v57, 0xbfb8aa3b, v59
	v_exp_f32_e32 v56, v56
	v_exp_f32_e32 v57, v57
	v_lshlrev_b32_e32 v59, 16, v88
	v_pk_add_f32 v[56:57], v[56:57], 1.0 op_sel_hi:[1,0]
	s_nop 0
	v_mul_f32_e32 v56, v56, v57
	v_rcp_f32_e32 v56, v56
	s_nop 0
	v_mul_f32_e32 v56, v58, v56
	v_lshlrev_b32_e32 v58, 16, v84
	v_cvt_pk_bf16_f32 v55, v55, v56
	v_exp_f32_e32 v56, v50
	v_mul_f32_e32 v50, 0xbfb8aa3b, v58
	v_exp_f32_e32 v57, v50
	v_mul_f32_e32 v50, v59, v58
	v_and_b32_e32 v58, 0xffff0000, v84
	v_pk_add_f32 v[56:57], v[56:57], 1.0 op_sel_hi:[1,0]
	s_nop 0
	v_mul_f32_e32 v56, v56, v57
	v_rcp_f32_e32 v56, v56
	v_and_b32_e32 v57, 0xffff0000, v88
	v_mul_f32_e32 v57, v57, v58
	v_mul_f32_e32 v56, v50, v56
	v_mul_f32_e32 v50, 0xbfb8aa3b, v51
	v_mul_f32_e32 v51, 0xbfb8aa3b, v58
	v_exp_f32_e32 v50, v50
	v_exp_f32_e32 v51, v51
	v_lshlrev_b32_e32 v58, 16, v89
	v_pk_add_f32 v[50:51], v[50:51], 1.0 op_sel_hi:[1,0]
	s_nop 0
	v_mul_f32_e32 v50, v50, v51
	v_rcp_f32_e32 v50, v50
	s_nop 0
	v_mul_f32_e32 v50, v57, v50
	v_lshlrev_b32_e32 v57, 16, v85
	v_cvt_pk_bf16_f32 v56, v56, v50
	v_mul_f32_e32 v50, 0xbfb8aa3b, v52
	v_mul_f32_e32 v51, 0xbfb8aa3b, v57
	v_exp_f32_e32 v50, v50
	v_exp_f32_e32 v51, v51
	v_mul_f32_e32 v52, v58, v57
	v_and_b32_e32 v58, 0xffff0000, v85
	v_and_b32_e32 v57, 0xffff0000, v89
	v_pk_add_f32 v[50:51], v[50:51], 1.0 op_sel_hi:[1,0]
	s_nop 0
	v_mul_f32_e32 v50, v50, v51
	v_rcp_f32_e32 v50, v50
	v_mul_f32_e32 v51, 0xbfb8aa3b, v58
	v_exp_f32_e32 v51, v51
	v_mul_f32_e32 v52, v52, v50
	v_mul_f32_e32 v50, 0xbfb8aa3b, v53
	v_exp_f32_e32 v50, v50
	v_mul_f32_e32 v53, v57, v58
	v_pk_add_f32 v[50:51], v[50:51], 1.0 op_sel_hi:[1,0]
	s_nop 0
	v_mul_f32_e32 v50, v50, v51
	v_rcp_f32_e32 v50, v50
	s_nop 0
	v_mul_f32_e32 v50, v53, v50
	v_cvt_pk_bf16_f32 v57, v52, v50
	v_lshlrev_b32_e32 v52, 16, v74
	v_exp_f32_e32 v50, v46
	v_mul_f32_e32 v46, 0xbfb8aa3b, v52
	v_exp_f32_e32 v51, v46
	v_lshlrev_b32_e32 v53, 16, v78
	v_mul_f32_e32 v46, v53, v52
	v_and_b32_e32 v52, 0xffff0000, v74
	v_pk_add_f32 v[50:51], v[50:51], 1.0 op_sel_hi:[1,0]
	global_store_dwordx4 v[146:147], v[54:57], off offset:256
	v_mul_f32_e32 v50, v50, v51
	v_rcp_f32_e32 v50, v50
	v_and_b32_e32 v51, 0xffff0000, v78
	v_mul_f32_e32 v51, v51, v52
	v_exp_f32_e32 v74, v38
	v_mul_f32_e32 v50, v46, v50
	v_mul_f32_e32 v46, 0xbfb8aa3b, v47
	v_mul_f32_e32 v47, 0xbfb8aa3b, v52
	v_exp_f32_e32 v46, v46
	v_exp_f32_e32 v47, v47
	v_lshlrev_b32_e32 v52, 16, v79
	v_pk_add_f32 v[46:47], v[46:47], 1.0 op_sel_hi:[1,0]
	s_nop 0
	v_mul_f32_e32 v46, v46, v47
	v_rcp_f32_e32 v46, v46
	v_lshlrev_b32_e32 v47, 16, v75
	v_mul_f32_e32 v46, v51, v46
	v_cvt_pk_bf16_f32 v46, v50, v46
	v_exp_f32_e32 v50, v48
	v_mul_f32_e32 v48, 0xbfb8aa3b, v47
	v_exp_f32_e32 v51, v48
	v_mul_f32_e32 v47, v52, v47
	v_pk_add_f32 v[50:51], v[50:51], 1.0 op_sel_hi:[1,0]
	s_nop 0
	v_mul_f32_e32 v48, v50, v51
	v_rcp_f32_e32 v48, v48
	v_and_b32_e32 v51, 0xffff0000, v75
	v_and_b32_e32 v50, 0xffff0000, v79
	v_mul_f32_e32 v50, v50, v51
	v_mul_f32_e32 v47, v47, v48
	v_mul_f32_e32 v48, 0xbfb8aa3b, v49
	v_mul_f32_e32 v49, 0xbfb8aa3b, v51
	v_exp_f32_e32 v48, v48
	v_exp_f32_e32 v49, v49
	v_lshlrev_b32_e32 v51, 16, v80
	v_pk_add_f32 v[48:49], v[48:49], 1.0 op_sel_hi:[1,0]
	s_nop 0
	v_mul_f32_e32 v48, v48, v49
	v_rcp_f32_e32 v48, v48
	s_nop 0
	v_mul_f32_e32 v48, v50, v48
	v_lshlrev_b32_e32 v50, 16, v76
	v_cvt_pk_bf16_f32 v47, v47, v48
	v_exp_f32_e32 v48, v42
	v_mul_f32_e32 v42, 0xbfb8aa3b, v50
	v_exp_f32_e32 v49, v42
	v_mul_f32_e32 v42, v51, v50
	v_and_b32_e32 v50, 0xffff0000, v76
	v_pk_add_f32 v[48:49], v[48:49], 1.0 op_sel_hi:[1,0]
	s_nop 0
	v_mul_f32_e32 v48, v48, v49
	v_rcp_f32_e32 v48, v48
	v_and_b32_e32 v49, 0xffff0000, v80
	v_mul_f32_e32 v49, v49, v50
	v_mul_f32_e32 v48, v42, v48
	v_mul_f32_e32 v42, 0xbfb8aa3b, v43
	v_mul_f32_e32 v43, 0xbfb8aa3b, v50
	v_exp_f32_e32 v42, v42
	v_exp_f32_e32 v43, v43
	v_lshlrev_b32_e32 v50, 16, v81
	v_pk_add_f32 v[42:43], v[42:43], 1.0 op_sel_hi:[1,0]
	s_nop 0
	v_mul_f32_e32 v42, v42, v43
	v_rcp_f32_e32 v42, v42
	s_nop 0
	v_mul_f32_e32 v42, v49, v42
	v_lshlrev_b32_e32 v49, 16, v77
	v_cvt_pk_bf16_f32 v48, v48, v42
; __device__ __forceinline__ unsigned cvt_pk_bf16(float lo, float hi) { unsigned r; asm volatile("v_cvt_pk_bf16_f32 %0, %1, %2" : "=v"(r) : "v"(lo), "v"(hi)); return r; }
; __device__ __forceinline__ float bf_lo(unsigned w) { return __uint_as_float(w << 16); }
; __device__ __forceinline__ float bf_hi(unsigned w) { return __uint_as_float(w & 0xffff0000u); }
;     __device__ __forceinline__ void operator()(const f32x4 (&acc)[2][2][4][2], const Unit& u, int wr, int wc, int fr, int fq, const Pre&) const {
;     ...
;         for (int bj = 0; bj < 2; ++bj) { const int c = col0 + bj * HALF;
; #pragma unroll
;             for (int ai = 0; ai < 2; ++ai) { u32x4 zv[4], gv[4];
; #pragma unroll
;                 for (int m = 0; m < 4; ++m) { const int r = row0 + ai * HALF + m * 16; zv[m] = *(const u32x4*)(Z + (size_t)r * DE2 + c); gv[m] = *(const u32x4*)(Gm + (size_t)(c >> 4) * GSTR + r * 16 + (c & 15)); }
; #pragma unroll
;                 for (int m = 0; m < 4; ++m) { const int r = row0 + ai * HALF + m * 16;
;                     const u32x4 zw = zv[m], gw = gv[m];
;                     const f32x4 a0 = acc[ai][bj][m][0] + bs[bj][0], a1 = acc[ai][bj][m][1] + bs[bj][1];
;                     u32x4 w;
;                     w.x = cvt_pk_bf16(glu_gate_f(bf_lo(gw.x), a0[0], bf_lo(zw.x)), glu_gate_f(bf_hi(gw.x), a0[1], bf_hi(zw.x)));
;                     w.y = cvt_pk_bf16(glu_gate_f(bf_lo(gw.y), a0[2], bf_lo(zw.y)), glu_gate_f(bf_hi(gw.y), a0[3], bf_hi(zw.y)));
;                     w.z = cvt_pk_bf16(glu_gate_f(bf_lo(gw.z), a1[0], bf_lo(zw.z)), glu_gate_f(bf_hi(gw.z), a1[1], bf_hi(zw.z)));
;                     w.w = cvt_pk_bf16(glu_gate_f(bf_lo(gw.w), a1[2], bf_lo(zw.w)), glu_gate_f(bf_hi(gw.w), a1[3], bf_hi(zw.w)));
;                     *(u32x4*)(O + (size_t)r * DE + c) = w; } } }
	v_mul_f32_e32 v42, 0xbfb8aa3b, v44
	v_mul_f32_e32 v43, 0xbfb8aa3b, v49
	v_exp_f32_e32 v42, v42
	v_exp_f32_e32 v43, v43
	v_mul_f32_e32 v44, v50, v49
	v_and_b32_e32 v50, 0xffff0000, v77
	v_and_b32_e32 v49, 0xffff0000, v81
	v_pk_add_f32 v[42:43], v[42:43], 1.0 op_sel_hi:[1,0]
	s_nop 0
	v_mul_f32_e32 v42, v42, v43
	v_rcp_f32_e32 v42, v42
	v_mul_f32_e32 v43, 0xbfb8aa3b, v50
	v_exp_f32_e32 v43, v43
	v_mul_f32_e32 v44, v44, v42
	v_mul_f32_e32 v42, 0xbfb8aa3b, v45
	v_exp_f32_e32 v42, v42
	v_mul_f32_e32 v45, v49, v50
	v_pk_add_f32 v[42:43], v[42:43], 1.0 op_sel_hi:[1,0]
	s_nop 0
	v_mul_f32_e32 v42, v42, v43
	v_rcp_f32_e32 v42, v42
	s_nop 0
	v_mul_f32_e32 v42, v45, v42
	v_cvt_pk_bf16_f32 v49, v44, v42
	v_lshl_add_u64 v[42:43], s[46:47], 0, v[150:151]
	global_store_dwordx4 v[148:149], v[46:49], off offset:256
	v_lshl_add_u64 v[42:43], v[42:43], 0, v[116:117]
	global_load_dwordx4 v[66:69], v[42:43], off
	v_lshl_add_u64 v[46:47], v[114:115], 0, v[168:169]
	global_load_dwordx4 v[46:49], v[46:47], off
	v_lshl_add_u64 v[42:43], v[114:115], 0, v[152:153]
	global_load_dwordx4 v[70:73], v[42:43], off
	v_lshl_add_u64 v[42:43], s[46:47], 0, v[156:157]
	v_lshl_add_u64 v[42:43], v[42:43], 0, v[116:117]
	global_load_dwordx4 v[58:61], v[42:43], off
	v_lshl_add_u64 v[42:43], v[114:115], 0, v[158:159]
	global_load_dwordx4 v[62:65], v[42:43], off
	v_lshl_add_u64 v[42:43], s[46:47], 0, v[160:161]
	v_lshl_add_u64 v[42:43], v[42:43], 0, v[116:117]
	global_load_dwordx4 v[50:53], v[42:43], off
	v_lshl_add_u64 v[42:43], v[114:115], 0, v[164:165]
	global_load_dwordx4 v[54:57], v[42:43], off
	v_lshl_add_u64 v[42:43], s[46:47], 0, v[166:167]
	v_lshl_add_u64 v[42:43], v[42:43], 0, v[116:117]
	global_load_dwordx4 v[42:45], v[42:43], off
	s_waitcnt vmcnt(0)
	v_lshlrev_b32_e32 v76, 16, v66
	v_mul_f32_e32 v38, 0xbfb8aa3b, v76
	v_exp_f32_e32 v75, v38
	v_and_b32_e32 v66, 0xffff0000, v66
	v_lshlrev_b32_e32 v77, 16, v70
	v_mul_f32_e32 v38, v77, v76
	v_pk_add_f32 v[74:75], v[74:75], 1.0 op_sel_hi:[1,0]
	v_and_b32_e32 v70, 0xffff0000, v70
	v_mul_f32_e32 v74, v74, v75
	v_rcp_f32_e32 v74, v74
	s_nop 0
	v_mul_f32_e32 v74, v38, v74
	v_mul_f32_e32 v38, 0xbfb8aa3b, v39
	v_mul_f32_e32 v39, 0xbfb8aa3b, v66
	v_exp_f32_e32 v38, v38
	v_exp_f32_e32 v39, v39
	v_mul_f32_e32 v66, v70, v66
	v_pk_add_f32 v[38:39], v[38:39], 1.0 op_sel_hi:[1,0]
	s_nop 0
	v_mul_f32_e32 v38, v38, v39
	v_rcp_f32_e32 v38, v38
	v_lshlrev_b32_e32 v39, 16, v67
	v_and_b32_e32 v67, 0xffff0000, v67
	v_mul_f32_e32 v38, v66, v38
	v_cvt_pk_bf16_f32 v38, v74, v38
	v_exp_f32_e32 v74, v40
	v_mul_f32_e32 v40, 0xbfb8aa3b, v39
	v_exp_f32_e32 v75, v40
	v_lshlrev_b32_e32 v66, 16, v71
	v_mul_f32_e32 v39, v66, v39
	v_and_b32_e32 v66, 0xffff0000, v71
	v_pk_add_f32 v[74:75], v[74:75], 1.0 op_sel_hi:[1,0]
	v_mul_f32_e32 v66, v66, v67
	v_mul_f32_e32 v40, v74, v75
	v_rcp_f32_e32 v40, v40
	s_nop 0
	v_mul_f32_e32 v39, v39, v40
	v_mul_f32_e32 v40, 0xbfb8aa3b, v41
	v_mul_f32_e32 v41, 0xbfb8aa3b, v67
	v_exp_f32_e32 v40, v40
	v_exp_f32_e32 v41, v41
	v_lshlrev_b32_e32 v67, 16, v72
	v_pk_add_f32 v[40:41], v[40:41], 1.0 op_sel_hi:[1,0]
	s_nop 0
	v_mul_f32_e32 v40, v40, v41
	v_rcp_f32_e32 v40, v40
	s_nop 0
	v_mul_f32_e32 v40, v66, v40
	v_lshlrev_b32_e32 v66, 16, v68
	v_cvt_pk_bf16_f32 v39, v39, v40
	v_exp_f32_e32 v40, v34
	v_mul_f32_e32 v34, 0xbfb8aa3b, v66
	v_exp_f32_e32 v41, v34
	v_mul_f32_e32 v34, v67, v66
	v_and_b32_e32 v66, 0xffff0000, v68
	v_pk_add_f32 v[40:41], v[40:41], 1.0 op_sel_hi:[1,0]
	s_nop 0
	v_mul_f32_e32 v40, v40, v41
	v_rcp_f32_e32 v40, v40
	v_and_b32_e32 v41, 0xffff0000, v72
	v_mul_f32_e32 v41, v41, v66
	v_mul_f32_e32 v40, v34, v40
	v_mul_f32_e32 v34, 0xbfb8aa3b, v35
	v_mul_f32_e32 v35, 0xbfb8aa3b, v66
	v_exp_f32_e32 v34, v34
	v_exp_f32_e32 v35, v35
	v_lshlrev_b32_e32 v66, 16, v73
	v_pk_add_f32 v[34:35], v[34:35], 1.0 op_sel_hi:[1,0]
	s_nop 0
	v_mul_f32_e32 v34, v34, v35
	v_rcp_f32_e32 v34, v34
	s_nop 0
	v_mul_f32_e32 v34, v41, v34
	v_lshlrev_b32_e32 v41, 16, v69
	v_cvt_pk_bf16_f32 v40, v40, v34
	v_mul_f32_e32 v34, 0xbfb8aa3b, v36
	v_mul_f32_e32 v35, 0xbfb8aa3b, v41
	v_exp_f32_e32 v34, v34
	v_exp_f32_e32 v35, v35
	v_mul_f32_e32 v36, v66, v41
	v_and_b32_e32 v66, 0xffff0000, v69
	v_and_b32_e32 v41, 0xffff0000, v73
	v_pk_add_f32 v[34:35], v[34:35], 1.0 op_sel_hi:[1,0]
	s_nop 0
	v_mul_f32_e32 v34, v34, v35
	v_rcp_f32_e32 v34, v34
	v_mul_f32_e32 v35, 0xbfb8aa3b, v66
	v_exp_f32_e32 v35, v35
	v_mul_f32_e32 v36, v36, v34
	v_mul_f32_e32 v34, 0xbfb8aa3b, v37
	v_exp_f32_e32 v34, v34
	v_mul_f32_e32 v37, v41, v66
	v_pk_add_f32 v[34:35], v[34:35], 1.0 op_sel_hi:[1,0]
	s_nop 0
	v_mul_f32_e32 v34, v34, v35
	v_rcp_f32_e32 v34, v34
	s_nop 0
	v_mul_f32_e32 v34, v37, v34
	v_cvt_pk_bf16_f32 v41, v36, v34
	v_lshlrev_b32_e32 v36, 16, v58
	v_exp_f32_e32 v34, v22
	v_mul_f32_e32 v22, 0xbfb8aa3b, v36
	v_exp_f32_e32 v35, v22
	v_lshlrev_b32_e32 v37, 16, v62
	v_mul_f32_e32 v22, v37, v36
	v_and_b32_e32 v36, 0xffff0000, v58
	v_pk_add_f32 v[34:35], v[34:35], 1.0 op_sel_hi:[1,0]
	global_store_dwordx4 v[106:107], v[38:41], off offset:256
	v_mul_f32_e32 v34, v34, v35
	v_rcp_f32_e32 v34, v34
	v_and_b32_e32 v35, 0xffff0000, v62
	v_mul_f32_e32 v35, v35, v36
	v_mul_f32_e32 v34, v22, v34
	v_mul_f32_e32 v22, 0xbfb8aa3b, v23
	v_mul_f32_e32 v23, 0xbfb8aa3b, v36
	v_exp_f32_e32 v22, v22
	v_exp_f32_e32 v23, v23
	v_lshlrev_b32_e32 v36, 16, v63
	v_pk_add_f32 v[22:23], v[22:23], 1.0 op_sel_hi:[1,0]
	s_nop 0
	v_mul_f32_e32 v22, v22, v23
	v_rcp_f32_e32 v22, v22
	v_lshlrev_b32_e32 v23, 16, v59
	v_mul_f32_e32 v22, v35, v22
	v_cvt_pk_bf16_f32 v22, v34, v22
	v_exp_f32_e32 v34, v24
	v_mul_f32_e32 v24, 0xbfb8aa3b, v23
	v_exp_f32_e32 v35, v24
	v_mul_f32_e32 v23, v36, v23
; __device__ __forceinline__ unsigned cvt_pk_bf16(float lo, float hi) { unsigned r; asm volatile("v_cvt_pk_bf16_f32 %0, %1, %2" : "=v"(r) : "v"(lo), "v"(hi)); return r; }
; __device__ __forceinline__ float bf_lo(unsigned w) { return __uint_as_float(w << 16); }
; __device__ __forceinline__ float bf_hi(unsigned w) { return __uint_as_float(w & 0xffff0000u); }
;     __device__ __forceinline__ void operator()(const f32x4 (&acc)[2][2][4][2], const Unit& u, int wr, int wc, int fr, int fq, const Pre&) const {
;     ...
;         for (int bj = 0; bj < 2; ++bj) { const int c = col0 + bj * HALF;
; #pragma unroll
;             for (int ai = 0; ai < 2; ++ai) { u32x4 zv[4], gv[4];
; #pragma unroll
;                 for (int m = 0; m < 4; ++m) { const int r = row0 + ai * HALF + m * 16; zv[m] = *(const u32x4*)(Z + (size_t)r * DE2 + c); gv[m] = *(const u32x4*)(Gm + (size_t)(c >> 4) * GSTR + r * 16 + (c & 15)); }
; #pragma unroll
;                 for (int m = 0; m < 4; ++m) { const int r = row0 + ai * HALF + m * 16;
;                     const u32x4 zw = zv[m], gw = gv[m];
;                     const f32x4 a0 = acc[ai][bj][m][0] + bs[bj][0], a1 = acc[ai][bj][m][1] + bs[bj][1];
;                     u32x4 w;
;                     w.x = cvt_pk_bf16(glu_gate_f(bf_lo(gw.x), a0[0], bf_lo(zw.x)), glu_gate_f(bf_hi(gw.x), a0[1], bf_hi(zw.x)));
;                     w.y = cvt_pk_bf16(glu_gate_f(bf_lo(gw.y), a0[2], bf_lo(zw.y)), glu_gate_f(bf_hi(gw.y), a0[3], bf_hi(zw.y)));
;                     w.z = cvt_pk_bf16(glu_gate_f(bf_lo(gw.z), a1[0], bf_lo(zw.z)), glu_gate_f(bf_hi(gw.z), a1[1], bf_hi(zw.z)));
;                     w.w = cvt_pk_bf16(glu_gate_f(bf_lo(gw.w), a1[2], bf_lo(zw.w)), glu_gate_f(bf_hi(gw.w), a1[3], bf_hi(zw.w)));
;                     *(u32x4*)(O + (size_t)r * DE + c) = w; } } }
	v_pk_add_f32 v[34:35], v[34:35], 1.0 op_sel_hi:[1,0]
	s_nop 0
	v_mul_f32_e32 v24, v34, v35
	v_rcp_f32_e32 v24, v24
	v_and_b32_e32 v35, 0xffff0000, v59
	v_and_b32_e32 v34, 0xffff0000, v63
	v_mul_f32_e32 v34, v34, v35
	v_mul_f32_e32 v23, v23, v24
	v_mul_f32_e32 v24, 0xbfb8aa3b, v25
	v_mul_f32_e32 v25, 0xbfb8aa3b, v35
	v_exp_f32_e32 v24, v24
	v_exp_f32_e32 v25, v25
	v_lshlrev_b32_e32 v35, 16, v64
	v_pk_add_f32 v[24:25], v[24:25], 1.0 op_sel_hi:[1,0]
	s_nop 0
	v_mul_f32_e32 v24, v24, v25
	v_rcp_f32_e32 v24, v24
	s_nop 0
	v_mul_f32_e32 v24, v34, v24
	v_lshlrev_b32_e32 v34, 16, v60
	v_cvt_pk_bf16_f32 v23, v23, v24
	v_exp_f32_e32 v24, v18
	v_mul_f32_e32 v18, 0xbfb8aa3b, v34
	v_exp_f32_e32 v25, v18
	v_mul_f32_e32 v18, v35, v34
	v_and_b32_e32 v34, 0xffff0000, v60
	v_pk_add_f32 v[24:25], v[24:25], 1.0 op_sel_hi:[1,0]
	s_nop 0
	v_mul_f32_e32 v24, v24, v25
	v_rcp_f32_e32 v24, v24
	v_and_b32_e32 v25, 0xffff0000, v64
	v_mul_f32_e32 v25, v25, v34
	v_mul_f32_e32 v24, v18, v24
	v_mul_f32_e32 v18, 0xbfb8aa3b, v19
	v_mul_f32_e32 v19, 0xbfb8aa3b, v34
	v_exp_f32_e32 v18, v18
	v_exp_f32_e32 v19, v19
	v_lshlrev_b32_e32 v34, 16, v65
	v_pk_add_f32 v[18:19], v[18:19], 1.0 op_sel_hi:[1,0]
	s_nop 0
	v_mul_f32_e32 v18, v18, v19
	v_rcp_f32_e32 v18, v18
	s_nop 0
	v_mul_f32_e32 v18, v25, v18
	v_lshlrev_b32_e32 v25, 16, v61
	v_cvt_pk_bf16_f32 v24, v24, v18
	v_mul_f32_e32 v18, 0xbfb8aa3b, v20
	v_mul_f32_e32 v19, 0xbfb8aa3b, v25
	v_exp_f32_e32 v18, v18
	v_exp_f32_e32 v19, v19
	v_mul_f32_e32 v20, v34, v25
	v_and_b32_e32 v34, 0xffff0000, v61
	v_and_b32_e32 v25, 0xffff0000, v65
	v_pk_add_f32 v[18:19], v[18:19], 1.0 op_sel_hi:[1,0]
	s_nop 0
	v_mul_f32_e32 v18, v18, v19
	v_rcp_f32_e32 v18, v18
	v_mul_f32_e32 v19, 0xbfb8aa3b, v34
	v_exp_f32_e32 v19, v19
	v_mul_f32_e32 v20, v20, v18
	v_mul_f32_e32 v18, 0xbfb8aa3b, v21
	v_exp_f32_e32 v18, v18
	v_mul_f32_e32 v21, v25, v34
	v_pk_add_f32 v[18:19], v[18:19], 1.0 op_sel_hi:[1,0]
	s_nop 0
	v_mul_f32_e32 v18, v18, v19
	v_rcp_f32_e32 v18, v18
	s_nop 0
	v_mul_f32_e32 v18, v21, v18
	v_cvt_pk_bf16_f32 v25, v20, v18
	v_lshlrev_b32_e32 v20, 16, v50
	v_exp_f32_e32 v18, v14
	v_mul_f32_e32 v14, 0xbfb8aa3b, v20
	v_exp_f32_e32 v19, v14
	v_lshlrev_b32_e32 v21, 16, v54
	v_mul_f32_e32 v14, v21, v20
	v_and_b32_e32 v20, 0xffff0000, v50
	v_pk_add_f32 v[18:19], v[18:19], 1.0 op_sel_hi:[1,0]
	global_store_dwordx4 v[108:109], v[22:25], off offset:256
	v_mul_f32_e32 v18, v18, v19
	v_rcp_f32_e32 v18, v18
	v_and_b32_e32 v19, 0xffff0000, v54
	v_mul_f32_e32 v19, v19, v20
	v_mul_f32_e32 v18, v14, v18
	v_mul_f32_e32 v14, 0xbfb8aa3b, v15
	v_mul_f32_e32 v15, 0xbfb8aa3b, v20
	v_exp_f32_e32 v14, v14
	v_exp_f32_e32 v15, v15
	v_lshlrev_b32_e32 v20, 16, v55
	v_pk_add_f32 v[14:15], v[14:15], 1.0 op_sel_hi:[1,0]
	s_nop 0
	v_mul_f32_e32 v14, v14, v15
	v_rcp_f32_e32 v14, v14
	v_lshlrev_b32_e32 v15, 16, v51
	v_mul_f32_e32 v14, v19, v14
	v_cvt_pk_bf16_f32 v14, v18, v14
	v_exp_f32_e32 v18, v16
	v_mul_f32_e32 v16, 0xbfb8aa3b, v15
	v_exp_f32_e32 v19, v16
	v_mul_f32_e32 v15, v20, v15
	v_pk_add_f32 v[18:19], v[18:19], 1.0 op_sel_hi:[1,0]
	s_nop 0
	v_mul_f32_e32 v16, v18, v19
	v_rcp_f32_e32 v16, v16
	v_and_b32_e32 v19, 0xffff0000, v51
	v_and_b32_e32 v18, 0xffff0000, v55
	v_mul_f32_e32 v18, v18, v19
	v_mul_f32_e32 v15, v15, v16
	v_mul_f32_e32 v16, 0xbfb8aa3b, v17
	v_mul_f32_e32 v17, 0xbfb8aa3b, v19
	v_exp_f32_e32 v16, v16
	v_exp_f32_e32 v17, v17
	v_lshlrev_b32_e32 v19, 16, v56
	v_pk_add_f32 v[16:17], v[16:17], 1.0 op_sel_hi:[1,0]
	s_nop 0
	v_mul_f32_e32 v16, v16, v17
	v_rcp_f32_e32 v16, v16
	s_nop 0
	v_mul_f32_e32 v16, v18, v16
	v_lshlrev_b32_e32 v18, 16, v52
	v_cvt_pk_bf16_f32 v15, v15, v16
	v_exp_f32_e32 v16, v10
	v_mul_f32_e32 v10, 0xbfb8aa3b, v18
	v_exp_f32_e32 v17, v10
	v_mul_f32_e32 v10, v19, v18
	v_and_b32_e32 v18, 0xffff0000, v52
	v_pk_add_f32 v[16:17], v[16:17], 1.0 op_sel_hi:[1,0]
	s_nop 0
	v_mul_f32_e32 v16, v16, v17
	v_rcp_f32_e32 v16, v16
	v_and_b32_e32 v17, 0xffff0000, v56
	v_mul_f32_e32 v17, v17, v18
	v_mul_f32_e32 v16, v10, v16
	v_mul_f32_e32 v10, 0xbfb8aa3b, v11
	v_mul_f32_e32 v11, 0xbfb8aa3b, v18
	v_exp_f32_e32 v10, v10
; __device__ __forceinline__ unsigned cvt_pk_bf16(float lo, float hi) { unsigned r; asm volatile("v_cvt_pk_bf16_f32 %0, %1, %2" : "=v"(r) : "v"(lo), "v"(hi)); return r; }
; __device__ __forceinline__ float bf_lo(unsigned w) { return __uint_as_float(w << 16); }
; __device__ __forceinline__ float bf_hi(unsigned w) { return __uint_as_float(w & 0xffff0000u); }
; #define PG8_WAIT_V(n) asm volatile("s_waitcnt vmcnt(" #n ")" ::: "memory")
; #define PG8_BAR __builtin_amdgcn_s_barrier()
; template <class Epi>
; __device__ __forceinline__ void gemm_phase(LAS unsigned char* lds, const Gemm g, const StaticOrder& S, const Epi& E) {
;     ...
;     PG8_WAIT_V(0);
;     if (wr == 0) PG8_BAR;
;     PG8_BAR;
;     __device__ __forceinline__ void operator()(const f32x4 (&acc)[2][2][4][2], const Unit& u, int wr, int wc, int fr, int fq, const Pre&) const {
;     ...
;         for (int bj = 0; bj < 2; ++bj) { const int c = col0 + bj * HALF;
; #pragma unroll
;             for (int ai = 0; ai < 2; ++ai) { u32x4 zv[4], gv[4];
; #pragma unroll
;                 for (int m = 0; m < 4; ++m) { const int r = row0 + ai * HALF + m * 16; zv[m] = *(const u32x4*)(Z + (size_t)r * DE2 + c); gv[m] = *(const u32x4*)(Gm + (size_t)(c >> 4) * GSTR + r * 16 + (c & 15)); }
; #pragma unroll
;                 for (int m = 0; m < 4; ++m) { const int r = row0 + ai * HALF + m * 16;
;                     const u32x4 zw = zv[m], gw = gv[m];
;                     const f32x4 a0 = acc[ai][bj][m][0] + bs[bj][0], a1 = acc[ai][bj][m][1] + bs[bj][1];
;                     u32x4 w;
;                     w.x = cvt_pk_bf16(glu_gate_f(bf_lo(gw.x), a0[0], bf_lo(zw.x)), glu_gate_f(bf_hi(gw.x), a0[1], bf_hi(zw.x)));
;                     w.y = cvt_pk_bf16(glu_gate_f(bf_lo(gw.y), a0[2], bf_lo(zw.y)), glu_gate_f(bf_hi(gw.y), a0[3], bf_hi(zw.y)));
;                     w.z = cvt_pk_bf16(glu_gate_f(bf_lo(gw.z), a1[0], bf_lo(zw.z)), glu_gate_f(bf_hi(gw.z), a1[1], bf_hi(zw.z)));
;                     w.w = cvt_pk_bf16(glu_gate_f(bf_lo(gw.w), a1[2], bf_lo(zw.w)), glu_gate_f(bf_hi(gw.w), a1[3], bf_hi(zw.w)));
;                     *(u32x4*)(O + (size_t)r * DE + c) = w; } } }
	v_exp_f32_e32 v11, v11
	v_lshlrev_b32_e32 v18, 16, v57
	v_pk_add_f32 v[10:11], v[10:11], 1.0 op_sel_hi:[1,0]
	s_nop 0
	v_mul_f32_e32 v10, v10, v11
	v_rcp_f32_e32 v10, v10
	s_nop 0
	v_mul_f32_e32 v10, v17, v10
	v_lshlrev_b32_e32 v17, 16, v53
	v_cvt_pk_bf16_f32 v16, v16, v10
	v_mul_f32_e32 v10, 0xbfb8aa3b, v12
	v_mul_f32_e32 v11, 0xbfb8aa3b, v17
	v_exp_f32_e32 v10, v10
	v_exp_f32_e32 v11, v11
	v_mul_f32_e32 v12, v18, v17
	v_and_b32_e32 v18, 0xffff0000, v53
	v_and_b32_e32 v17, 0xffff0000, v57
	v_pk_add_f32 v[10:11], v[10:11], 1.0 op_sel_hi:[1,0]
	s_nop 0
	v_mul_f32_e32 v10, v10, v11
	v_rcp_f32_e32 v10, v10
	v_mul_f32_e32 v11, 0xbfb8aa3b, v18
	v_exp_f32_e32 v11, v11
	v_mul_f32_e32 v12, v12, v10
	v_mul_f32_e32 v10, 0xbfb8aa3b, v13
	v_exp_f32_e32 v10, v10
	v_mul_f32_e32 v13, v17, v18
	v_pk_add_f32 v[10:11], v[10:11], 1.0 op_sel_hi:[1,0]
	s_nop 0
	v_mul_f32_e32 v10, v10, v11
	v_rcp_f32_e32 v10, v10
	s_nop 0
	v_mul_f32_e32 v10, v13, v10
	v_cvt_pk_bf16_f32 v17, v12, v10
	v_lshlrev_b32_e32 v12, 16, v42
	v_exp_f32_e32 v10, v6
	v_mul_f32_e32 v6, 0xbfb8aa3b, v12
	v_exp_f32_e32 v11, v6
	v_lshlrev_b32_e32 v13, 16, v46
	v_mul_f32_e32 v6, v13, v12
	v_and_b32_e32 v12, 0xffff0000, v42
	v_pk_add_f32 v[10:11], v[10:11], 1.0 op_sel_hi:[1,0]
	global_store_dwordx4 v[110:111], v[14:17], off offset:256
	v_mul_f32_e32 v10, v10, v11
	v_rcp_f32_e32 v10, v10
	v_and_b32_e32 v11, 0xffff0000, v46
	v_mul_f32_e32 v11, v11, v12
	v_mul_f32_e32 v10, v6, v10
	v_mul_f32_e32 v6, 0xbfb8aa3b, v7
	v_mul_f32_e32 v7, 0xbfb8aa3b, v12
	v_exp_f32_e32 v6, v6
	v_exp_f32_e32 v7, v7
	v_lshlrev_b32_e32 v12, 16, v47
	v_pk_add_f32 v[6:7], v[6:7], 1.0 op_sel_hi:[1,0]
	s_nop 0
	v_mul_f32_e32 v6, v6, v7
	v_rcp_f32_e32 v6, v6
	v_lshlrev_b32_e32 v7, 16, v43
	v_mul_f32_e32 v6, v11, v6
	v_cvt_pk_bf16_f32 v6, v10, v6
	v_exp_f32_e32 v10, v8
	v_mul_f32_e32 v8, 0xbfb8aa3b, v7
	v_exp_f32_e32 v11, v8
	v_mul_f32_e32 v7, v12, v7
	v_pk_add_f32 v[10:11], v[10:11], 1.0 op_sel_hi:[1,0]
	s_nop 0
	v_mul_f32_e32 v8, v10, v11
	v_rcp_f32_e32 v8, v8
	v_and_b32_e32 v11, 0xffff0000, v43
	v_and_b32_e32 v10, 0xffff0000, v47
	v_mul_f32_e32 v10, v10, v11
	v_mul_f32_e32 v7, v7, v8
	v_mul_f32_e32 v8, 0xbfb8aa3b, v9
	v_mul_f32_e32 v9, 0xbfb8aa3b, v11
	v_exp_f32_e32 v8, v8
	v_exp_f32_e32 v9, v9
	v_lshlrev_b32_e32 v11, 16, v48
	v_pk_add_f32 v[8:9], v[8:9], 1.0 op_sel_hi:[1,0]
	s_nop 0
	v_mul_f32_e32 v8, v8, v9
	v_rcp_f32_e32 v8, v8
	s_nop 0
	v_mul_f32_e32 v8, v10, v8
	v_lshlrev_b32_e32 v10, 16, v44
	v_cvt_pk_bf16_f32 v7, v7, v8
	v_exp_f32_e32 v8, v2
	v_mul_f32_e32 v2, 0xbfb8aa3b, v10
	v_exp_f32_e32 v9, v2
	v_mul_f32_e32 v2, v11, v10
	v_and_b32_e32 v10, 0xffff0000, v44
	v_pk_add_f32 v[8:9], v[8:9], 1.0 op_sel_hi:[1,0]
	s_nop 0
	v_mul_f32_e32 v8, v8, v9
	v_rcp_f32_e32 v8, v8
	v_and_b32_e32 v9, 0xffff0000, v48
	v_mul_f32_e32 v9, v9, v10
	v_mul_f32_e32 v8, v2, v8
	v_mul_f32_e32 v2, 0xbfb8aa3b, v3
	v_mul_f32_e32 v3, 0xbfb8aa3b, v10
	v_exp_f32_e32 v2, v2
	v_exp_f32_e32 v3, v3
	v_lshlrev_b32_e32 v10, 16, v49
	v_pk_add_f32 v[2:3], v[2:3], 1.0 op_sel_hi:[1,0]
	s_nop 0
	v_mul_f32_e32 v2, v2, v3
	v_rcp_f32_e32 v2, v2
	s_nop 0
	v_mul_f32_e32 v2, v9, v2
	v_lshlrev_b32_e32 v9, 16, v45
	v_cvt_pk_bf16_f32 v8, v8, v2
	v_mul_f32_e32 v2, 0xbfb8aa3b, v4
	v_mul_f32_e32 v3, 0xbfb8aa3b, v9
	v_exp_f32_e32 v2, v2
	v_exp_f32_e32 v3, v3
	v_mul_f32_e32 v4, v10, v9
	v_and_b32_e32 v10, 0xffff0000, v45
	v_and_b32_e32 v9, 0xffff0000, v49
	v_pk_add_f32 v[2:3], v[2:3], 1.0 op_sel_hi:[1,0]
	s_nop 0
	v_mul_f32_e32 v2, v2, v3
	v_rcp_f32_e32 v2, v2
	v_mul_f32_e32 v3, 0xbfb8aa3b, v10
	v_exp_f32_e32 v3, v3
	v_mul_f32_e32 v4, v4, v2
	v_mul_f32_e32 v2, 0xbfb8aa3b, v5
	v_exp_f32_e32 v2, v2
	v_mul_f32_e32 v5, v9, v10
	v_pk_add_f32 v[2:3], v[2:3], 1.0 op_sel_hi:[1,0]
	s_nop 0
	v_mul_f32_e32 v2, v2, v3
	v_rcp_f32_e32 v2, v2
	s_nop 0
	v_mul_f32_e32 v2, v5, v2
	v_cvt_pk_bf16_f32 v9, v4, v2
	global_store_dwordx4 v[112:113], v[6:9], off offset:256
	s_cbranch_vccz .LBB0_789
	s_waitcnt vmcnt(0)
	v_readlane_b32 s36, v254, 56
	s_cmpk_gt_u32 s18, 0xff
	v_readlane_b32 s37, v254, 57
	s_cbranch_scc1 .LBB0_800
	s_barrier
